# speedup vs baseline: 1.0086x; 1.0037x over previous
; #define WAIT_V(n) asm volatile("s_waitcnt vmcnt(%0)" ::"n"(n) : "memory")
; #define WAIT_L(n) asm volatile("s_waitcnt lgkmcnt(%0)" ::"n"(n) : "memory")
; #define SBAR() __builtin_amdgcn_sched_barrier(0)
; #define STAGE(P, base, kt) do { _Pragma("unroll") for (int _i = 0; _i < 2; ++_i)                                        \
;       __builtin_amdgcn_global_load_lds((const unsigned*)((base) + (size_t)(sOff[_i] + (unsigned)(kt) * (BK * 2))),        \
;                                        (unsigned*)((P) + wid * 1024 + _i * 8192), 16, 0, 0); } while (0)
; #define LDA(dst, b, h) _Pragma("unroll") for (int m = 0; m < 4; ++m) _Pragma("unroll") for (int k = 0; k < 2; ++k) \
;       dst[m][k] = *(const bf16x8*)(SA(b, h) + aoff + (m * 2048 + k * 1024))
; #define LDB(dst, b, h) _Pragma("unroll") for (int n = 0; n < 2; ++n) _Pragma("unroll") for (int k = 0; k < 2; ++k) \
;       dst[n][k] = *(const bf16x8*)(SB(b, h) + boff + (n * 256 + k * 1024))
; #define BAR __builtin_amdgcn_s_barrier()
; template <int EPI, int N, int K>
; __device__ __forceinline__ void phase_gemm(const Params& p, const u16* __restrict__ A, const u16* __restrict__ Bt, int nM, char* shm,
;                            u16* __restrict__ outp, float* __restrict__ rowss) {
;     ...
;       LDB(B0, 0, 0); SBAR(); LDA(At, 0, 0); STAGE(SA(1, 1), A1, t + 1);
;       WAIT_L(8); BAR; WAIT_L(0); MMA(0, 0, At, B0); BAR; SBAR();
;       LDB(B1, 0, 1); STAGE(SB(0, 0), B0p, t + 2);
;       BAR; WAIT_L(0); MMA(0, 1, At, B1); BAR;
;       LDA(At, 0, 1); STAGE(SA(0, 0), A0, t + 2);
;       BAR; WAIT_L(0); MMA(1, 0, At, B0); BAR; SBAR();
;       STAGE(SB(0, 1), B1p, t + 2);
;       WAIT_V(6); BAR; MMA(1, 1, At, B1); BAR;
.LBB0_94:
	v_or_b32_e32 v143, 0x10000, v146
	v_add_u32_e32 v145, 0x10100, v146
	v_add_u32_e32 v144, 0x10400, v146
	ds_read_b128 v[156:159], v143
	ds_read_b128 v[160:163], v144
	v_add_u32_e32 v151, 0x10500, v146
	ds_read_b128 v[164:167], v145
	ds_read_b128 v[168:171], v151
	v_add_u32_e32 v240, v148, v96
	s_mov_b32 m0, s56
	v_add_u32_e32 v152, 0x80, v240
	v_add_u32_e32 v241, v148, v142
	ds_read_b128 v[172:175], v147
	ds_read_b128 v[176:179], v147 offset:1024
	ds_read_b128 v[180:183], v147 offset:2048
	ds_read_b128 v[196:199], v147 offset:3072
	ds_read_b128 v[200:203], v147 offset:4096
	ds_read_b128 v[204:207], v147 offset:5120
	ds_read_b128 v[208:211], v147 offset:6144
	ds_read_b128 v[212:215], v147 offset:7168
	global_load_lds_dwordx4 v152, s[6:7]
	v_add_u32_e32 v152, 0x80, v241
	s_mov_b32 m0, s57
	s_nop 0
	global_load_lds_dwordx4 v152, s[6:7]
	v_or_b32_e32 v152, 0x14000, v146
	v_add_u32_e32 v154, 0x14100, v146
	v_add_u32_e32 v153, 0x14400, v146
	ds_read_b128 v[216:219], v152
	ds_read_b128 v[220:223], v153
	v_add_u32_e32 v155, 0x14500, v146
	ds_read_b128 v[224:227], v154
	ds_read_b128 v[228:231], v155
	s_waitcnt lgkmcnt(0)
	s_barrier
	v_mfma_f32_16x16x32_bf16 v[126:129], v[156:159], v[172:175], v[126:129]
	v_mfma_f32_16x16x32_bf16 v[122:125], v[164:167], v[172:175], v[122:125]
	v_mfma_f32_16x16x32_bf16 v[118:121], v[156:159], v[180:183], v[118:121]
	v_mfma_f32_16x16x32_bf16 v[114:117], v[164:167], v[180:183], v[114:117]
	v_mfma_f32_16x16x32_bf16 v[110:113], v[156:159], v[200:203], v[110:113]
	v_mfma_f32_16x16x32_bf16 v[106:109], v[164:167], v[200:203], v[106:109]
	v_mfma_f32_16x16x32_bf16 v[102:105], v[156:159], v[208:211], v[102:105]
	v_mfma_f32_16x16x32_bf16 v[98:101], v[164:167], v[208:211], v[98:101]
	v_mfma_f32_16x16x32_bf16 v[126:129], v[160:163], v[176:179], v[126:129]
	v_mfma_f32_16x16x32_bf16 v[122:125], v[168:171], v[176:179], v[122:125]
	v_mfma_f32_16x16x32_bf16 v[118:121], v[160:163], v[196:199], v[118:121]
	v_mfma_f32_16x16x32_bf16 v[114:117], v[168:171], v[196:199], v[114:117]
	v_mfma_f32_16x16x32_bf16 v[110:113], v[160:163], v[204:207], v[110:113]
	v_mfma_f32_16x16x32_bf16 v[106:109], v[168:171], v[204:207], v[106:109]
	v_mfma_f32_16x16x32_bf16 v[102:105], v[160:163], v[212:215], v[102:105]
	v_mfma_f32_16x16x32_bf16 v[98:101], v[168:171], v[212:215], v[98:101]
	v_mfma_f32_16x16x32_bf16 v[92:95], v[216:219], v[172:175], v[92:95]
	v_mfma_f32_16x16x32_bf16 v[88:91], v[224:227], v[172:175], v[88:91]
	v_mfma_f32_16x16x32_bf16 v[84:87], v[216:219], v[180:183], v[84:87]
	v_mfma_f32_16x16x32_bf16 v[80:83], v[224:227], v[180:183], v[80:83]
	v_mfma_f32_16x16x32_bf16 v[76:79], v[216:219], v[200:203], v[76:79]
	v_mfma_f32_16x16x32_bf16 v[72:75], v[224:227], v[200:203], v[72:75]
	v_mfma_f32_16x16x32_bf16 v[68:71], v[216:219], v[208:211], v[68:71]
	v_mfma_f32_16x16x32_bf16 v[64:67], v[224:227], v[208:211], v[64:67]
	v_mfma_f32_16x16x32_bf16 v[92:95], v[220:223], v[176:179], v[92:95]
	v_mfma_f32_16x16x32_bf16 v[88:91], v[228:231], v[176:179], v[88:91]
	v_mfma_f32_16x16x32_bf16 v[84:87], v[220:223], v[196:199], v[84:87]
	v_mfma_f32_16x16x32_bf16 v[80:83], v[228:231], v[196:199], v[80:83]
	v_mfma_f32_16x16x32_bf16 v[76:79], v[220:223], v[204:207], v[76:79]
	v_mfma_f32_16x16x32_bf16 v[72:75], v[228:231], v[204:207], v[72:75]
	v_mfma_f32_16x16x32_bf16 v[68:71], v[220:223], v[212:215], v[68:71]
	v_mfma_f32_16x16x32_bf16 v[64:67], v[228:231], v[212:215], v[64:67]
	s_barrier
	ds_read_b128 v[172:175], v147 offset:16384
	ds_read_b128 v[176:179], v147 offset:17408
	ds_read_b128 v[180:183], v147 offset:18432
	ds_read_b128 v[196:199], v147 offset:19456
	ds_read_b128 v[200:203], v147 offset:20480
	ds_read_b128 v[204:207], v147 offset:21504
	ds_read_b128 v[208:211], v147 offset:22528
	ds_read_b128 v[212:215], v147 offset:23552
	s_mov_b32 m0, s26
	v_add_u32_e32 v232, 0x100, v240
	global_load_lds_dwordx4 v232, s[12:13]
	v_add_u32_e32 v233, 0x100, v241
	s_mov_b32 m0, s27
	s_nop 0
	global_load_lds_dwordx4 v233, s[12:13]
	s_mov_b32 m0, s5
	s_nop 0
	global_load_lds_dwordx4 v232, s[14:15]
	s_mov_b32 m0, s24
	s_nop 0
	global_load_lds_dwordx4 v233, s[14:15]
	s_mov_b32 m0, s28
	s_nop 0
	global_load_lds_dwordx4 v232, s[22:23]
	s_mov_b32 m0, s29
	s_nop 0
	global_load_lds_dwordx4 v233, s[22:23]
	s_waitcnt vmcnt(6)
	s_waitcnt lgkmcnt(0)
	s_barrier
	v_mfma_f32_16x16x32_bf16 v[60:63], v[156:159], v[172:175], v[60:63]
	v_mfma_f32_16x16x32_bf16 v[56:59], v[164:167], v[172:175], v[56:59]
	v_mfma_f32_16x16x32_bf16 v[52:55], v[156:159], v[180:183], v[52:55]
	v_mfma_f32_16x16x32_bf16 v[48:51], v[164:167], v[180:183], v[48:51]
	v_mfma_f32_16x16x32_bf16 v[44:47], v[156:159], v[200:203], v[44:47]
	v_mfma_f32_16x16x32_bf16 v[40:43], v[164:167], v[200:203], v[40:43]
	v_mfma_f32_16x16x32_bf16 v[36:39], v[156:159], v[208:211], v[36:39]
	v_mfma_f32_16x16x32_bf16 v[32:35], v[164:167], v[208:211], v[32:35]
	v_mfma_f32_16x16x32_bf16 v[60:63], v[160:163], v[176:179], v[60:63]
	v_mfma_f32_16x16x32_bf16 v[56:59], v[168:171], v[176:179], v[56:59]
	v_mfma_f32_16x16x32_bf16 v[52:55], v[160:163], v[196:199], v[52:55]
	v_mfma_f32_16x16x32_bf16 v[48:51], v[168:171], v[196:199], v[48:51]
	v_mfma_f32_16x16x32_bf16 v[44:47], v[160:163], v[204:207], v[44:47]
	v_mfma_f32_16x16x32_bf16 v[40:43], v[168:171], v[204:207], v[40:43]
	v_mfma_f32_16x16x32_bf16 v[36:39], v[160:163], v[212:215], v[36:39]
	v_mfma_f32_16x16x32_bf16 v[32:35], v[168:171], v[212:215], v[32:35]
	v_mfma_f32_16x16x32_bf16 v[28:31], v[216:219], v[172:175], v[28:31]
	v_mfma_f32_16x16x32_bf16 v[24:27], v[224:227], v[172:175], v[24:27]
	v_mfma_f32_16x16x32_bf16 v[20:23], v[216:219], v[180:183], v[20:23]
	v_mfma_f32_16x16x32_bf16 v[16:19], v[224:227], v[180:183], v[16:19]
	v_mfma_f32_16x16x32_bf16 v[12:15], v[216:219], v[200:203], v[12:15]
	v_mfma_f32_16x16x32_bf16 v[8:11], v[224:227], v[200:203], v[8:11]
	v_mfma_f32_16x16x32_bf16 v[4:7], v[216:219], v[208:211], v[4:7]
	v_mfma_f32_16x16x32_bf16 v[0:3], v[224:227], v[208:211], v[0:3]
	v_mfma_f32_16x16x32_bf16 v[28:31], v[220:223], v[176:179], v[28:31]
	v_mfma_f32_16x16x32_bf16 v[24:27], v[228:231], v[176:179], v[24:27]
	v_mfma_f32_16x16x32_bf16 v[20:23], v[220:223], v[196:199], v[20:23]
	v_mfma_f32_16x16x32_bf16 v[16:19], v[228:231], v[196:199], v[16:19]
	v_mfma_f32_16x16x32_bf16 v[12:15], v[220:223], v[204:207], v[12:15]
	v_mfma_f32_16x16x32_bf16 v[8:11], v[228:231], v[204:207], v[8:11]
	v_mfma_f32_16x16x32_bf16 v[4:7], v[220:223], v[212:215], v[4:7]
	v_mfma_f32_16x16x32_bf16 v[0:3], v[228:231], v[212:215], v[0:3]
	v_or_b32_e32 v156, 0x18000, v146
	v_add_u32_e32 v158, 0x18100, v146
	s_barrier
; #define WAIT_V(n) asm volatile("s_waitcnt vmcnt(%0)" ::"n"(n) : "memory")
; #define WAIT_L(n) asm volatile("s_waitcnt lgkmcnt(%0)" ::"n"(n) : "memory")
; #define SBAR() __builtin_amdgcn_sched_barrier(0)
; #define STAGE(P, base, kt) do { _Pragma("unroll") for (int _i = 0; _i < 2; ++_i)                                        \
;       __builtin_amdgcn_global_load_lds((const unsigned*)((base) + (size_t)(sOff[_i] + (unsigned)(kt) * (BK * 2))),        \
;                                        (unsigned*)((P) + wid * 1024 + _i * 8192), 16, 0, 0); } while (0)
; #define LDA(dst, b, h) _Pragma("unroll") for (int m = 0; m < 4; ++m) _Pragma("unroll") for (int k = 0; k < 2; ++k) \
;       dst[m][k] = *(const bf16x8*)(SA(b, h) + aoff + (m * 2048 + k * 1024))
; #define LDB(dst, b, h) _Pragma("unroll") for (int n = 0; n < 2; ++n) _Pragma("unroll") for (int k = 0; k < 2; ++k) \
;       dst[n][k] = *(const bf16x8*)(SB(b, h) + boff + (n * 256 + k * 1024))
; #define BAR __builtin_amdgcn_s_barrier()
; template <int EPI, int N, int K>
; __device__ __forceinline__ void phase_gemm(const Params& p, const u16* __restrict__ A, const u16* __restrict__ Bt, int nM, char* shm,
;                            u16* __restrict__ outp, float* __restrict__ rowss) {
;     ...
;       LDB(B0, 1, 0); SBAR(); LDA(At, 1, 0); STAGE(SA(0, 1), A1, t + 2);
;       WAIT_L(8); BAR; WAIT_L(0); MMA(0, 0, At, B0); BAR; SBAR();
;       LDB(B1, 1, 1); STAGE(SB(1, 0), B0p, t + 3);
;       BAR; WAIT_L(0); MMA(0, 1, At, B1); BAR;
;       LDA(At, 1, 1); STAGE(SA(1, 0), A0, t + 3);
;       BAR; WAIT_L(0); MMA(1, 0, At, B0); BAR; SBAR();
;       STAGE(SB(1, 1), B1p, t + 3);
;       WAIT_V(6); BAR; MMA(1, 1, At, B1); BAR;
	v_add_u32_e32 v157, 0x18400, v146
	ds_read_b128 v[164:167], v156
	ds_read_b128 v[168:171], v157
	v_add_u32_e32 v159, 0x18500, v146
	ds_read_b128 v[172:175], v158
	ds_read_b128 v[176:179], v159
	s_mov_b32 m0, s30
	ds_read_b128 v[180:183], v147 offset:32768
	ds_read_b128 v[196:199], v147 offset:33792
	ds_read_b128 v[200:203], v147 offset:34816
	ds_read_b128 v[204:207], v147 offset:35840
	ds_read_b128 v[208:211], v147 offset:36864
	ds_read_b128 v[212:215], v147 offset:37888
	ds_read_b128 v[216:219], v147 offset:38912
	ds_read_b128 v[220:223], v147 offset:39936
	global_load_lds_dwordx4 v232, s[6:7]
	s_mov_b32 m0, s31
	s_nop 0
	global_load_lds_dwordx4 v233, s[6:7]
	v_or_b32_e32 v160, 0x1c000, v146
	v_add_u32_e32 v162, 0x1c100, v146
	v_add_u32_e32 v161, 0x1c400, v146
	ds_read_b128 v[224:227], v160
	ds_read_b128 v[228:231], v161
	v_add_u32_e32 v163, 0x1c500, v146
	ds_read_b128 v[232:235], v162
	ds_read_b128 v[236:239], v163
	s_waitcnt lgkmcnt(0)
	s_barrier
	v_mfma_f32_16x16x32_bf16 v[126:129], v[164:167], v[180:183], v[126:129]
	v_mfma_f32_16x16x32_bf16 v[122:125], v[172:175], v[180:183], v[122:125]
	v_mfma_f32_16x16x32_bf16 v[118:121], v[164:167], v[200:203], v[118:121]
	v_mfma_f32_16x16x32_bf16 v[114:117], v[172:175], v[200:203], v[114:117]
	v_mfma_f32_16x16x32_bf16 v[110:113], v[164:167], v[208:211], v[110:113]
	v_mfma_f32_16x16x32_bf16 v[106:109], v[172:175], v[208:211], v[106:109]
	v_mfma_f32_16x16x32_bf16 v[102:105], v[164:167], v[216:219], v[102:105]
	v_mfma_f32_16x16x32_bf16 v[98:101], v[172:175], v[216:219], v[98:101]
	v_mfma_f32_16x16x32_bf16 v[126:129], v[168:171], v[196:199], v[126:129]
	v_mfma_f32_16x16x32_bf16 v[122:125], v[176:179], v[196:199], v[122:125]
	v_mfma_f32_16x16x32_bf16 v[118:121], v[168:171], v[204:207], v[118:121]
	v_mfma_f32_16x16x32_bf16 v[114:117], v[176:179], v[204:207], v[114:117]
	v_mfma_f32_16x16x32_bf16 v[110:113], v[168:171], v[212:215], v[110:113]
	v_mfma_f32_16x16x32_bf16 v[106:109], v[176:179], v[212:215], v[106:109]
	v_mfma_f32_16x16x32_bf16 v[102:105], v[168:171], v[220:223], v[102:105]
	v_mfma_f32_16x16x32_bf16 v[98:101], v[176:179], v[220:223], v[98:101]
	v_mfma_f32_16x16x32_bf16 v[92:95], v[224:227], v[180:183], v[92:95]
	v_mfma_f32_16x16x32_bf16 v[88:91], v[232:235], v[180:183], v[88:91]
	v_mfma_f32_16x16x32_bf16 v[84:87], v[224:227], v[200:203], v[84:87]
	v_mfma_f32_16x16x32_bf16 v[80:83], v[232:235], v[200:203], v[80:83]
	v_mfma_f32_16x16x32_bf16 v[76:79], v[224:227], v[208:211], v[76:79]
	v_mfma_f32_16x16x32_bf16 v[72:75], v[232:235], v[208:211], v[72:75]
	v_mfma_f32_16x16x32_bf16 v[68:71], v[224:227], v[216:219], v[68:71]
	v_mfma_f32_16x16x32_bf16 v[64:67], v[232:235], v[216:219], v[64:67]
	v_mfma_f32_16x16x32_bf16 v[92:95], v[228:231], v[196:199], v[92:95]
	v_mfma_f32_16x16x32_bf16 v[88:91], v[236:239], v[196:199], v[88:91]
	v_mfma_f32_16x16x32_bf16 v[84:87], v[228:231], v[204:207], v[84:87]
	v_mfma_f32_16x16x32_bf16 v[80:83], v[236:239], v[204:207], v[80:83]
	v_mfma_f32_16x16x32_bf16 v[76:79], v[228:231], v[212:215], v[76:79]
	v_mfma_f32_16x16x32_bf16 v[72:75], v[236:239], v[212:215], v[72:75]
	v_mfma_f32_16x16x32_bf16 v[68:71], v[228:231], v[220:223], v[68:71]
	v_mfma_f32_16x16x32_bf16 v[64:67], v[236:239], v[220:223], v[64:67]
	s_barrier
	ds_read_b128 v[180:183], v147 offset:49152
	ds_read_b128 v[196:199], v147 offset:50176
	ds_read_b128 v[200:203], v147 offset:51200
	ds_read_b128 v[204:207], v147 offset:52224
	ds_read_b128 v[208:211], v147 offset:53248
	ds_read_b128 v[212:215], v147 offset:54272
	ds_read_b128 v[216:219], v147 offset:55296
	ds_read_b128 v[220:223], v147 offset:56320
	s_mov_b32 m0, s33
	v_add_u32_e32 v240, 0x180, v240
	global_load_lds_dwordx4 v240, s[12:13]
	v_add_u32_e32 v241, 0x180, v241
	s_mov_b32 m0, s35
	s_nop 0
	global_load_lds_dwordx4 v241, s[12:13]
	s_mov_b32 m0, s93
	s_nop 0
	global_load_lds_dwordx4 v240, s[14:15]
	s_mov_b32 m0, s96
	s_nop 0
	global_load_lds_dwordx4 v241, s[14:15]
	s_mov_b32 m0, s52
	s_nop 0
	global_load_lds_dwordx4 v240, s[22:23]
	s_mov_b32 m0, s53
	s_nop 0
	global_load_lds_dwordx4 v241, s[22:23]
	s_waitcnt vmcnt(6)
	s_waitcnt lgkmcnt(0)
	s_barrier
	v_mfma_f32_16x16x32_bf16 v[60:63], v[164:167], v[180:183], v[60:63]
	v_mfma_f32_16x16x32_bf16 v[56:59], v[172:175], v[180:183], v[56:59]
	v_mfma_f32_16x16x32_bf16 v[52:55], v[164:167], v[200:203], v[52:55]
	v_mfma_f32_16x16x32_bf16 v[48:51], v[172:175], v[200:203], v[48:51]
	v_mfma_f32_16x16x32_bf16 v[44:47], v[164:167], v[208:211], v[44:47]
	v_mfma_f32_16x16x32_bf16 v[40:43], v[172:175], v[208:211], v[40:43]
	v_mfma_f32_16x16x32_bf16 v[36:39], v[164:167], v[216:219], v[36:39]
	v_mfma_f32_16x16x32_bf16 v[32:35], v[172:175], v[216:219], v[32:35]
	v_mfma_f32_16x16x32_bf16 v[60:63], v[168:171], v[196:199], v[60:63]
	v_mfma_f32_16x16x32_bf16 v[56:59], v[176:179], v[196:199], v[56:59]
	v_mfma_f32_16x16x32_bf16 v[52:55], v[168:171], v[204:207], v[52:55]
	v_mfma_f32_16x16x32_bf16 v[48:51], v[176:179], v[204:207], v[48:51]
	v_mfma_f32_16x16x32_bf16 v[44:47], v[168:171], v[212:215], v[44:47]
	v_mfma_f32_16x16x32_bf16 v[40:43], v[176:179], v[212:215], v[40:43]
	v_mfma_f32_16x16x32_bf16 v[36:39], v[168:171], v[220:223], v[36:39]
	v_mfma_f32_16x16x32_bf16 v[32:35], v[176:179], v[220:223], v[32:35]
	v_mfma_f32_16x16x32_bf16 v[28:31], v[224:227], v[180:183], v[28:31]
	v_mfma_f32_16x16x32_bf16 v[24:27], v[232:235], v[180:183], v[24:27]
	v_mfma_f32_16x16x32_bf16 v[20:23], v[224:227], v[200:203], v[20:23]
	v_mfma_f32_16x16x32_bf16 v[16:19], v[232:235], v[200:203], v[16:19]
	v_mfma_f32_16x16x32_bf16 v[12:15], v[224:227], v[208:211], v[12:15]
	v_mfma_f32_16x16x32_bf16 v[8:11], v[232:235], v[208:211], v[8:11]
	v_mfma_f32_16x16x32_bf16 v[4:7], v[224:227], v[216:219], v[4:7]
	v_mfma_f32_16x16x32_bf16 v[0:3], v[232:235], v[216:219], v[0:3]
	v_mfma_f32_16x16x32_bf16 v[28:31], v[228:231], v[196:199], v[28:31]
	v_mfma_f32_16x16x32_bf16 v[24:27], v[236:239], v[196:199], v[24:27]
	v_mfma_f32_16x16x32_bf16 v[20:23], v[228:231], v[204:207], v[20:23]
	v_mfma_f32_16x16x32_bf16 v[16:19], v[236:239], v[204:207], v[16:19]
	v_mfma_f32_16x16x32_bf16 v[12:15], v[228:231], v[212:215], v[12:15]
	v_mfma_f32_16x16x32_bf16 v[8:11], v[236:239], v[212:215], v[8:11]
	v_mfma_f32_16x16x32_bf16 v[4:7], v[228:231], v[220:223], v[4:7]
	v_mfma_f32_16x16x32_bf16 v[0:3], v[236:239], v[220:223], v[0:3]
	s_add_i32 s61, s61, 2
	v_add_u32_e32 v142, 0x100, v142
	s_cmp_lt_u32 s61, 40
	v_add_u32_e32 v96, 0x100, v96
	s_barrier
; #define WAIT_V(n) asm volatile("s_waitcnt vmcnt(%0)" ::"n"(n) : "memory")
; #define WAIT_L(n) asm volatile("s_waitcnt lgkmcnt(%0)" ::"n"(n) : "memory")
; #define STAGE(P, base, kt) do { _Pragma("unroll") for (int _i = 0; _i < 2; ++_i)                                        \
;       __builtin_amdgcn_global_load_lds((const unsigned*)((base) + (size_t)(sOff[_i] + (unsigned)(kt) * (BK * 2))),        \
;                                        (unsigned*)((P) + wid * 1024 + _i * 8192), 16, 0, 0); } while (0)
; #define LDA(dst, b, h) _Pragma("unroll") for (int m = 0; m < 4; ++m) _Pragma("unroll") for (int k = 0; k < 2; ++k) \
;       dst[m][k] = *(const bf16x8*)(SA(b, h) + aoff + (m * 2048 + k * 1024))
; #define LDB(dst, b, h) _Pragma("unroll") for (int n = 0; n < 2; ++n) _Pragma("unroll") for (int k = 0; k < 2; ++k) \
;       dst[n][k] = *(const bf16x8*)(SB(b, h) + boff + (n * 256 + k * 1024))
; #define BAR __builtin_amdgcn_s_barrier()
; template <int EPI, int N, int K>
; __device__ __forceinline__ void phase_gemm(const Params& p, const u16* __restrict__ A, const u16* __restrict__ Bt, int nM, char* shm,
;                            u16* __restrict__ outp, float* __restrict__ rowss) {
;     ...
;     { LDB(B0, 0, 0); LDA(At, 0, 0); STAGE(SA(1, 1), A1, nt - 1);
;       BAR; WAIT_L(0); MMA(0, 0, At, B0); BAR;
;       LDB(B1, 0, 1); BAR; WAIT_L(0); MMA(0, 1, At, B1); BAR;
;       LDA(At, 0, 1); WAIT_V(4); BAR; WAIT_L(0); MMA(1, 0, At, B0); MMA(1, 1, At, B1); BAR; }
;     { LDB(B0, 1, 0); LDA(At, 1, 0); WAIT_V(2); BAR; WAIT_L(0); MMA(0, 0, At, B0); BAR;
;       LDB(B1, 1, 1); WAIT_V(0); BAR; WAIT_L(0); MMA(0, 1, At, B1); BAR;
;       LDA(At, 1, 1); BAR; WAIT_L(0); MMA(1, 0, At, B0); MMA(1, 1, At, B1); BAR; }
	s_cbranch_scc1 .LBB0_94
	s_mov_b32 m0, s56
	v_lshl_add_u64 v[220:221], s[6:7], 0, v[138:139]
	ds_read_b128 v[164:167], v143
	ds_read_b128 v[168:171], v144
	ds_read_b128 v[142:145], v145
	ds_read_b128 v[172:175], v151
	ds_read_b128 v[176:179], v147
	ds_read_b128 v[180:183], v147 offset:1024
	ds_read_b128 v[196:199], v147 offset:2048
	ds_read_b128 v[200:203], v147 offset:3072
	ds_read_b128 v[204:207], v147 offset:4096
	ds_read_b128 v[208:211], v147 offset:5120
	ds_read_b128 v[212:215], v147 offset:6144
	ds_read_b128 v[216:219], v147 offset:7168
	global_load_lds_dwordx4 v[220:221], off
	v_lshl_add_u64 v[220:221], s[6:7], 0, v[140:141]
	s_mov_b32 m0, s57
	s_nop 0
	global_load_lds_dwordx4 v[220:221], off
	s_barrier
	s_waitcnt lgkmcnt(0)
	s_waitcnt lgkmcnt(0)
	v_mfma_f32_16x16x32_bf16 v[126:129], v[164:167], v[176:179], v[126:129]
	v_mfma_f32_16x16x32_bf16 v[122:125], v[142:145], v[176:179], v[122:125]
	v_mfma_f32_16x16x32_bf16 v[118:121], v[164:167], v[196:199], v[118:121]
	v_mfma_f32_16x16x32_bf16 v[102:105], v[164:167], v[212:215], v[102:105]
	v_mfma_f32_16x16x32_bf16 v[98:101], v[142:145], v[212:215], v[98:101]
	v_mfma_f32_16x16x32_bf16 v[126:129], v[168:171], v[180:183], v[126:129]
	v_mfma_f32_16x16x32_bf16 v[122:125], v[172:175], v[180:183], v[122:125]
	v_mfma_f32_16x16x32_bf16 v[118:121], v[168:171], v[200:203], v[118:121]
	v_mfma_f32_16x16x32_bf16 v[114:117], v[142:145], v[196:199], v[114:117]
	v_mfma_f32_16x16x32_bf16 v[110:113], v[164:167], v[204:207], v[110:113]
	v_mfma_f32_16x16x32_bf16 v[106:109], v[142:145], v[204:207], v[106:109]
	v_mfma_f32_16x16x32_bf16 v[102:105], v[168:171], v[216:219], v[102:105]
	v_mfma_f32_16x16x32_bf16 v[98:101], v[172:175], v[216:219], v[98:101]
	v_mfma_f32_16x16x32_bf16 v[220:223], v[172:175], v[200:203], v[114:117]
	v_mfma_f32_16x16x32_bf16 v[224:227], v[168:171], v[208:211], v[110:113]
	v_mfma_f32_16x16x32_bf16 v[228:231], v[172:175], v[208:211], v[106:109]
	s_barrier
	s_nop 0
	ds_read_b128 v[106:109], v152
	ds_read_b128 v[110:113], v153
	ds_read_b128 v[114:117], v154
	ds_read_b128 v[152:155], v155
	s_barrier
	s_waitcnt lgkmcnt(0)
	s_waitcnt lgkmcnt(0)
	v_mfma_f32_16x16x32_bf16 v[84:87], v[106:109], v[196:199], v[84:87]
	v_mfma_f32_16x16x32_bf16 v[80:83], v[114:117], v[196:199], v[80:83]
	v_mfma_f32_16x16x32_bf16 v[68:71], v[106:109], v[212:215], v[68:71]
	v_mfma_f32_16x16x32_bf16 v[92:95], v[106:109], v[176:179], v[92:95]
	v_mfma_f32_16x16x32_bf16 v[88:91], v[114:117], v[176:179], v[88:91]
	v_mfma_f32_16x16x32_bf16 v[84:87], v[110:113], v[200:203], v[84:87]
	v_mfma_f32_16x16x32_bf16 v[80:83], v[152:155], v[200:203], v[80:83]
	v_mfma_f32_16x16x32_bf16 v[76:79], v[106:109], v[204:207], v[76:79]
	v_mfma_f32_16x16x32_bf16 v[72:75], v[114:117], v[204:207], v[72:75]
	v_mfma_f32_16x16x32_bf16 v[68:71], v[110:113], v[216:219], v[68:71]
	v_mfma_f32_16x16x32_bf16 v[64:67], v[114:117], v[212:215], v[64:67]
	v_mfma_f32_16x16x32_bf16 v[232:235], v[110:113], v[180:183], v[92:95]
	v_mfma_f32_16x16x32_bf16 v[176:179], v[152:155], v[180:183], v[88:91]
	v_mfma_f32_16x16x32_bf16 v[180:183], v[110:113], v[208:211], v[76:79]
	v_mfma_f32_16x16x32_bf16 v[196:199], v[152:155], v[208:211], v[72:75]
	v_mfma_f32_16x16x32_bf16 v[200:203], v[152:155], v[216:219], v[64:67]
	s_barrier
	s_nop 0
	ds_read_b128 v[64:67], v147 offset:16384
	ds_read_b128 v[72:75], v147 offset:17408
	ds_read_b128 v[76:79], v147 offset:18432
	ds_read_b128 v[88:91], v147 offset:19456
	ds_read_b128 v[92:95], v147 offset:20480
	ds_read_b128 v[204:207], v147 offset:21504
	ds_read_b128 v[208:211], v147 offset:22528
	ds_read_b128 v[212:215], v147 offset:23552
	s_waitcnt vmcnt(4)
	s_barrier
	s_waitcnt lgkmcnt(0)
	s_waitcnt lgkmcnt(0)
	v_mfma_f32_16x16x32_bf16 v[60:63], v[164:167], v[64:67], v[60:63]
	v_mfma_f32_16x16x32_bf16 v[52:55], v[164:167], v[76:79], v[52:55]
	v_mfma_f32_16x16x32_bf16 v[48:51], v[142:145], v[76:79], v[48:51]
	v_mfma_f32_16x16x32_bf16 v[36:39], v[164:167], v[208:211], v[36:39]
	v_mfma_f32_16x16x32_bf16 v[32:35], v[142:145], v[208:211], v[32:35]
	v_mfma_f32_16x16x32_bf16 v[60:63], v[168:171], v[72:75], v[60:63]
	v_mfma_f32_16x16x32_bf16 v[56:59], v[142:145], v[64:67], v[56:59]
	v_mfma_f32_16x16x32_bf16 v[52:55], v[168:171], v[88:91], v[52:55]
	v_mfma_f32_16x16x32_bf16 v[48:51], v[172:175], v[88:91], v[48:51]
	v_mfma_f32_16x16x32_bf16 v[44:47], v[164:167], v[92:95], v[44:47]
	v_mfma_f32_16x16x32_bf16 v[40:43], v[142:145], v[92:95], v[40:43]
	v_mfma_f32_16x16x32_bf16 v[36:39], v[168:171], v[212:215], v[36:39]
	v_mfma_f32_16x16x32_bf16 v[32:35], v[172:175], v[212:215], v[32:35]
	v_mfma_f32_16x16x32_bf16 v[216:219], v[172:175], v[72:75], v[56:59]
	v_mfma_f32_16x16x32_bf16 v[236:239], v[168:171], v[204:207], v[44:47]
	v_mfma_f32_16x16x32_bf16 v[240:243], v[172:175], v[204:207], v[40:43]
	v_mfma_f32_16x16x32_bf16 v[20:23], v[106:109], v[76:79], v[20:23]
	v_mfma_f32_16x16x32_bf16 v[16:19], v[114:117], v[76:79], v[16:19]
	v_mfma_f32_16x16x32_bf16 v[4:7], v[106:109], v[208:211], v[4:7]
	v_mfma_f32_16x16x32_bf16 v[28:31], v[106:109], v[64:67], v[28:31]
	v_mfma_f32_16x16x32_bf16 v[24:27], v[114:117], v[64:67], v[24:27]
	v_mfma_f32_16x16x32_bf16 v[20:23], v[110:113], v[88:91], v[20:23]
	v_mfma_f32_16x16x32_bf16 v[16:19], v[152:155], v[88:91], v[16:19]
	v_mfma_f32_16x16x32_bf16 v[12:15], v[106:109], v[92:95], v[12:15]
	v_mfma_f32_16x16x32_bf16 v[8:11], v[114:117], v[92:95], v[8:11]
	v_mfma_f32_16x16x32_bf16 v[4:7], v[110:113], v[212:215], v[4:7]
	v_mfma_f32_16x16x32_bf16 v[0:3], v[114:117], v[208:211], v[0:3]
	v_mfma_f32_16x16x32_bf16 v[142:145], v[110:113], v[72:75], v[28:31]
	v_mfma_f32_16x16x32_bf16 v[164:167], v[152:155], v[72:75], v[24:27]
	v_mfma_f32_16x16x32_bf16 v[168:171], v[110:113], v[204:207], v[12:15]
	v_mfma_f32_16x16x32_bf16 v[172:175], v[152:155], v[204:207], v[8:11]
	v_mfma_f32_16x16x32_bf16 v[152:155], v[152:155], v[212:215], v[0:3]
	s_barrier
; #define WAIT_V(n) asm volatile("s_waitcnt vmcnt(%0)" ::"n"(n) : "memory")
; #define WAIT_L(n) asm volatile("s_waitcnt lgkmcnt(%0)" ::"n"(n) : "memory")
; #define LDA(dst, b, h) _Pragma("unroll") for (int m = 0; m < 4; ++m) _Pragma("unroll") for (int k = 0; k < 2; ++k) \
;       dst[m][k] = *(const bf16x8*)(SA(b, h) + aoff + (m * 2048 + k * 1024))
; #define LDB(dst, b, h) _Pragma("unroll") for (int n = 0; n < 2; ++n) _Pragma("unroll") for (int k = 0; k < 2; ++k) \
;       dst[n][k] = *(const bf16x8*)(SB(b, h) + boff + (n * 256 + k * 1024))
; #define BAR __builtin_amdgcn_s_barrier()
; template <int EPI, int N, int K>
; __device__ __forceinline__ void phase_gemm(const Params& p, const u16* __restrict__ A, const u16* __restrict__ Bt, int nM, char* shm,
;                            u16* __restrict__ outp, float* __restrict__ rowss) {
;     ...
;     { LDB(B0, 1, 0); LDA(At, 1, 0); WAIT_V(2); BAR; WAIT_L(0); MMA(0, 0, At, B0); BAR;
;       LDB(B1, 1, 1); WAIT_V(0); BAR; WAIT_L(0); MMA(0, 1, At, B1); BAR;
;       LDA(At, 1, 1); BAR; WAIT_L(0); MMA(1, 0, At, B0); MMA(1, 1, At, B1); BAR; }
;     if (wr == 0) BAR;
	s_nop 0
	ds_read_b128 v[0:3], v156
	ds_read_b128 v[8:11], v157
	ds_read_b128 v[12:15], v158
	ds_read_b128 v[156:159], v159
	ds_read_b128 v[24:27], v147 offset:32768
	ds_read_b128 v[28:31], v147 offset:33792
	ds_read_b128 v[40:43], v147 offset:34816
	ds_read_b128 v[44:47], v147 offset:35840
	ds_read_b128 v[56:59], v147 offset:36864
	ds_read_b128 v[64:67], v147 offset:37888
	ds_read_b128 v[204:207], v147 offset:38912
	ds_read_b128 v[208:211], v147 offset:39936
	s_waitcnt vmcnt(2)
	s_barrier
	s_waitcnt lgkmcnt(0)
	s_waitcnt lgkmcnt(0)
	v_mfma_f32_16x16x32_bf16 v[72:75], v[0:3], v[24:27], v[126:129]
	v_mfma_f32_16x16x32_bf16 v[126:129], v[8:11], v[28:31], v[72:75]
	v_mfma_f32_16x16x32_bf16 v[72:75], v[12:15], v[24:27], v[122:125]
	v_mfma_f32_16x16x32_bf16 v[114:117], v[156:159], v[28:31], v[72:75]
	v_mfma_f32_16x16x32_bf16 v[72:75], v[0:3], v[40:43], v[118:121]
	v_mfma_f32_16x16x32_bf16 v[106:109], v[8:11], v[44:47], v[72:75]
	v_mfma_f32_16x16x32_bf16 v[72:75], v[12:15], v[40:43], v[220:223]
	v_mfma_f32_16x16x32_bf16 v[110:113], v[156:159], v[44:47], v[72:75]
	v_mfma_f32_16x16x32_bf16 v[72:75], v[0:3], v[56:59], v[224:227]
	v_mfma_f32_16x16x32_bf16 v[88:91], v[8:11], v[64:67], v[72:75]
	v_mfma_f32_16x16x32_bf16 v[72:75], v[12:15], v[56:59], v[228:231]
	v_mfma_f32_16x16x32_bf16 v[92:95], v[156:159], v[64:67], v[72:75]
	v_mfma_f32_16x16x32_bf16 v[72:75], v[0:3], v[204:207], v[102:105]
	v_mfma_f32_16x16x32_bf16 v[76:79], v[12:15], v[204:207], v[98:101]
	v_mfma_f32_16x16x32_bf16 v[72:75], v[8:11], v[208:211], v[72:75]
	v_mfma_f32_16x16x32_bf16 v[76:79], v[156:159], v[208:211], v[76:79]
	s_barrier
	ds_read_b128 v[212:215], v160
	ds_read_b128 v[220:223], v161
	ds_read_b128 v[224:227], v162
	ds_read_b128 v[160:163], v163
	s_waitcnt vmcnt(0)
	s_barrier
	s_waitcnt lgkmcnt(0)
	s_waitcnt lgkmcnt(0)
	v_mfma_f32_16x16x32_bf16 v[98:101], v[212:215], v[24:27], v[232:235]
	v_mfma_f32_16x16x32_bf16 v[24:27], v[224:227], v[24:27], v[176:179]
	v_mfma_f32_16x16x32_bf16 v[122:125], v[160:163], v[28:31], v[24:27]
	v_mfma_f32_16x16x32_bf16 v[24:27], v[212:215], v[40:43], v[84:87]
	v_mfma_f32_16x16x32_bf16 v[118:121], v[220:223], v[28:31], v[98:101]
	v_mfma_f32_16x16x32_bf16 v[98:101], v[220:223], v[44:47], v[24:27]
	v_mfma_f32_16x16x32_bf16 v[24:27], v[224:227], v[40:43], v[80:83]
	v_mfma_f32_16x16x32_bf16 v[102:105], v[160:163], v[44:47], v[24:27]
	v_mfma_f32_16x16x32_bf16 v[24:27], v[212:215], v[56:59], v[180:183]
	v_mfma_f32_16x16x32_bf16 v[80:83], v[220:223], v[64:67], v[24:27]
	v_mfma_f32_16x16x32_bf16 v[24:27], v[224:227], v[56:59], v[196:199]
	v_mfma_f32_16x16x32_bf16 v[84:87], v[160:163], v[64:67], v[24:27]
	v_mfma_f32_16x16x32_bf16 v[24:27], v[212:215], v[204:207], v[68:71]
	v_mfma_f32_16x16x32_bf16 v[64:67], v[220:223], v[208:211], v[24:27]
	v_mfma_f32_16x16x32_bf16 v[24:27], v[224:227], v[204:207], v[200:203]
	v_mfma_f32_16x16x32_bf16 v[68:71], v[160:163], v[208:211], v[24:27]
	s_barrier
	ds_read_b128 v[176:179], v147 offset:49152
	ds_read_b128 v[180:183], v147 offset:50176
	ds_read_b128 v[196:199], v147 offset:51200
	ds_read_b128 v[200:203], v147 offset:52224
	ds_read_b128 v[204:207], v147 offset:53248
	ds_read_b128 v[208:211], v147 offset:54272
	ds_read_b128 v[228:231], v147 offset:55296
	ds_read_b128 v[232:235], v147 offset:56320
	s_barrier
	s_waitcnt lgkmcnt(0)
	s_waitcnt lgkmcnt(0)
	v_mfma_f32_16x16x32_bf16 v[24:27], v[0:3], v[176:179], v[60:63]
	v_mfma_f32_16x16x32_bf16 v[56:59], v[8:11], v[180:183], v[24:27]
	v_mfma_f32_16x16x32_bf16 v[24:27], v[12:15], v[176:179], v[216:219]
	v_mfma_f32_16x16x32_bf16 v[60:63], v[156:159], v[180:183], v[24:27]
	v_mfma_f32_16x16x32_bf16 v[24:27], v[0:3], v[196:199], v[52:55]
	v_mfma_f32_16x16x32_bf16 v[40:43], v[8:11], v[200:203], v[24:27]
	v_mfma_f32_16x16x32_bf16 v[24:27], v[12:15], v[196:199], v[48:51]
	v_mfma_f32_16x16x32_bf16 v[44:47], v[156:159], v[200:203], v[24:27]
	v_mfma_f32_16x16x32_bf16 v[24:27], v[0:3], v[204:207], v[236:239]
	v_mfma_f32_16x16x32_bf16 v[0:3], v[0:3], v[228:231], v[36:39]
	v_mfma_f32_16x16x32_bf16 v[24:27], v[8:11], v[208:211], v[24:27]
	v_mfma_f32_16x16x32_bf16 v[28:31], v[12:15], v[204:207], v[240:243]
	v_mfma_f32_16x16x32_bf16 v[8:11], v[8:11], v[232:235], v[0:3]
	v_mfma_f32_16x16x32_bf16 v[0:3], v[12:15], v[228:231], v[32:35]
	v_mfma_f32_16x16x32_bf16 v[28:31], v[156:159], v[208:211], v[28:31]
	v_mfma_f32_16x16x32_bf16 v[12:15], v[156:159], v[232:235], v[0:3]
	v_mfma_f32_16x16x32_bf16 v[0:3], v[212:215], v[176:179], v[142:145]
	v_mfma_f32_16x16x32_bf16 v[48:51], v[220:223], v[180:183], v[0:3]
	v_mfma_f32_16x16x32_bf16 v[0:3], v[224:227], v[176:179], v[164:167]
	v_mfma_f32_16x16x32_bf16 v[52:55], v[160:163], v[180:183], v[0:3]
	v_mfma_f32_16x16x32_bf16 v[0:3], v[212:215], v[196:199], v[20:23]
	v_mfma_f32_16x16x32_bf16 v[32:35], v[220:223], v[200:203], v[0:3]
	v_mfma_f32_16x16x32_bf16 v[0:3], v[224:227], v[196:199], v[16:19]
	v_mfma_f32_16x16x32_bf16 v[36:39], v[160:163], v[200:203], v[0:3]
	v_mfma_f32_16x16x32_bf16 v[0:3], v[212:215], v[204:207], v[168:171]
	v_mfma_f32_16x16x32_bf16 v[16:19], v[220:223], v[208:211], v[0:3]
	v_mfma_f32_16x16x32_bf16 v[0:3], v[224:227], v[204:207], v[172:175]
	v_mfma_f32_16x16x32_bf16 v[20:23], v[160:163], v[208:211], v[0:3]
	v_mfma_f32_16x16x32_bf16 v[0:3], v[212:215], v[228:231], v[4:7]
	v_mfma_f32_16x16x32_bf16 v[4:7], v[224:227], v[228:231], v[152:155]
	v_mfma_f32_16x16x32_bf16 v[0:3], v[220:223], v[232:235], v[0:3]
	v_mfma_f32_16x16x32_bf16 v[4:7], v[160:163], v[232:235], v[4:7]
	s_andn2_b64 vcc, exec, s[18:19]
	s_barrier
	s_cbranch_vccnz .LBB0_97
	s_barrier

; #define WAIT_V(n) asm volatile("s_waitcnt vmcnt(%0)" ::"n"(n) : "memory")
; #define WAIT_L(n) asm volatile("s_waitcnt lgkmcnt(%0)" ::"n"(n) : "memory")
; #define SBAR() __builtin_amdgcn_sched_barrier(0)
; #define STAGE(P, base, kt) do { _Pragma("unroll") for (int _i = 0; _i < 2; ++_i)                                        \
;       __builtin_amdgcn_global_load_lds((const unsigned*)((base) + (size_t)(sOff[_i] + (unsigned)(kt) * (BK * 2))),        \
;                                        (unsigned*)((P) + wid * 1024 + _i * 8192), 16, 0, 0); } while (0)
; #define LDA(dst, b, h) _Pragma("unroll") for (int m = 0; m < 4; ++m) _Pragma("unroll") for (int k = 0; k < 2; ++k) \
;       dst[m][k] = *(const bf16x8*)(SA(b, h) + aoff + (m * 2048 + k * 1024))
; #define LDB(dst, b, h) _Pragma("unroll") for (int n = 0; n < 2; ++n) _Pragma("unroll") for (int k = 0; k < 2; ++k) \
;       dst[n][k] = *(const bf16x8*)(SB(b, h) + boff + (n * 256 + k * 1024))
; #define BAR __builtin_amdgcn_s_barrier()
; template <int EPI, int N, int K>
; __device__ __forceinline__ void phase_gemm(const Params& p, const u16* __restrict__ A, const u16* __restrict__ Bt, int nM, char* shm,
;                            u16* __restrict__ outp, float* __restrict__ rowss) {
;     ...
;       LDB(B0, 0, 0); SBAR(); LDA(At, 0, 0); STAGE(SA(1, 1), A1, t + 1);
;       WAIT_L(8); BAR; WAIT_L(0); MMA(0, 0, At, B0); BAR; SBAR();
;       LDB(B1, 0, 1); STAGE(SB(0, 0), B0p, t + 2);
;       BAR; WAIT_L(0); MMA(0, 1, At, B1); BAR;
;       LDA(At, 0, 1); STAGE(SA(0, 0), A0, t + 2);
;       BAR; WAIT_L(0); MMA(1, 0, At, B0); BAR; SBAR();
;       STAGE(SB(0, 1), B1p, t + 2);
;       WAIT_V(6); BAR; MMA(1, 1, At, B1); BAR;
.LBB0_130:
	v_or_b32_e32 v147, 0x10000, v143
	v_add_u32_e32 v149, 0x10100, v143
	v_add_u32_e32 v148, 0x10400, v143
	ds_read_b128 v[156:159], v147
	ds_read_b128 v[160:163], v148
	v_add_u32_e32 v150, 0x10500, v143
	ds_read_b128 v[164:167], v149
	ds_read_b128 v[168:171], v150
	v_add_u32_e32 v240, v142, v140
	s_add_i32 s55, s5, 0xc000
	v_add_u32_e32 v151, 0x80, v240
	s_mov_b32 m0, s55
	v_add_u32_e32 v241, v142, v141
	s_add_i32 s54, s5, 0xe000
	ds_read_b128 v[172:175], v144
	ds_read_b128 v[176:179], v144 offset:1024
	ds_read_b128 v[180:183], v144 offset:2048
	ds_read_b128 v[196:199], v144 offset:3072
	ds_read_b128 v[200:203], v144 offset:4096
	ds_read_b128 v[204:207], v144 offset:5120
	ds_read_b128 v[208:211], v144 offset:6144
	ds_read_b128 v[212:215], v144 offset:7168
	global_load_lds_dwordx4 v151, s[16:17]
	v_add_u32_e32 v151, 0x80, v241
	s_mov_b32 m0, s54
	s_nop 0
	global_load_lds_dwordx4 v151, s[16:17]
	v_or_b32_e32 v151, 0x14000, v143
	v_add_u32_e32 v153, 0x14100, v143
	v_add_u32_e32 v152, 0x14400, v143
	ds_read_b128 v[216:219], v151
	ds_read_b128 v[220:223], v152
	v_add_u32_e32 v154, 0x14500, v143
	ds_read_b128 v[224:227], v153
	ds_read_b128 v[228:231], v154
	s_waitcnt lgkmcnt(0)
	s_barrier
	v_mfma_f32_16x16x32_bf16 v[126:129], v[156:159], v[172:175], v[126:129]
	v_mfma_f32_16x16x32_bf16 v[122:125], v[164:167], v[172:175], v[122:125]
	v_mfma_f32_16x16x32_bf16 v[118:121], v[156:159], v[180:183], v[118:121]
	v_mfma_f32_16x16x32_bf16 v[114:117], v[164:167], v[180:183], v[114:117]
	v_mfma_f32_16x16x32_bf16 v[110:113], v[156:159], v[200:203], v[110:113]
	v_mfma_f32_16x16x32_bf16 v[106:109], v[164:167], v[200:203], v[106:109]
	v_mfma_f32_16x16x32_bf16 v[102:105], v[156:159], v[208:211], v[102:105]
	v_mfma_f32_16x16x32_bf16 v[98:101], v[164:167], v[208:211], v[98:101]
	v_mfma_f32_16x16x32_bf16 v[126:129], v[160:163], v[176:179], v[126:129]
	v_mfma_f32_16x16x32_bf16 v[122:125], v[168:171], v[176:179], v[122:125]
	v_mfma_f32_16x16x32_bf16 v[118:121], v[160:163], v[196:199], v[118:121]
	v_mfma_f32_16x16x32_bf16 v[114:117], v[168:171], v[196:199], v[114:117]
	v_mfma_f32_16x16x32_bf16 v[110:113], v[160:163], v[204:207], v[110:113]
	v_mfma_f32_16x16x32_bf16 v[106:109], v[168:171], v[204:207], v[106:109]
	v_mfma_f32_16x16x32_bf16 v[102:105], v[160:163], v[212:215], v[102:105]
	v_mfma_f32_16x16x32_bf16 v[98:101], v[168:171], v[212:215], v[98:101]
	v_mfma_f32_16x16x32_bf16 v[92:95], v[216:219], v[172:175], v[92:95]
	v_mfma_f32_16x16x32_bf16 v[88:91], v[224:227], v[172:175], v[88:91]
	v_mfma_f32_16x16x32_bf16 v[84:87], v[216:219], v[180:183], v[84:87]
	v_mfma_f32_16x16x32_bf16 v[80:83], v[224:227], v[180:183], v[80:83]
	v_mfma_f32_16x16x32_bf16 v[76:79], v[216:219], v[200:203], v[76:79]
	v_mfma_f32_16x16x32_bf16 v[72:75], v[224:227], v[200:203], v[72:75]
	v_mfma_f32_16x16x32_bf16 v[68:71], v[216:219], v[208:211], v[68:71]
	v_mfma_f32_16x16x32_bf16 v[64:67], v[224:227], v[208:211], v[64:67]
	v_mfma_f32_16x16x32_bf16 v[92:95], v[220:223], v[176:179], v[92:95]
	v_mfma_f32_16x16x32_bf16 v[88:91], v[228:231], v[176:179], v[88:91]
	v_mfma_f32_16x16x32_bf16 v[84:87], v[220:223], v[196:199], v[84:87]
	v_mfma_f32_16x16x32_bf16 v[80:83], v[228:231], v[196:199], v[80:83]
	v_mfma_f32_16x16x32_bf16 v[76:79], v[220:223], v[204:207], v[76:79]
	v_mfma_f32_16x16x32_bf16 v[72:75], v[228:231], v[204:207], v[72:75]
	v_mfma_f32_16x16x32_bf16 v[68:71], v[220:223], v[212:215], v[68:71]
	v_mfma_f32_16x16x32_bf16 v[64:67], v[228:231], v[212:215], v[64:67]
	s_barrier
	ds_read_b128 v[172:175], v144 offset:16384
	ds_read_b128 v[176:179], v144 offset:17408
	ds_read_b128 v[180:183], v144 offset:18432
	ds_read_b128 v[196:199], v144 offset:19456
	ds_read_b128 v[200:203], v144 offset:20480
	ds_read_b128 v[204:207], v144 offset:21504
	ds_read_b128 v[208:211], v144 offset:22528
	ds_read_b128 v[212:215], v144 offset:23552
	s_mov_b32 m0, s23
	v_add_u32_e32 v232, 0x100, v240
	global_load_lds_dwordx4 v232, s[8:9]
	v_add_u32_e32 v233, 0x100, v241
	s_mov_b32 m0, s94
	s_nop 0
	global_load_lds_dwordx4 v233, s[8:9]
	s_mov_b32 m0, s5
	s_nop 0
	global_load_lds_dwordx4 v232, s[10:11]
	s_mov_b32 m0, s22
	s_nop 0
	global_load_lds_dwordx4 v233, s[10:11]
	s_mov_b32 m0, s95
	s_nop 0
	global_load_lds_dwordx4 v232, s[18:19]
	s_mov_b32 m0, s96
	s_nop 0
	global_load_lds_dwordx4 v233, s[18:19]
	s_waitcnt vmcnt(6)
	s_waitcnt lgkmcnt(0)
	s_barrier
	v_mfma_f32_16x16x32_bf16 v[60:63], v[156:159], v[172:175], v[60:63]
	v_mfma_f32_16x16x32_bf16 v[56:59], v[164:167], v[172:175], v[56:59]
	v_mfma_f32_16x16x32_bf16 v[52:55], v[156:159], v[180:183], v[52:55]
	v_mfma_f32_16x16x32_bf16 v[48:51], v[164:167], v[180:183], v[48:51]
	v_mfma_f32_16x16x32_bf16 v[44:47], v[156:159], v[200:203], v[44:47]
	v_mfma_f32_16x16x32_bf16 v[40:43], v[164:167], v[200:203], v[40:43]
	v_mfma_f32_16x16x32_bf16 v[36:39], v[156:159], v[208:211], v[36:39]
	v_mfma_f32_16x16x32_bf16 v[32:35], v[164:167], v[208:211], v[32:35]
	v_mfma_f32_16x16x32_bf16 v[60:63], v[160:163], v[176:179], v[60:63]
	v_mfma_f32_16x16x32_bf16 v[56:59], v[168:171], v[176:179], v[56:59]
	v_mfma_f32_16x16x32_bf16 v[52:55], v[160:163], v[196:199], v[52:55]
	v_mfma_f32_16x16x32_bf16 v[48:51], v[168:171], v[196:199], v[48:51]
	v_mfma_f32_16x16x32_bf16 v[44:47], v[160:163], v[204:207], v[44:47]
	v_mfma_f32_16x16x32_bf16 v[40:43], v[168:171], v[204:207], v[40:43]
	v_mfma_f32_16x16x32_bf16 v[36:39], v[160:163], v[212:215], v[36:39]
	v_mfma_f32_16x16x32_bf16 v[32:35], v[168:171], v[212:215], v[32:35]
	v_mfma_f32_16x16x32_bf16 v[28:31], v[216:219], v[172:175], v[28:31]
	v_mfma_f32_16x16x32_bf16 v[24:27], v[224:227], v[172:175], v[24:27]
	v_mfma_f32_16x16x32_bf16 v[20:23], v[216:219], v[180:183], v[20:23]
	v_mfma_f32_16x16x32_bf16 v[16:19], v[224:227], v[180:183], v[16:19]
	v_mfma_f32_16x16x32_bf16 v[12:15], v[216:219], v[200:203], v[12:15]
	v_mfma_f32_16x16x32_bf16 v[8:11], v[224:227], v[200:203], v[8:11]
	v_mfma_f32_16x16x32_bf16 v[4:7], v[216:219], v[208:211], v[4:7]
	v_mfma_f32_16x16x32_bf16 v[0:3], v[224:227], v[208:211], v[0:3]
	v_mfma_f32_16x16x32_bf16 v[28:31], v[220:223], v[176:179], v[28:31]
	v_mfma_f32_16x16x32_bf16 v[24:27], v[228:231], v[176:179], v[24:27]
	v_mfma_f32_16x16x32_bf16 v[20:23], v[220:223], v[196:199], v[20:23]
	v_mfma_f32_16x16x32_bf16 v[16:19], v[228:231], v[196:199], v[16:19]
	v_mfma_f32_16x16x32_bf16 v[12:15], v[220:223], v[204:207], v[12:15]
	v_mfma_f32_16x16x32_bf16 v[8:11], v[228:231], v[204:207], v[8:11]
	v_mfma_f32_16x16x32_bf16 v[4:7], v[220:223], v[212:215], v[4:7]
	v_mfma_f32_16x16x32_bf16 v[0:3], v[228:231], v[212:215], v[0:3]
	v_or_b32_e32 v155, 0x18000, v143
	v_add_u32_e32 v157, 0x18100, v143
	s_barrier
; #define WAIT_V(n) asm volatile("s_waitcnt vmcnt(%0)" ::"n"(n) : "memory")
; #define WAIT_L(n) asm volatile("s_waitcnt lgkmcnt(%0)" ::"n"(n) : "memory")
; #define SBAR() __builtin_amdgcn_sched_barrier(0)
; #define STAGE(P, base, kt) do { _Pragma("unroll") for (int _i = 0; _i < 2; ++_i)                                        \
;       __builtin_amdgcn_global_load_lds((const unsigned*)((base) + (size_t)(sOff[_i] + (unsigned)(kt) * (BK * 2))),        \
;                                        (unsigned*)((P) + wid * 1024 + _i * 8192), 16, 0, 0); } while (0)
; #define LDA(dst, b, h) _Pragma("unroll") for (int m = 0; m < 4; ++m) _Pragma("unroll") for (int k = 0; k < 2; ++k) \
;       dst[m][k] = *(const bf16x8*)(SA(b, h) + aoff + (m * 2048 + k * 1024))
; #define LDB(dst, b, h) _Pragma("unroll") for (int n = 0; n < 2; ++n) _Pragma("unroll") for (int k = 0; k < 2; ++k) \
;       dst[n][k] = *(const bf16x8*)(SB(b, h) + boff + (n * 256 + k * 1024))
; #define BAR __builtin_amdgcn_s_barrier()
; template <int EPI, int N, int K>
; __device__ __forceinline__ void phase_gemm(const Params& p, const u16* __restrict__ A, const u16* __restrict__ Bt, int nM, char* shm,
;                            u16* __restrict__ outp, float* __restrict__ rowss) {
;     ...
;       LDB(B0, 1, 0); SBAR(); LDA(At, 1, 0); STAGE(SA(0, 1), A1, t + 2);
;       WAIT_L(8); BAR; WAIT_L(0); MMA(0, 0, At, B0); BAR; SBAR();
;       LDB(B1, 1, 1); STAGE(SB(1, 0), B0p, t + 3);
;       BAR; WAIT_L(0); MMA(0, 1, At, B1); BAR;
;       LDA(At, 1, 1); STAGE(SA(1, 0), A0, t + 3);
;       BAR; WAIT_L(0); MMA(1, 0, At, B0); BAR; SBAR();
;       STAGE(SB(1, 1), B1p, t + 3);
;       WAIT_V(6); BAR; MMA(1, 1, At, B1); BAR;
	v_add_u32_e32 v156, 0x18400, v143
	ds_read_b128 v[164:167], v155
	ds_read_b128 v[168:171], v156
	v_add_u32_e32 v158, 0x18500, v143
	ds_read_b128 v[172:175], v157
	ds_read_b128 v[176:179], v158
	s_mov_b32 m0, s97
	ds_read_b128 v[180:183], v144 offset:32768
	ds_read_b128 v[196:199], v144 offset:33792
	ds_read_b128 v[200:203], v144 offset:34816
	ds_read_b128 v[204:207], v144 offset:35840
	ds_read_b128 v[208:211], v144 offset:36864
	ds_read_b128 v[212:215], v144 offset:37888
	ds_read_b128 v[216:219], v144 offset:38912
	ds_read_b128 v[220:223], v144 offset:39936
	global_load_lds_dwordx4 v232, s[16:17]
	s_mov_b32 m0, s33
	s_nop 0
	global_load_lds_dwordx4 v233, s[16:17]
	v_or_b32_e32 v159, 0x1c000, v143
	v_add_u32_e32 v161, 0x1c100, v143
	v_add_u32_e32 v160, 0x1c400, v143
	ds_read_b128 v[224:227], v159
	ds_read_b128 v[228:231], v160
	v_add_u32_e32 v162, 0x1c500, v143
	ds_read_b128 v[232:235], v161
	ds_read_b128 v[236:239], v162
	s_waitcnt lgkmcnt(0)
	s_barrier
	v_mfma_f32_16x16x32_bf16 v[126:129], v[164:167], v[180:183], v[126:129]
	v_mfma_f32_16x16x32_bf16 v[122:125], v[172:175], v[180:183], v[122:125]
	v_mfma_f32_16x16x32_bf16 v[118:121], v[164:167], v[200:203], v[118:121]
	v_mfma_f32_16x16x32_bf16 v[114:117], v[172:175], v[200:203], v[114:117]
	v_mfma_f32_16x16x32_bf16 v[110:113], v[164:167], v[208:211], v[110:113]
	v_mfma_f32_16x16x32_bf16 v[106:109], v[172:175], v[208:211], v[106:109]
	v_mfma_f32_16x16x32_bf16 v[102:105], v[164:167], v[216:219], v[102:105]
	v_mfma_f32_16x16x32_bf16 v[98:101], v[172:175], v[216:219], v[98:101]
	v_mfma_f32_16x16x32_bf16 v[126:129], v[168:171], v[196:199], v[126:129]
	v_mfma_f32_16x16x32_bf16 v[122:125], v[176:179], v[196:199], v[122:125]
	v_mfma_f32_16x16x32_bf16 v[118:121], v[168:171], v[204:207], v[118:121]
	v_mfma_f32_16x16x32_bf16 v[114:117], v[176:179], v[204:207], v[114:117]
	v_mfma_f32_16x16x32_bf16 v[110:113], v[168:171], v[212:215], v[110:113]
	v_mfma_f32_16x16x32_bf16 v[106:109], v[176:179], v[212:215], v[106:109]
	v_mfma_f32_16x16x32_bf16 v[102:105], v[168:171], v[220:223], v[102:105]
	v_mfma_f32_16x16x32_bf16 v[98:101], v[176:179], v[220:223], v[98:101]
	v_mfma_f32_16x16x32_bf16 v[92:95], v[224:227], v[180:183], v[92:95]
	v_mfma_f32_16x16x32_bf16 v[88:91], v[232:235], v[180:183], v[88:91]
	v_mfma_f32_16x16x32_bf16 v[84:87], v[224:227], v[200:203], v[84:87]
	v_mfma_f32_16x16x32_bf16 v[80:83], v[232:235], v[200:203], v[80:83]
	v_mfma_f32_16x16x32_bf16 v[76:79], v[224:227], v[208:211], v[76:79]
	v_mfma_f32_16x16x32_bf16 v[72:75], v[232:235], v[208:211], v[72:75]
	v_mfma_f32_16x16x32_bf16 v[68:71], v[224:227], v[216:219], v[68:71]
	v_mfma_f32_16x16x32_bf16 v[64:67], v[232:235], v[216:219], v[64:67]
	v_mfma_f32_16x16x32_bf16 v[92:95], v[228:231], v[196:199], v[92:95]
	v_mfma_f32_16x16x32_bf16 v[88:91], v[236:239], v[196:199], v[88:91]
	v_mfma_f32_16x16x32_bf16 v[84:87], v[228:231], v[204:207], v[84:87]
	v_mfma_f32_16x16x32_bf16 v[80:83], v[236:239], v[204:207], v[80:83]
	v_mfma_f32_16x16x32_bf16 v[76:79], v[228:231], v[212:215], v[76:79]
	v_mfma_f32_16x16x32_bf16 v[72:75], v[236:239], v[212:215], v[72:75]
	v_mfma_f32_16x16x32_bf16 v[68:71], v[228:231], v[220:223], v[68:71]
	v_mfma_f32_16x16x32_bf16 v[64:67], v[236:239], v[220:223], v[64:67]
	s_barrier
	ds_read_b128 v[180:183], v144 offset:49152
	ds_read_b128 v[196:199], v144 offset:50176
	ds_read_b128 v[200:203], v144 offset:51200
	ds_read_b128 v[204:207], v144 offset:52224
	ds_read_b128 v[208:211], v144 offset:53248
	ds_read_b128 v[212:215], v144 offset:54272
	ds_read_b128 v[216:219], v144 offset:55296
	ds_read_b128 v[220:223], v144 offset:56320
	s_mov_b32 m0, s35
	v_add_u32_e32 v163, 0x180, v240
	global_load_lds_dwordx4 v163, s[8:9]
	v_add_u32_e32 v240, 0x180, v241
	s_mov_b32 m0, s93
	s_nop 0
	global_load_lds_dwordx4 v240, s[8:9]
	s_mov_b32 m0, s24
	s_nop 0
	global_load_lds_dwordx4 v163, s[10:11]
	s_mov_b32 m0, s25
	s_nop 0
	global_load_lds_dwordx4 v240, s[10:11]
	s_mov_b32 m0, s26
	s_nop 0
	global_load_lds_dwordx4 v163, s[18:19]
	s_mov_b32 m0, s27
	s_nop 0
	global_load_lds_dwordx4 v240, s[18:19]
	s_waitcnt vmcnt(6)
	s_waitcnt lgkmcnt(0)
	s_barrier
	v_mfma_f32_16x16x32_bf16 v[60:63], v[164:167], v[180:183], v[60:63]
	v_mfma_f32_16x16x32_bf16 v[56:59], v[172:175], v[180:183], v[56:59]
	v_mfma_f32_16x16x32_bf16 v[52:55], v[164:167], v[200:203], v[52:55]
	v_mfma_f32_16x16x32_bf16 v[48:51], v[172:175], v[200:203], v[48:51]
	v_mfma_f32_16x16x32_bf16 v[44:47], v[164:167], v[208:211], v[44:47]
	v_mfma_f32_16x16x32_bf16 v[40:43], v[172:175], v[208:211], v[40:43]
	v_mfma_f32_16x16x32_bf16 v[36:39], v[164:167], v[216:219], v[36:39]
	v_mfma_f32_16x16x32_bf16 v[32:35], v[172:175], v[216:219], v[32:35]
	v_mfma_f32_16x16x32_bf16 v[60:63], v[168:171], v[196:199], v[60:63]
	v_mfma_f32_16x16x32_bf16 v[56:59], v[176:179], v[196:199], v[56:59]
	v_mfma_f32_16x16x32_bf16 v[52:55], v[168:171], v[204:207], v[52:55]
	v_mfma_f32_16x16x32_bf16 v[48:51], v[176:179], v[204:207], v[48:51]
	v_mfma_f32_16x16x32_bf16 v[44:47], v[168:171], v[212:215], v[44:47]
	v_mfma_f32_16x16x32_bf16 v[40:43], v[176:179], v[212:215], v[40:43]
	v_mfma_f32_16x16x32_bf16 v[36:39], v[168:171], v[220:223], v[36:39]
	v_mfma_f32_16x16x32_bf16 v[32:35], v[176:179], v[220:223], v[32:35]
	v_mfma_f32_16x16x32_bf16 v[28:31], v[224:227], v[180:183], v[28:31]
	v_mfma_f32_16x16x32_bf16 v[24:27], v[232:235], v[180:183], v[24:27]
	v_mfma_f32_16x16x32_bf16 v[20:23], v[224:227], v[200:203], v[20:23]
	v_mfma_f32_16x16x32_bf16 v[16:19], v[232:235], v[200:203], v[16:19]
	v_mfma_f32_16x16x32_bf16 v[12:15], v[224:227], v[208:211], v[12:15]
	v_mfma_f32_16x16x32_bf16 v[8:11], v[232:235], v[208:211], v[8:11]
	v_mfma_f32_16x16x32_bf16 v[4:7], v[224:227], v[216:219], v[4:7]
	v_mfma_f32_16x16x32_bf16 v[0:3], v[232:235], v[216:219], v[0:3]
	v_mfma_f32_16x16x32_bf16 v[28:31], v[228:231], v[196:199], v[28:31]
	v_mfma_f32_16x16x32_bf16 v[24:27], v[236:239], v[196:199], v[24:27]
	v_mfma_f32_16x16x32_bf16 v[20:23], v[228:231], v[204:207], v[20:23]
	v_mfma_f32_16x16x32_bf16 v[16:19], v[236:239], v[204:207], v[16:19]
	v_mfma_f32_16x16x32_bf16 v[12:15], v[228:231], v[212:215], v[12:15]
	v_mfma_f32_16x16x32_bf16 v[8:11], v[236:239], v[212:215], v[8:11]
	v_mfma_f32_16x16x32_bf16 v[4:7], v[228:231], v[220:223], v[4:7]
	v_mfma_f32_16x16x32_bf16 v[0:3], v[236:239], v[220:223], v[0:3]
	s_add_i32 s53, s53, 2
	v_add_u32_e32 v141, 0x100, v141
	s_cmp_lt_u32 s53, 12
	v_add_u32_e32 v140, 0x100, v140
	s_barrier
; #define WAIT_V(n) asm volatile("s_waitcnt vmcnt(%0)" ::"n"(n) : "memory")
; #define WAIT_L(n) asm volatile("s_waitcnt lgkmcnt(%0)" ::"n"(n) : "memory")
; #define STAGE(P, base, kt) do { _Pragma("unroll") for (int _i = 0; _i < 2; ++_i)                                        \
;       __builtin_amdgcn_global_load_lds((const unsigned*)((base) + (size_t)(sOff[_i] + (unsigned)(kt) * (BK * 2))),        \
;                                        (unsigned*)((P) + wid * 1024 + _i * 8192), 16, 0, 0); } while (0)
; #define LDA(dst, b, h) _Pragma("unroll") for (int m = 0; m < 4; ++m) _Pragma("unroll") for (int k = 0; k < 2; ++k) \
;       dst[m][k] = *(const bf16x8*)(SA(b, h) + aoff + (m * 2048 + k * 1024))
; #define LDB(dst, b, h) _Pragma("unroll") for (int n = 0; n < 2; ++n) _Pragma("unroll") for (int k = 0; k < 2; ++k) \
;       dst[n][k] = *(const bf16x8*)(SB(b, h) + boff + (n * 256 + k * 1024))
; #define BAR __builtin_amdgcn_s_barrier()
; template <int EPI, int N, int K>
; __device__ __forceinline__ void phase_gemm(const Params& p, const u16* __restrict__ A, const u16* __restrict__ Bt, int nM, char* shm,
;                            u16* __restrict__ outp, float* __restrict__ rowss) {
;     ...
;     { LDB(B0, 0, 0); LDA(At, 0, 0); STAGE(SA(1, 1), A1, nt - 1);
;       BAR; WAIT_L(0); MMA(0, 0, At, B0); BAR;
;       LDB(B1, 0, 1); BAR; WAIT_L(0); MMA(0, 1, At, B1); BAR;
;       LDA(At, 0, 1); WAIT_V(4); BAR; WAIT_L(0); MMA(1, 0, At, B0); MMA(1, 1, At, B1); BAR; }
;     { LDB(B0, 1, 0); LDA(At, 1, 0); WAIT_V(2); BAR; WAIT_L(0); MMA(0, 0, At, B0); BAR;
;       LDB(B1, 1, 1); WAIT_V(0); BAR; WAIT_L(0); MMA(0, 1, At, B1); BAR;
;       LDA(At, 1, 1); BAR; WAIT_L(0); MMA(1, 0, At, B0); MMA(1, 1, At, B1); BAR; }
	s_cbranch_scc1 .LBB0_130
	s_mov_b32 m0, s55
	v_lshl_add_u64 v[140:141], s[16:17], 0, v[136:137]
	ds_read_b128 v[164:167], v147
	ds_read_b128 v[168:171], v148
	ds_read_b128 v[172:175], v149
	ds_read_b128 v[176:179], v150
	ds_read_b128 v[180:183], v144
	ds_read_b128 v[196:199], v144 offset:1024
	ds_read_b128 v[200:203], v144 offset:2048
	ds_read_b128 v[204:207], v144 offset:3072
	ds_read_b128 v[208:211], v144 offset:4096
	ds_read_b128 v[212:215], v144 offset:5120
	ds_read_b128 v[216:219], v144 offset:6144
	ds_read_b128 v[220:223], v144 offset:7168
	global_load_lds_dwordx4 v[140:141], off
	v_lshl_add_u64 v[140:141], s[16:17], 0, v[138:139]
	s_mov_b32 m0, s54
	s_nop 0
	global_load_lds_dwordx4 v[140:141], off
	s_barrier
	s_waitcnt lgkmcnt(0)
	s_waitcnt lgkmcnt(0)
	v_mfma_f32_16x16x32_bf16 v[126:129], v[164:167], v[180:183], v[126:129]
	v_mfma_f32_16x16x32_bf16 v[118:121], v[164:167], v[200:203], v[118:121]
	v_mfma_f32_16x16x32_bf16 v[110:113], v[164:167], v[208:211], v[110:113]
	v_mfma_f32_16x16x32_bf16 v[102:105], v[164:167], v[216:219], v[102:105]
	v_mfma_f32_16x16x32_bf16 v[126:129], v[168:171], v[196:199], v[126:129]
	v_mfma_f32_16x16x32_bf16 v[122:125], v[172:175], v[180:183], v[122:125]
	v_mfma_f32_16x16x32_bf16 v[118:121], v[168:171], v[204:207], v[118:121]
	v_mfma_f32_16x16x32_bf16 v[114:117], v[172:175], v[200:203], v[114:117]
	v_mfma_f32_16x16x32_bf16 v[110:113], v[168:171], v[212:215], v[110:113]
	v_mfma_f32_16x16x32_bf16 v[106:109], v[172:175], v[208:211], v[106:109]
	v_mfma_f32_16x16x32_bf16 v[102:105], v[168:171], v[220:223], v[102:105]
	v_mfma_f32_16x16x32_bf16 v[98:101], v[172:175], v[216:219], v[98:101]
	v_mfma_f32_16x16x32_bf16 v[224:227], v[176:179], v[196:199], v[122:125]
	v_mfma_f32_16x16x32_bf16 v[228:231], v[176:179], v[204:207], v[114:117]
	v_mfma_f32_16x16x32_bf16 v[232:235], v[176:179], v[212:215], v[106:109]
	v_mfma_f32_16x16x32_bf16 v[236:239], v[176:179], v[220:223], v[98:101]
	s_barrier
	s_nop 1
	ds_read_b128 v[98:101], v151
	ds_read_b128 v[106:109], v152
	ds_read_b128 v[114:117], v153
	ds_read_b128 v[122:125], v154
	s_barrier
	s_waitcnt lgkmcnt(0)
	s_waitcnt lgkmcnt(0)
	v_mfma_f32_16x16x32_bf16 v[92:95], v[98:101], v[180:183], v[92:95]
	v_mfma_f32_16x16x32_bf16 v[84:87], v[98:101], v[200:203], v[84:87]
	v_mfma_f32_16x16x32_bf16 v[76:79], v[98:101], v[208:211], v[76:79]
	v_mfma_f32_16x16x32_bf16 v[68:71], v[98:101], v[216:219], v[68:71]
	v_mfma_f32_16x16x32_bf16 v[92:95], v[106:109], v[196:199], v[92:95]
	v_mfma_f32_16x16x32_bf16 v[88:91], v[114:117], v[180:183], v[88:91]
	v_mfma_f32_16x16x32_bf16 v[84:87], v[106:109], v[204:207], v[84:87]
	v_mfma_f32_16x16x32_bf16 v[80:83], v[114:117], v[200:203], v[80:83]
	v_mfma_f32_16x16x32_bf16 v[76:79], v[106:109], v[212:215], v[76:79]
	v_mfma_f32_16x16x32_bf16 v[72:75], v[114:117], v[208:211], v[72:75]
	v_mfma_f32_16x16x32_bf16 v[68:71], v[106:109], v[220:223], v[68:71]
	v_mfma_f32_16x16x32_bf16 v[64:67], v[114:117], v[216:219], v[64:67]
	v_mfma_f32_16x16x32_bf16 v[148:151], v[122:125], v[196:199], v[88:91]
	v_mfma_f32_16x16x32_bf16 v[180:183], v[122:125], v[204:207], v[80:83]
	v_mfma_f32_16x16x32_bf16 v[196:199], v[122:125], v[212:215], v[72:75]
	v_mfma_f32_16x16x32_bf16 v[200:203], v[122:125], v[220:223], v[64:67]
	s_barrier
	s_nop 1
	ds_read_b128 v[64:67], v144 offset:16384
	ds_read_b128 v[72:75], v144 offset:17408
	ds_read_b128 v[80:83], v144 offset:18432
	ds_read_b128 v[88:91], v144 offset:19456
	ds_read_b128 v[204:207], v144 offset:20480
	ds_read_b128 v[208:211], v144 offset:21504
	ds_read_b128 v[212:215], v144 offset:22528
	ds_read_b128 v[216:219], v144 offset:23552
	s_waitcnt vmcnt(4)
	s_barrier
	s_waitcnt lgkmcnt(0)
	s_waitcnt lgkmcnt(0)
	v_mfma_f32_16x16x32_bf16 v[60:63], v[164:167], v[64:67], v[60:63]
	v_mfma_f32_16x16x32_bf16 v[52:55], v[164:167], v[80:83], v[52:55]
	v_mfma_f32_16x16x32_bf16 v[44:47], v[164:167], v[204:207], v[44:47]
	v_mfma_f32_16x16x32_bf16 v[36:39], v[164:167], v[212:215], v[36:39]
	v_mfma_f32_16x16x32_bf16 v[60:63], v[168:171], v[72:75], v[60:63]
	v_mfma_f32_16x16x32_bf16 v[56:59], v[172:175], v[64:67], v[56:59]
	v_mfma_f32_16x16x32_bf16 v[52:55], v[168:171], v[88:91], v[52:55]
	v_mfma_f32_16x16x32_bf16 v[48:51], v[172:175], v[80:83], v[48:51]
	v_mfma_f32_16x16x32_bf16 v[44:47], v[168:171], v[208:211], v[44:47]
	v_mfma_f32_16x16x32_bf16 v[40:43], v[172:175], v[204:207], v[40:43]
	v_mfma_f32_16x16x32_bf16 v[36:39], v[168:171], v[216:219], v[36:39]
	v_mfma_f32_16x16x32_bf16 v[32:35], v[172:175], v[212:215], v[32:35]
	v_mfma_f32_16x16x32_bf16 v[220:223], v[176:179], v[72:75], v[56:59]
	v_mfma_f32_16x16x32_bf16 v[240:243], v[176:179], v[88:91], v[48:51]
	v_mfma_f32_16x16x32_bf16 v[244:247], v[176:179], v[208:211], v[40:43]
	v_mfma_f32_16x16x32_bf16 v[164:167], v[176:179], v[216:219], v[32:35]
	v_mfma_f32_16x16x32_bf16 v[28:31], v[98:101], v[64:67], v[28:31]
	v_mfma_f32_16x16x32_bf16 v[20:23], v[98:101], v[80:83], v[20:23]
	v_mfma_f32_16x16x32_bf16 v[12:15], v[98:101], v[204:207], v[12:15]
	v_mfma_f32_16x16x32_bf16 v[4:7], v[98:101], v[212:215], v[4:7]
	v_mfma_f32_16x16x32_bf16 v[28:31], v[106:109], v[72:75], v[28:31]
	v_mfma_f32_16x16x32_bf16 v[24:27], v[114:117], v[64:67], v[24:27]
	v_mfma_f32_16x16x32_bf16 v[20:23], v[106:109], v[88:91], v[20:23]
	v_mfma_f32_16x16x32_bf16 v[16:19], v[114:117], v[80:83], v[16:19]
	v_mfma_f32_16x16x32_bf16 v[12:15], v[106:109], v[208:211], v[12:15]
	v_mfma_f32_16x16x32_bf16 v[8:11], v[114:117], v[204:207], v[8:11]
	v_mfma_f32_16x16x32_bf16 v[4:7], v[106:109], v[216:219], v[4:7]
	v_mfma_f32_16x16x32_bf16 v[0:3], v[114:117], v[212:215], v[0:3]
	v_mfma_f32_16x16x32_bf16 v[168:171], v[122:125], v[72:75], v[24:27]
	v_mfma_f32_16x16x32_bf16 v[172:175], v[122:125], v[88:91], v[16:19]
	v_mfma_f32_16x16x32_bf16 v[176:179], v[122:125], v[208:211], v[8:11]
	v_mfma_f32_16x16x32_bf16 v[204:207], v[122:125], v[216:219], v[0:3]
	s_barrier
; #define WAIT_V(n) asm volatile("s_waitcnt vmcnt(%0)" ::"n"(n) : "memory")
; #define WAIT_L(n) asm volatile("s_waitcnt lgkmcnt(%0)" ::"n"(n) : "memory")
; #define LDA(dst, b, h) _Pragma("unroll") for (int m = 0; m < 4; ++m) _Pragma("unroll") for (int k = 0; k < 2; ++k) \
;       dst[m][k] = *(const bf16x8*)(SA(b, h) + aoff + (m * 2048 + k * 1024))
; #define LDB(dst, b, h) _Pragma("unroll") for (int n = 0; n < 2; ++n) _Pragma("unroll") for (int k = 0; k < 2; ++k) \
;       dst[n][k] = *(const bf16x8*)(SB(b, h) + boff + (n * 256 + k * 1024))
; #define BAR __builtin_amdgcn_s_barrier()
; template <int EPI, int N, int K>
; __device__ __forceinline__ void phase_gemm(const Params& p, const u16* __restrict__ A, const u16* __restrict__ Bt, int nM, char* shm,
;                            u16* __restrict__ outp, float* __restrict__ rowss) {
;     ...
;     { LDB(B0, 1, 0); LDA(At, 1, 0); WAIT_V(2); BAR; WAIT_L(0); MMA(0, 0, At, B0); BAR;
;       LDB(B1, 1, 1); WAIT_V(0); BAR; WAIT_L(0); MMA(0, 1, At, B1); BAR;
;       LDA(At, 1, 1); BAR; WAIT_L(0); MMA(1, 0, At, B0); MMA(1, 1, At, B1); BAR; }
;     if (wr == 0) BAR;
	s_nop 1
	ds_read_b128 v[0:3], v155
	ds_read_b128 v[8:11], v156
	ds_read_b128 v[152:155], v157
	ds_read_b128 v[208:211], v158
	ds_read_b128 v[16:19], v144 offset:32768
	ds_read_b128 v[24:27], v144 offset:33792
	ds_read_b128 v[32:35], v144 offset:34816
	ds_read_b128 v[40:43], v144 offset:35840
	ds_read_b128 v[48:51], v144 offset:36864
	ds_read_b128 v[56:59], v144 offset:37888
	ds_read_b128 v[212:215], v144 offset:38912
	ds_read_b128 v[216:219], v144 offset:39936
	s_waitcnt vmcnt(2)
	s_barrier
	s_waitcnt lgkmcnt(0)
	s_waitcnt lgkmcnt(0)
	v_mfma_f32_16x16x32_bf16 v[64:67], v[0:3], v[16:19], v[126:129]
	v_mfma_f32_16x16x32_bf16 v[122:125], v[8:11], v[24:27], v[64:67]
	v_mfma_f32_16x16x32_bf16 v[64:67], v[152:155], v[16:19], v[224:227]
	v_mfma_f32_16x16x32_bf16 v[114:117], v[208:211], v[24:27], v[64:67]
	v_mfma_f32_16x16x32_bf16 v[64:67], v[0:3], v[32:35], v[118:121]
	v_mfma_f32_16x16x32_bf16 v[106:109], v[8:11], v[40:43], v[64:67]
	v_mfma_f32_16x16x32_bf16 v[64:67], v[152:155], v[32:35], v[228:231]
	v_mfma_f32_16x16x32_bf16 v[98:101], v[208:211], v[40:43], v[64:67]
	v_mfma_f32_16x16x32_bf16 v[64:67], v[0:3], v[48:51], v[110:113]
	v_mfma_f32_16x16x32_bf16 v[88:91], v[8:11], v[56:59], v[64:67]
	v_mfma_f32_16x16x32_bf16 v[64:67], v[152:155], v[48:51], v[232:235]
	v_mfma_f32_16x16x32_bf16 v[80:83], v[208:211], v[56:59], v[64:67]
	v_mfma_f32_16x16x32_bf16 v[64:67], v[0:3], v[212:215], v[102:105]
	v_mfma_f32_16x16x32_bf16 v[72:75], v[8:11], v[216:219], v[64:67]
	v_mfma_f32_16x16x32_bf16 v[64:67], v[152:155], v[212:215], v[236:239]
	v_mfma_f32_16x16x32_bf16 v[64:67], v[208:211], v[216:219], v[64:67]
	s_barrier
	ds_read_b128 v[156:159], v159
	ds_read_b128 v[224:227], v160
	ds_read_b128 v[228:231], v161
	ds_read_b128 v[160:163], v162
	s_waitcnt vmcnt(0)
	s_barrier
	s_waitcnt lgkmcnt(0)
	s_waitcnt lgkmcnt(0)
	v_mfma_f32_16x16x32_bf16 v[92:95], v[156:159], v[16:19], v[92:95]
	v_mfma_f32_16x16x32_bf16 v[16:19], v[228:231], v[16:19], v[148:151]
	v_mfma_f32_16x16x32_bf16 v[118:121], v[160:163], v[24:27], v[16:19]
	v_mfma_f32_16x16x32_bf16 v[16:19], v[156:159], v[32:35], v[84:87]
	v_mfma_f32_16x16x32_bf16 v[110:113], v[224:227], v[40:43], v[16:19]
	v_mfma_f32_16x16x32_bf16 v[16:19], v[228:231], v[32:35], v[180:183]
	v_mfma_f32_16x16x32_bf16 v[102:105], v[160:163], v[40:43], v[16:19]
	v_mfma_f32_16x16x32_bf16 v[16:19], v[156:159], v[48:51], v[76:79]
	v_mfma_f32_16x16x32_bf16 v[126:129], v[224:227], v[24:27], v[92:95]
	v_mfma_f32_16x16x32_bf16 v[92:95], v[224:227], v[56:59], v[16:19]
	v_mfma_f32_16x16x32_bf16 v[16:19], v[228:231], v[48:51], v[196:199]
	v_mfma_f32_16x16x32_bf16 v[84:87], v[160:163], v[56:59], v[16:19]
	v_mfma_f32_16x16x32_bf16 v[16:19], v[156:159], v[212:215], v[68:71]
	v_mfma_f32_16x16x32_bf16 v[76:79], v[224:227], v[216:219], v[16:19]
	v_mfma_f32_16x16x32_bf16 v[16:19], v[228:231], v[212:215], v[200:203]
	v_mfma_f32_16x16x32_bf16 v[68:71], v[160:163], v[216:219], v[16:19]
	s_barrier
	ds_read_b128 v[148:151], v144 offset:49152
	ds_read_b128 v[180:183], v144 offset:50176
	ds_read_b128 v[196:199], v144 offset:51200
	ds_read_b128 v[200:203], v144 offset:52224
	ds_read_b128 v[212:215], v144 offset:53248
	ds_read_b128 v[216:219], v144 offset:54272
	ds_read_b128 v[232:235], v144 offset:55296
	ds_read_b128 v[236:239], v144 offset:56320
	s_barrier
	s_waitcnt lgkmcnt(0)
	s_waitcnt lgkmcnt(0)
	v_mfma_f32_16x16x32_bf16 v[16:19], v[0:3], v[148:151], v[60:63]
	v_mfma_f32_16x16x32_bf16 v[56:59], v[8:11], v[180:183], v[16:19]
	v_mfma_f32_16x16x32_bf16 v[16:19], v[152:155], v[148:151], v[220:223]
	v_mfma_f32_16x16x32_bf16 v[48:51], v[208:211], v[180:183], v[16:19]
	v_mfma_f32_16x16x32_bf16 v[16:19], v[0:3], v[196:199], v[52:55]
	v_mfma_f32_16x16x32_bf16 v[40:43], v[8:11], v[200:203], v[16:19]
	v_mfma_f32_16x16x32_bf16 v[16:19], v[152:155], v[196:199], v[240:243]
	v_mfma_f32_16x16x32_bf16 v[32:35], v[208:211], v[200:203], v[16:19]
	v_mfma_f32_16x16x32_bf16 v[16:19], v[0:3], v[212:215], v[44:47]
	v_mfma_f32_16x16x32_bf16 v[0:3], v[0:3], v[232:235], v[36:39]
	v_mfma_f32_16x16x32_bf16 v[24:27], v[8:11], v[216:219], v[16:19]
	v_mfma_f32_16x16x32_bf16 v[16:19], v[152:155], v[212:215], v[244:247]
	v_mfma_f32_16x16x32_bf16 v[8:11], v[8:11], v[236:239], v[0:3]
	v_mfma_f32_16x16x32_bf16 v[0:3], v[152:155], v[232:235], v[164:167]
	v_mfma_f32_16x16x32_bf16 v[16:19], v[208:211], v[216:219], v[16:19]
	v_mfma_f32_16x16x32_bf16 v[0:3], v[208:211], v[236:239], v[0:3]
	v_mfma_f32_16x16x32_bf16 v[28:31], v[156:159], v[148:151], v[28:31]
	v_mfma_f32_16x16x32_bf16 v[60:63], v[224:227], v[180:183], v[28:31]
	v_mfma_f32_16x16x32_bf16 v[28:31], v[228:231], v[148:151], v[168:171]
	v_mfma_f32_16x16x32_bf16 v[20:23], v[156:159], v[196:199], v[20:23]
	v_mfma_f32_16x16x32_bf16 v[12:15], v[156:159], v[212:215], v[12:15]
	v_mfma_f32_16x16x32_bf16 v[52:55], v[160:163], v[180:183], v[28:31]
	v_mfma_f32_16x16x32_bf16 v[44:47], v[224:227], v[200:203], v[20:23]
	v_mfma_f32_16x16x32_bf16 v[20:23], v[228:231], v[196:199], v[172:175]
	v_mfma_f32_16x16x32_bf16 v[28:31], v[224:227], v[216:219], v[12:15]
	v_mfma_f32_16x16x32_bf16 v[12:15], v[228:231], v[212:215], v[176:179]
	v_mfma_f32_16x16x32_bf16 v[4:7], v[156:159], v[232:235], v[4:7]
	v_mfma_f32_16x16x32_bf16 v[36:39], v[160:163], v[200:203], v[20:23]
	v_mfma_f32_16x16x32_bf16 v[20:23], v[160:163], v[216:219], v[12:15]
	v_mfma_f32_16x16x32_bf16 v[12:15], v[224:227], v[236:239], v[4:7]
	v_mfma_f32_16x16x32_bf16 v[4:7], v[228:231], v[232:235], v[204:207]
	v_mfma_f32_16x16x32_bf16 v[4:7], v[160:163], v[236:239], v[4:7]
	s_andn2_b64 vcc, exec, s[14:15]
	s_barrier
	s_cbranch_vccnz .LBB0_133
	s_barrier

; #define WAIT_V(n) asm volatile("s_waitcnt vmcnt(%0)" ::"n"(n) : "memory")
; #define WAIT_L(n) asm volatile("s_waitcnt lgkmcnt(%0)" ::"n"(n) : "memory")
; #define SBAR() __builtin_amdgcn_sched_barrier(0)
; #define STAGE(P, base, kt) do { _Pragma("unroll") for (int _i = 0; _i < 2; ++_i)                                        \
;       __builtin_amdgcn_global_load_lds((const unsigned*)((base) + (size_t)(sOff[_i] + (unsigned)(kt) * (BK * 2))),        \
;                                        (unsigned*)((P) + wid * 1024 + _i * 8192), 16, 0, 0); } while (0)
; #define LDA(dst, b, h) _Pragma("unroll") for (int m = 0; m < 4; ++m) _Pragma("unroll") for (int k = 0; k < 2; ++k) \
;       dst[m][k] = *(const bf16x8*)(SA(b, h) + aoff + (m * 2048 + k * 1024))
; #define LDB(dst, b, h) _Pragma("unroll") for (int n = 0; n < 2; ++n) _Pragma("unroll") for (int k = 0; k < 2; ++k) \
;       dst[n][k] = *(const bf16x8*)(SB(b, h) + boff + (n * 256 + k * 1024))
; #define BAR __builtin_amdgcn_s_barrier()
; template <int EPI, int N, int K>
; __device__ __forceinline__ void phase_gemm(const Params& p, const u16* __restrict__ A, const u16* __restrict__ Bt, int nM, char* shm,
;                            u16* __restrict__ outp, float* __restrict__ rowss) {
;     ...
;       LDB(B0, 0, 0); SBAR(); LDA(At, 0, 0); STAGE(SA(1, 1), A1, t + 1);
;       WAIT_L(8); BAR; WAIT_L(0); MMA(0, 0, At, B0); BAR; SBAR();
;       LDB(B1, 0, 1); STAGE(SB(0, 0), B0p, t + 2);
;       BAR; WAIT_L(0); MMA(0, 1, At, B1); BAR;
;       LDA(At, 0, 1); STAGE(SA(0, 0), A0, t + 2);
;       BAR; WAIT_L(0); MMA(1, 0, At, B0); BAR; SBAR();
;       STAGE(SB(0, 1), B1p, t + 2);
;       WAIT_V(6); BAR; MMA(1, 1, At, B1); BAR;
.LBB0_198:
	v_or_b32_e32 v143, 0x10000, v147
	v_add_u32_e32 v145, 0x10100, v147
	v_add_u32_e32 v144, 0x10400, v147
	ds_read_b128 v[156:159], v143
	ds_read_b128 v[160:163], v144
	v_add_u32_e32 v151, 0x10500, v147
	ds_read_b128 v[164:167], v145
	ds_read_b128 v[168:171], v151
	v_add_u32_e32 v240, v146, v96
	s_add_i32 s61, s5, 0xc000
	v_add_u32_e32 v152, 0x80, v240
	s_mov_b32 m0, s61
	v_add_u32_e32 v241, v146, v142
	s_add_i32 s60, s5, 0xe000
	ds_read_b128 v[172:175], v148
	ds_read_b128 v[176:179], v148 offset:1024
	ds_read_b128 v[180:183], v148 offset:2048
	ds_read_b128 v[196:199], v148 offset:3072
	ds_read_b128 v[200:203], v148 offset:4096
	ds_read_b128 v[204:207], v148 offset:5120
	ds_read_b128 v[208:211], v148 offset:6144
	ds_read_b128 v[212:215], v148 offset:7168
	global_load_lds_dwordx4 v152, s[6:7]
	v_add_u32_e32 v152, 0x80, v241
	s_mov_b32 m0, s60
	s_nop 0
	global_load_lds_dwordx4 v152, s[6:7]
	v_or_b32_e32 v152, 0x14000, v147
	v_add_u32_e32 v154, 0x14100, v147
	v_add_u32_e32 v153, 0x14400, v147
	ds_read_b128 v[216:219], v152
	ds_read_b128 v[220:223], v153
	v_add_u32_e32 v155, 0x14500, v147
	ds_read_b128 v[224:227], v154
	ds_read_b128 v[228:231], v155
	s_waitcnt lgkmcnt(0)
	s_barrier
	v_mfma_f32_16x16x32_bf16 v[126:129], v[156:159], v[172:175], v[126:129]
	v_mfma_f32_16x16x32_bf16 v[122:125], v[164:167], v[172:175], v[122:125]
	v_mfma_f32_16x16x32_bf16 v[118:121], v[156:159], v[180:183], v[118:121]
	v_mfma_f32_16x16x32_bf16 v[114:117], v[164:167], v[180:183], v[114:117]
	v_mfma_f32_16x16x32_bf16 v[110:113], v[156:159], v[200:203], v[110:113]
	v_mfma_f32_16x16x32_bf16 v[106:109], v[164:167], v[200:203], v[106:109]
	v_mfma_f32_16x16x32_bf16 v[102:105], v[156:159], v[208:211], v[102:105]
	v_mfma_f32_16x16x32_bf16 v[98:101], v[164:167], v[208:211], v[98:101]
	v_mfma_f32_16x16x32_bf16 v[126:129], v[160:163], v[176:179], v[126:129]
	v_mfma_f32_16x16x32_bf16 v[122:125], v[168:171], v[176:179], v[122:125]
	v_mfma_f32_16x16x32_bf16 v[118:121], v[160:163], v[196:199], v[118:121]
	v_mfma_f32_16x16x32_bf16 v[114:117], v[168:171], v[196:199], v[114:117]
	v_mfma_f32_16x16x32_bf16 v[110:113], v[160:163], v[204:207], v[110:113]
	v_mfma_f32_16x16x32_bf16 v[106:109], v[168:171], v[204:207], v[106:109]
	v_mfma_f32_16x16x32_bf16 v[102:105], v[160:163], v[212:215], v[102:105]
	v_mfma_f32_16x16x32_bf16 v[98:101], v[168:171], v[212:215], v[98:101]
	v_mfma_f32_16x16x32_bf16 v[92:95], v[216:219], v[172:175], v[92:95]
	v_mfma_f32_16x16x32_bf16 v[88:91], v[224:227], v[172:175], v[88:91]
	v_mfma_f32_16x16x32_bf16 v[84:87], v[216:219], v[180:183], v[84:87]
	v_mfma_f32_16x16x32_bf16 v[80:83], v[224:227], v[180:183], v[80:83]
	v_mfma_f32_16x16x32_bf16 v[76:79], v[216:219], v[200:203], v[76:79]
	v_mfma_f32_16x16x32_bf16 v[72:75], v[224:227], v[200:203], v[72:75]
	v_mfma_f32_16x16x32_bf16 v[68:71], v[216:219], v[208:211], v[68:71]
	v_mfma_f32_16x16x32_bf16 v[64:67], v[224:227], v[208:211], v[64:67]
	v_mfma_f32_16x16x32_bf16 v[92:95], v[220:223], v[176:179], v[92:95]
	v_mfma_f32_16x16x32_bf16 v[88:91], v[228:231], v[176:179], v[88:91]
	v_mfma_f32_16x16x32_bf16 v[84:87], v[220:223], v[196:199], v[84:87]
	v_mfma_f32_16x16x32_bf16 v[80:83], v[228:231], v[196:199], v[80:83]
	v_mfma_f32_16x16x32_bf16 v[76:79], v[220:223], v[204:207], v[76:79]
	v_mfma_f32_16x16x32_bf16 v[72:75], v[228:231], v[204:207], v[72:75]
	v_mfma_f32_16x16x32_bf16 v[68:71], v[220:223], v[212:215], v[68:71]
	v_mfma_f32_16x16x32_bf16 v[64:67], v[228:231], v[212:215], v[64:67]
	s_barrier
	ds_read_b128 v[172:175], v148 offset:16384
	ds_read_b128 v[176:179], v148 offset:17408
	ds_read_b128 v[180:183], v148 offset:18432
	ds_read_b128 v[196:199], v148 offset:19456
	ds_read_b128 v[200:203], v148 offset:20480
	ds_read_b128 v[204:207], v148 offset:21504
	ds_read_b128 v[208:211], v148 offset:22528
	ds_read_b128 v[212:215], v148 offset:23552
	s_mov_b32 m0, s26
	v_add_u32_e32 v232, 0x100, v240
	global_load_lds_dwordx4 v232, s[12:13]
	v_add_u32_e32 v233, 0x100, v241
	s_mov_b32 m0, s27
	s_nop 0
	global_load_lds_dwordx4 v233, s[12:13]
	s_mov_b32 m0, s5
	s_nop 0
	global_load_lds_dwordx4 v232, s[14:15]
	s_mov_b32 m0, s24
	s_nop 0
	global_load_lds_dwordx4 v233, s[14:15]
	s_mov_b32 m0, s28
	s_nop 0
	global_load_lds_dwordx4 v232, s[22:23]
	s_mov_b32 m0, s29
	s_nop 0
	global_load_lds_dwordx4 v233, s[22:23]
	s_waitcnt vmcnt(6)
	s_waitcnt lgkmcnt(0)
	s_barrier
	v_mfma_f32_16x16x32_bf16 v[60:63], v[156:159], v[172:175], v[60:63]
	v_mfma_f32_16x16x32_bf16 v[56:59], v[164:167], v[172:175], v[56:59]
	v_mfma_f32_16x16x32_bf16 v[52:55], v[156:159], v[180:183], v[52:55]
	v_mfma_f32_16x16x32_bf16 v[48:51], v[164:167], v[180:183], v[48:51]
	v_mfma_f32_16x16x32_bf16 v[44:47], v[156:159], v[200:203], v[44:47]
	v_mfma_f32_16x16x32_bf16 v[40:43], v[164:167], v[200:203], v[40:43]
	v_mfma_f32_16x16x32_bf16 v[36:39], v[156:159], v[208:211], v[36:39]
	v_mfma_f32_16x16x32_bf16 v[32:35], v[164:167], v[208:211], v[32:35]
	v_mfma_f32_16x16x32_bf16 v[60:63], v[160:163], v[176:179], v[60:63]
	v_mfma_f32_16x16x32_bf16 v[56:59], v[168:171], v[176:179], v[56:59]
	v_mfma_f32_16x16x32_bf16 v[52:55], v[160:163], v[196:199], v[52:55]
	v_mfma_f32_16x16x32_bf16 v[48:51], v[168:171], v[196:199], v[48:51]
	v_mfma_f32_16x16x32_bf16 v[44:47], v[160:163], v[204:207], v[44:47]
	v_mfma_f32_16x16x32_bf16 v[40:43], v[168:171], v[204:207], v[40:43]
	v_mfma_f32_16x16x32_bf16 v[36:39], v[160:163], v[212:215], v[36:39]
	v_mfma_f32_16x16x32_bf16 v[32:35], v[168:171], v[212:215], v[32:35]
	v_mfma_f32_16x16x32_bf16 v[28:31], v[216:219], v[172:175], v[28:31]
	v_mfma_f32_16x16x32_bf16 v[24:27], v[224:227], v[172:175], v[24:27]
	v_mfma_f32_16x16x32_bf16 v[20:23], v[216:219], v[180:183], v[20:23]
	v_mfma_f32_16x16x32_bf16 v[16:19], v[224:227], v[180:183], v[16:19]
	v_mfma_f32_16x16x32_bf16 v[12:15], v[216:219], v[200:203], v[12:15]
	v_mfma_f32_16x16x32_bf16 v[8:11], v[224:227], v[200:203], v[8:11]
	v_mfma_f32_16x16x32_bf16 v[4:7], v[216:219], v[208:211], v[4:7]
	v_mfma_f32_16x16x32_bf16 v[0:3], v[224:227], v[208:211], v[0:3]
	v_mfma_f32_16x16x32_bf16 v[28:31], v[220:223], v[176:179], v[28:31]
	v_mfma_f32_16x16x32_bf16 v[24:27], v[228:231], v[176:179], v[24:27]
	v_mfma_f32_16x16x32_bf16 v[20:23], v[220:223], v[196:199], v[20:23]
	v_mfma_f32_16x16x32_bf16 v[16:19], v[228:231], v[196:199], v[16:19]
	v_mfma_f32_16x16x32_bf16 v[12:15], v[220:223], v[204:207], v[12:15]
	v_mfma_f32_16x16x32_bf16 v[8:11], v[228:231], v[204:207], v[8:11]
	v_mfma_f32_16x16x32_bf16 v[4:7], v[220:223], v[212:215], v[4:7]
	v_mfma_f32_16x16x32_bf16 v[0:3], v[228:231], v[212:215], v[0:3]
	v_or_b32_e32 v156, 0x18000, v147
	v_add_u32_e32 v158, 0x18100, v147
	s_barrier
; #define WAIT_V(n) asm volatile("s_waitcnt vmcnt(%0)" ::"n"(n) : "memory")
; #define WAIT_L(n) asm volatile("s_waitcnt lgkmcnt(%0)" ::"n"(n) : "memory")
; #define SBAR() __builtin_amdgcn_sched_barrier(0)
; #define STAGE(P, base, kt) do { _Pragma("unroll") for (int _i = 0; _i < 2; ++_i)                                        \
;       __builtin_amdgcn_global_load_lds((const unsigned*)((base) + (size_t)(sOff[_i] + (unsigned)(kt) * (BK * 2))),        \
;                                        (unsigned*)((P) + wid * 1024 + _i * 8192), 16, 0, 0); } while (0)
; #define LDA(dst, b, h) _Pragma("unroll") for (int m = 0; m < 4; ++m) _Pragma("unroll") for (int k = 0; k < 2; ++k) \
;       dst[m][k] = *(const bf16x8*)(SA(b, h) + aoff + (m * 2048 + k * 1024))
; #define LDB(dst, b, h) _Pragma("unroll") for (int n = 0; n < 2; ++n) _Pragma("unroll") for (int k = 0; k < 2; ++k) \
;       dst[n][k] = *(const bf16x8*)(SB(b, h) + boff + (n * 256 + k * 1024))
; #define BAR __builtin_amdgcn_s_barrier()
; template <int EPI, int N, int K>
; __device__ __forceinline__ void phase_gemm(const Params& p, const u16* __restrict__ A, const u16* __restrict__ Bt, int nM, char* shm,
;                            u16* __restrict__ outp, float* __restrict__ rowss) {
;     ...
;       LDB(B0, 1, 0); SBAR(); LDA(At, 1, 0); STAGE(SA(0, 1), A1, t + 2);
;       WAIT_L(8); BAR; WAIT_L(0); MMA(0, 0, At, B0); BAR; SBAR();
;       LDB(B1, 1, 1); STAGE(SB(1, 0), B0p, t + 3);
;       BAR; WAIT_L(0); MMA(0, 1, At, B1); BAR;
;       LDA(At, 1, 1); STAGE(SA(1, 0), A0, t + 3);
;       BAR; WAIT_L(0); MMA(1, 0, At, B0); BAR; SBAR();
;       STAGE(SB(1, 1), B1p, t + 3);
;       WAIT_V(6); BAR; MMA(1, 1, At, B1); BAR;
	v_add_u32_e32 v157, 0x18400, v147
	ds_read_b128 v[164:167], v156
	ds_read_b128 v[168:171], v157
	v_add_u32_e32 v159, 0x18500, v147
	ds_read_b128 v[172:175], v158
	ds_read_b128 v[176:179], v159
	s_mov_b32 m0, s30
	ds_read_b128 v[180:183], v148 offset:32768
	ds_read_b128 v[196:199], v148 offset:33792
	ds_read_b128 v[200:203], v148 offset:34816
	ds_read_b128 v[204:207], v148 offset:35840
	ds_read_b128 v[208:211], v148 offset:36864
	ds_read_b128 v[212:215], v148 offset:37888
	ds_read_b128 v[216:219], v148 offset:38912
	ds_read_b128 v[220:223], v148 offset:39936
	global_load_lds_dwordx4 v232, s[6:7]
	s_mov_b32 m0, s31
	s_nop 0
	global_load_lds_dwordx4 v233, s[6:7]
	v_or_b32_e32 v160, 0x1c000, v147
	v_add_u32_e32 v162, 0x1c100, v147
	v_add_u32_e32 v161, 0x1c400, v147
	ds_read_b128 v[224:227], v160
	ds_read_b128 v[228:231], v161
	v_add_u32_e32 v163, 0x1c500, v147
	ds_read_b128 v[232:235], v162
	ds_read_b128 v[236:239], v163
	s_waitcnt lgkmcnt(0)
	s_barrier
	v_mfma_f32_16x16x32_bf16 v[126:129], v[164:167], v[180:183], v[126:129]
	v_mfma_f32_16x16x32_bf16 v[122:125], v[172:175], v[180:183], v[122:125]
	v_mfma_f32_16x16x32_bf16 v[118:121], v[164:167], v[200:203], v[118:121]
	v_mfma_f32_16x16x32_bf16 v[114:117], v[172:175], v[200:203], v[114:117]
	v_mfma_f32_16x16x32_bf16 v[110:113], v[164:167], v[208:211], v[110:113]
	v_mfma_f32_16x16x32_bf16 v[106:109], v[172:175], v[208:211], v[106:109]
	v_mfma_f32_16x16x32_bf16 v[102:105], v[164:167], v[216:219], v[102:105]
	v_mfma_f32_16x16x32_bf16 v[98:101], v[172:175], v[216:219], v[98:101]
	v_mfma_f32_16x16x32_bf16 v[126:129], v[168:171], v[196:199], v[126:129]
	v_mfma_f32_16x16x32_bf16 v[122:125], v[176:179], v[196:199], v[122:125]
	v_mfma_f32_16x16x32_bf16 v[118:121], v[168:171], v[204:207], v[118:121]
	v_mfma_f32_16x16x32_bf16 v[114:117], v[176:179], v[204:207], v[114:117]
	v_mfma_f32_16x16x32_bf16 v[110:113], v[168:171], v[212:215], v[110:113]
	v_mfma_f32_16x16x32_bf16 v[106:109], v[176:179], v[212:215], v[106:109]
	v_mfma_f32_16x16x32_bf16 v[102:105], v[168:171], v[220:223], v[102:105]
	v_mfma_f32_16x16x32_bf16 v[98:101], v[176:179], v[220:223], v[98:101]
	v_mfma_f32_16x16x32_bf16 v[92:95], v[224:227], v[180:183], v[92:95]
	v_mfma_f32_16x16x32_bf16 v[88:91], v[232:235], v[180:183], v[88:91]
	v_mfma_f32_16x16x32_bf16 v[84:87], v[224:227], v[200:203], v[84:87]
	v_mfma_f32_16x16x32_bf16 v[80:83], v[232:235], v[200:203], v[80:83]
	v_mfma_f32_16x16x32_bf16 v[76:79], v[224:227], v[208:211], v[76:79]
	v_mfma_f32_16x16x32_bf16 v[72:75], v[232:235], v[208:211], v[72:75]
	v_mfma_f32_16x16x32_bf16 v[68:71], v[224:227], v[216:219], v[68:71]
	v_mfma_f32_16x16x32_bf16 v[64:67], v[232:235], v[216:219], v[64:67]
	v_mfma_f32_16x16x32_bf16 v[92:95], v[228:231], v[196:199], v[92:95]
	v_mfma_f32_16x16x32_bf16 v[88:91], v[236:239], v[196:199], v[88:91]
	v_mfma_f32_16x16x32_bf16 v[84:87], v[228:231], v[204:207], v[84:87]
	v_mfma_f32_16x16x32_bf16 v[80:83], v[236:239], v[204:207], v[80:83]
	v_mfma_f32_16x16x32_bf16 v[76:79], v[228:231], v[212:215], v[76:79]
	v_mfma_f32_16x16x32_bf16 v[72:75], v[236:239], v[212:215], v[72:75]
	v_mfma_f32_16x16x32_bf16 v[68:71], v[228:231], v[220:223], v[68:71]
	v_mfma_f32_16x16x32_bf16 v[64:67], v[236:239], v[220:223], v[64:67]
	s_barrier
	ds_read_b128 v[180:183], v148 offset:49152
	ds_read_b128 v[196:199], v148 offset:50176
	ds_read_b128 v[200:203], v148 offset:51200
	ds_read_b128 v[204:207], v148 offset:52224
	ds_read_b128 v[208:211], v148 offset:53248
	ds_read_b128 v[212:215], v148 offset:54272
	ds_read_b128 v[216:219], v148 offset:55296
	ds_read_b128 v[220:223], v148 offset:56320
	s_mov_b32 m0, s33
	v_add_u32_e32 v240, 0x180, v240
	global_load_lds_dwordx4 v240, s[12:13]
	v_add_u32_e32 v241, 0x180, v241
	s_mov_b32 m0, s35
	s_nop 0
	global_load_lds_dwordx4 v241, s[12:13]
	s_mov_b32 m0, s92
	s_nop 0
	global_load_lds_dwordx4 v240, s[14:15]
	s_mov_b32 m0, s93
	s_nop 0
	global_load_lds_dwordx4 v241, s[14:15]
	s_mov_b32 m0, s52
	s_nop 0
	global_load_lds_dwordx4 v240, s[22:23]
	s_mov_b32 m0, s53
	s_nop 0
	global_load_lds_dwordx4 v241, s[22:23]
	s_waitcnt vmcnt(6)
	s_waitcnt lgkmcnt(0)
	s_barrier
	v_mfma_f32_16x16x32_bf16 v[60:63], v[164:167], v[180:183], v[60:63]
	v_mfma_f32_16x16x32_bf16 v[56:59], v[172:175], v[180:183], v[56:59]
	v_mfma_f32_16x16x32_bf16 v[52:55], v[164:167], v[200:203], v[52:55]
	v_mfma_f32_16x16x32_bf16 v[48:51], v[172:175], v[200:203], v[48:51]
	v_mfma_f32_16x16x32_bf16 v[44:47], v[164:167], v[208:211], v[44:47]
	v_mfma_f32_16x16x32_bf16 v[40:43], v[172:175], v[208:211], v[40:43]
	v_mfma_f32_16x16x32_bf16 v[36:39], v[164:167], v[216:219], v[36:39]
	v_mfma_f32_16x16x32_bf16 v[32:35], v[172:175], v[216:219], v[32:35]
	v_mfma_f32_16x16x32_bf16 v[60:63], v[168:171], v[196:199], v[60:63]
	v_mfma_f32_16x16x32_bf16 v[56:59], v[176:179], v[196:199], v[56:59]
	v_mfma_f32_16x16x32_bf16 v[52:55], v[168:171], v[204:207], v[52:55]
	v_mfma_f32_16x16x32_bf16 v[48:51], v[176:179], v[204:207], v[48:51]
	v_mfma_f32_16x16x32_bf16 v[44:47], v[168:171], v[212:215], v[44:47]
	v_mfma_f32_16x16x32_bf16 v[40:43], v[176:179], v[212:215], v[40:43]
	v_mfma_f32_16x16x32_bf16 v[36:39], v[168:171], v[220:223], v[36:39]
	v_mfma_f32_16x16x32_bf16 v[32:35], v[176:179], v[220:223], v[32:35]
	v_mfma_f32_16x16x32_bf16 v[28:31], v[224:227], v[180:183], v[28:31]
	v_mfma_f32_16x16x32_bf16 v[24:27], v[232:235], v[180:183], v[24:27]
	v_mfma_f32_16x16x32_bf16 v[20:23], v[224:227], v[200:203], v[20:23]
	v_mfma_f32_16x16x32_bf16 v[16:19], v[232:235], v[200:203], v[16:19]
	v_mfma_f32_16x16x32_bf16 v[12:15], v[224:227], v[208:211], v[12:15]
	v_mfma_f32_16x16x32_bf16 v[8:11], v[232:235], v[208:211], v[8:11]
	v_mfma_f32_16x16x32_bf16 v[4:7], v[224:227], v[216:219], v[4:7]
	v_mfma_f32_16x16x32_bf16 v[0:3], v[232:235], v[216:219], v[0:3]
	v_mfma_f32_16x16x32_bf16 v[28:31], v[228:231], v[196:199], v[28:31]
	v_mfma_f32_16x16x32_bf16 v[24:27], v[236:239], v[196:199], v[24:27]
	v_mfma_f32_16x16x32_bf16 v[20:23], v[228:231], v[204:207], v[20:23]
	v_mfma_f32_16x16x32_bf16 v[16:19], v[236:239], v[204:207], v[16:19]
	v_mfma_f32_16x16x32_bf16 v[12:15], v[228:231], v[212:215], v[12:15]
	v_mfma_f32_16x16x32_bf16 v[8:11], v[236:239], v[212:215], v[8:11]
	v_mfma_f32_16x16x32_bf16 v[4:7], v[228:231], v[220:223], v[4:7]
	v_mfma_f32_16x16x32_bf16 v[0:3], v[236:239], v[220:223], v[0:3]
	s_add_i32 s59, s59, 2
	v_add_u32_e32 v142, 0x100, v142
	s_cmp_lt_u32 s59, 12
	v_add_u32_e32 v96, 0x100, v96
	s_barrier
; #define WAIT_V(n) asm volatile("s_waitcnt vmcnt(%0)" ::"n"(n) : "memory")
; #define WAIT_L(n) asm volatile("s_waitcnt lgkmcnt(%0)" ::"n"(n) : "memory")
; #define STAGE(P, base, kt) do { _Pragma("unroll") for (int _i = 0; _i < 2; ++_i)                                        \
;       __builtin_amdgcn_global_load_lds((const unsigned*)((base) + (size_t)(sOff[_i] + (unsigned)(kt) * (BK * 2))),        \
;                                        (unsigned*)((P) + wid * 1024 + _i * 8192), 16, 0, 0); } while (0)
; #define LDA(dst, b, h) _Pragma("unroll") for (int m = 0; m < 4; ++m) _Pragma("unroll") for (int k = 0; k < 2; ++k) \
;       dst[m][k] = *(const bf16x8*)(SA(b, h) + aoff + (m * 2048 + k * 1024))
; #define LDB(dst, b, h) _Pragma("unroll") for (int n = 0; n < 2; ++n) _Pragma("unroll") for (int k = 0; k < 2; ++k) \
;       dst[n][k] = *(const bf16x8*)(SB(b, h) + boff + (n * 256 + k * 1024))
; #define BAR __builtin_amdgcn_s_barrier()
; template <int EPI, int N, int K>
; __device__ __forceinline__ void phase_gemm(const Params& p, const u16* __restrict__ A, const u16* __restrict__ Bt, int nM, char* shm,
;                            u16* __restrict__ outp, float* __restrict__ rowss) {
;     ...
;     { LDB(B0, 0, 0); LDA(At, 0, 0); STAGE(SA(1, 1), A1, nt - 1);
;       BAR; WAIT_L(0); MMA(0, 0, At, B0); BAR;
;       LDB(B1, 0, 1); BAR; WAIT_L(0); MMA(0, 1, At, B1); BAR;
;       LDA(At, 0, 1); WAIT_V(4); BAR; WAIT_L(0); MMA(1, 0, At, B0); MMA(1, 1, At, B1); BAR; }
;     { LDB(B0, 1, 0); LDA(At, 1, 0); WAIT_V(2); BAR; WAIT_L(0); MMA(0, 0, At, B0); BAR;
;       LDB(B1, 1, 1); WAIT_V(0); BAR; WAIT_L(0); MMA(0, 1, At, B1); BAR;
;       LDA(At, 1, 1); BAR; WAIT_L(0); MMA(1, 0, At, B0); MMA(1, 1, At, B1); BAR; }
	s_cbranch_scc1 .LBB0_198
	s_mov_b32 m0, s61
	v_lshl_add_u64 v[220:221], s[6:7], 0, v[138:139]
	ds_read_b128 v[164:167], v143
	ds_read_b128 v[168:171], v144
	ds_read_b128 v[142:145], v145
	ds_read_b128 v[172:175], v151
	ds_read_b128 v[176:179], v148
	ds_read_b128 v[180:183], v148 offset:1024
	ds_read_b128 v[196:199], v148 offset:2048
	ds_read_b128 v[200:203], v148 offset:3072
	ds_read_b128 v[204:207], v148 offset:4096
	ds_read_b128 v[208:211], v148 offset:5120
	ds_read_b128 v[212:215], v148 offset:6144
	ds_read_b128 v[216:219], v148 offset:7168
	global_load_lds_dwordx4 v[220:221], off
	v_lshl_add_u64 v[220:221], s[6:7], 0, v[140:141]
	s_mov_b32 m0, s60
	s_nop 0
	global_load_lds_dwordx4 v[220:221], off
	s_barrier
	s_waitcnt lgkmcnt(0)
	s_waitcnt lgkmcnt(0)
	v_mfma_f32_16x16x32_bf16 v[126:129], v[164:167], v[176:179], v[126:129]
	v_mfma_f32_16x16x32_bf16 v[122:125], v[142:145], v[176:179], v[122:125]
	v_mfma_f32_16x16x32_bf16 v[118:121], v[164:167], v[196:199], v[118:121]
	v_mfma_f32_16x16x32_bf16 v[102:105], v[164:167], v[212:215], v[102:105]
	v_mfma_f32_16x16x32_bf16 v[98:101], v[142:145], v[212:215], v[98:101]
	v_mfma_f32_16x16x32_bf16 v[126:129], v[168:171], v[180:183], v[126:129]
	v_mfma_f32_16x16x32_bf16 v[122:125], v[172:175], v[180:183], v[122:125]
	v_mfma_f32_16x16x32_bf16 v[118:121], v[168:171], v[200:203], v[118:121]
	v_mfma_f32_16x16x32_bf16 v[114:117], v[142:145], v[196:199], v[114:117]
	v_mfma_f32_16x16x32_bf16 v[110:113], v[164:167], v[204:207], v[110:113]
	v_mfma_f32_16x16x32_bf16 v[106:109], v[142:145], v[204:207], v[106:109]
	v_mfma_f32_16x16x32_bf16 v[102:105], v[168:171], v[216:219], v[102:105]
	v_mfma_f32_16x16x32_bf16 v[98:101], v[172:175], v[216:219], v[98:101]
	v_mfma_f32_16x16x32_bf16 v[220:223], v[172:175], v[200:203], v[114:117]
	v_mfma_f32_16x16x32_bf16 v[224:227], v[168:171], v[208:211], v[110:113]
	v_mfma_f32_16x16x32_bf16 v[228:231], v[172:175], v[208:211], v[106:109]
	s_barrier
	s_nop 0
	ds_read_b128 v[106:109], v152
	ds_read_b128 v[110:113], v153
	ds_read_b128 v[114:117], v154
	ds_read_b128 v[152:155], v155
	s_barrier
	s_waitcnt lgkmcnt(0)
	s_waitcnt lgkmcnt(0)
	v_mfma_f32_16x16x32_bf16 v[84:87], v[106:109], v[196:199], v[84:87]
	v_mfma_f32_16x16x32_bf16 v[80:83], v[114:117], v[196:199], v[80:83]
	v_mfma_f32_16x16x32_bf16 v[68:71], v[106:109], v[212:215], v[68:71]
	v_mfma_f32_16x16x32_bf16 v[92:95], v[106:109], v[176:179], v[92:95]
	v_mfma_f32_16x16x32_bf16 v[88:91], v[114:117], v[176:179], v[88:91]
	v_mfma_f32_16x16x32_bf16 v[84:87], v[110:113], v[200:203], v[84:87]
	v_mfma_f32_16x16x32_bf16 v[80:83], v[152:155], v[200:203], v[80:83]
	v_mfma_f32_16x16x32_bf16 v[76:79], v[106:109], v[204:207], v[76:79]
	v_mfma_f32_16x16x32_bf16 v[72:75], v[114:117], v[204:207], v[72:75]
	v_mfma_f32_16x16x32_bf16 v[68:71], v[110:113], v[216:219], v[68:71]
	v_mfma_f32_16x16x32_bf16 v[64:67], v[114:117], v[212:215], v[64:67]
	v_mfma_f32_16x16x32_bf16 v[232:235], v[110:113], v[180:183], v[92:95]
	v_mfma_f32_16x16x32_bf16 v[176:179], v[152:155], v[180:183], v[88:91]
	v_mfma_f32_16x16x32_bf16 v[180:183], v[110:113], v[208:211], v[76:79]
	v_mfma_f32_16x16x32_bf16 v[196:199], v[152:155], v[208:211], v[72:75]
	v_mfma_f32_16x16x32_bf16 v[200:203], v[152:155], v[216:219], v[64:67]
	s_barrier
	s_nop 0
	ds_read_b128 v[64:67], v148 offset:16384
	ds_read_b128 v[72:75], v148 offset:17408
	ds_read_b128 v[76:79], v148 offset:18432
	ds_read_b128 v[88:91], v148 offset:19456
	ds_read_b128 v[92:95], v148 offset:20480
	ds_read_b128 v[204:207], v148 offset:21504
	ds_read_b128 v[208:211], v148 offset:22528
	ds_read_b128 v[212:215], v148 offset:23552
	s_waitcnt vmcnt(4)
	s_barrier
	s_waitcnt lgkmcnt(0)
	s_waitcnt lgkmcnt(0)
	v_mfma_f32_16x16x32_bf16 v[60:63], v[164:167], v[64:67], v[60:63]
	v_mfma_f32_16x16x32_bf16 v[52:55], v[164:167], v[76:79], v[52:55]
	v_mfma_f32_16x16x32_bf16 v[48:51], v[142:145], v[76:79], v[48:51]
	v_mfma_f32_16x16x32_bf16 v[36:39], v[164:167], v[208:211], v[36:39]
	v_mfma_f32_16x16x32_bf16 v[32:35], v[142:145], v[208:211], v[32:35]
	v_mfma_f32_16x16x32_bf16 v[60:63], v[168:171], v[72:75], v[60:63]
	v_mfma_f32_16x16x32_bf16 v[56:59], v[142:145], v[64:67], v[56:59]
	v_mfma_f32_16x16x32_bf16 v[52:55], v[168:171], v[88:91], v[52:55]
	v_mfma_f32_16x16x32_bf16 v[48:51], v[172:175], v[88:91], v[48:51]
	v_mfma_f32_16x16x32_bf16 v[44:47], v[164:167], v[92:95], v[44:47]
	v_mfma_f32_16x16x32_bf16 v[40:43], v[142:145], v[92:95], v[40:43]
	v_mfma_f32_16x16x32_bf16 v[36:39], v[168:171], v[212:215], v[36:39]
	v_mfma_f32_16x16x32_bf16 v[32:35], v[172:175], v[212:215], v[32:35]
	v_mfma_f32_16x16x32_bf16 v[216:219], v[172:175], v[72:75], v[56:59]
	v_mfma_f32_16x16x32_bf16 v[236:239], v[168:171], v[204:207], v[44:47]
	v_mfma_f32_16x16x32_bf16 v[240:243], v[172:175], v[204:207], v[40:43]
	v_mfma_f32_16x16x32_bf16 v[20:23], v[106:109], v[76:79], v[20:23]
	v_mfma_f32_16x16x32_bf16 v[16:19], v[114:117], v[76:79], v[16:19]
	v_mfma_f32_16x16x32_bf16 v[4:7], v[106:109], v[208:211], v[4:7]
	v_mfma_f32_16x16x32_bf16 v[28:31], v[106:109], v[64:67], v[28:31]
	v_mfma_f32_16x16x32_bf16 v[24:27], v[114:117], v[64:67], v[24:27]
	v_mfma_f32_16x16x32_bf16 v[20:23], v[110:113], v[88:91], v[20:23]
	v_mfma_f32_16x16x32_bf16 v[16:19], v[152:155], v[88:91], v[16:19]
	v_mfma_f32_16x16x32_bf16 v[12:15], v[106:109], v[92:95], v[12:15]
	v_mfma_f32_16x16x32_bf16 v[8:11], v[114:117], v[92:95], v[8:11]
	v_mfma_f32_16x16x32_bf16 v[4:7], v[110:113], v[212:215], v[4:7]
	v_mfma_f32_16x16x32_bf16 v[0:3], v[114:117], v[208:211], v[0:3]
	v_mfma_f32_16x16x32_bf16 v[142:145], v[110:113], v[72:75], v[28:31]
	v_mfma_f32_16x16x32_bf16 v[164:167], v[152:155], v[72:75], v[24:27]
	v_mfma_f32_16x16x32_bf16 v[168:171], v[110:113], v[204:207], v[12:15]
	v_mfma_f32_16x16x32_bf16 v[172:175], v[152:155], v[204:207], v[8:11]
	v_mfma_f32_16x16x32_bf16 v[152:155], v[152:155], v[212:215], v[0:3]
	s_barrier
; #define WAIT_V(n) asm volatile("s_waitcnt vmcnt(%0)" ::"n"(n) : "memory")
; #define WAIT_L(n) asm volatile("s_waitcnt lgkmcnt(%0)" ::"n"(n) : "memory")
; #define LDA(dst, b, h) _Pragma("unroll") for (int m = 0; m < 4; ++m) _Pragma("unroll") for (int k = 0; k < 2; ++k) \
;       dst[m][k] = *(const bf16x8*)(SA(b, h) + aoff + (m * 2048 + k * 1024))
; #define LDB(dst, b, h) _Pragma("unroll") for (int n = 0; n < 2; ++n) _Pragma("unroll") for (int k = 0; k < 2; ++k) \
;       dst[n][k] = *(const bf16x8*)(SB(b, h) + boff + (n * 256 + k * 1024))
; #define BAR __builtin_amdgcn_s_barrier()
; template <int EPI, int N, int K>
; __device__ __forceinline__ void phase_gemm(const Params& p, const u16* __restrict__ A, const u16* __restrict__ Bt, int nM, char* shm,
;                            u16* __restrict__ outp, float* __restrict__ rowss) {
;     ...
;     { LDB(B0, 1, 0); LDA(At, 1, 0); WAIT_V(2); BAR; WAIT_L(0); MMA(0, 0, At, B0); BAR;
;       LDB(B1, 1, 1); WAIT_V(0); BAR; WAIT_L(0); MMA(0, 1, At, B1); BAR;
;       LDA(At, 1, 1); BAR; WAIT_L(0); MMA(1, 0, At, B0); MMA(1, 1, At, B1); BAR; }
;     if (wr == 0) BAR;
	s_nop 0
	ds_read_b128 v[0:3], v156
	ds_read_b128 v[8:11], v157
	ds_read_b128 v[12:15], v158
	ds_read_b128 v[156:159], v159
	ds_read_b128 v[24:27], v148 offset:32768
	ds_read_b128 v[28:31], v148 offset:33792
	ds_read_b128 v[40:43], v148 offset:34816
	ds_read_b128 v[44:47], v148 offset:35840
	ds_read_b128 v[56:59], v148 offset:36864
	ds_read_b128 v[64:67], v148 offset:37888
	ds_read_b128 v[204:207], v148 offset:38912
	ds_read_b128 v[208:211], v148 offset:39936
	s_waitcnt vmcnt(2)
	s_barrier
	s_waitcnt lgkmcnt(0)
	s_waitcnt lgkmcnt(0)
	v_mfma_f32_16x16x32_bf16 v[72:75], v[0:3], v[24:27], v[126:129]
	v_mfma_f32_16x16x32_bf16 v[126:129], v[8:11], v[28:31], v[72:75]
	v_mfma_f32_16x16x32_bf16 v[72:75], v[12:15], v[24:27], v[122:125]
	v_mfma_f32_16x16x32_bf16 v[114:117], v[156:159], v[28:31], v[72:75]
	v_mfma_f32_16x16x32_bf16 v[72:75], v[0:3], v[40:43], v[118:121]
	v_mfma_f32_16x16x32_bf16 v[106:109], v[8:11], v[44:47], v[72:75]
	v_mfma_f32_16x16x32_bf16 v[72:75], v[12:15], v[40:43], v[220:223]
	v_mfma_f32_16x16x32_bf16 v[110:113], v[156:159], v[44:47], v[72:75]
	v_mfma_f32_16x16x32_bf16 v[72:75], v[0:3], v[56:59], v[224:227]
	v_mfma_f32_16x16x32_bf16 v[88:91], v[8:11], v[64:67], v[72:75]
	v_mfma_f32_16x16x32_bf16 v[72:75], v[12:15], v[56:59], v[228:231]
	v_mfma_f32_16x16x32_bf16 v[92:95], v[156:159], v[64:67], v[72:75]
	v_mfma_f32_16x16x32_bf16 v[72:75], v[0:3], v[204:207], v[102:105]
	v_mfma_f32_16x16x32_bf16 v[76:79], v[12:15], v[204:207], v[98:101]
	v_mfma_f32_16x16x32_bf16 v[72:75], v[8:11], v[208:211], v[72:75]
	v_mfma_f32_16x16x32_bf16 v[76:79], v[156:159], v[208:211], v[76:79]
	s_barrier
	ds_read_b128 v[212:215], v160
	ds_read_b128 v[220:223], v161
	ds_read_b128 v[224:227], v162
	ds_read_b128 v[160:163], v163
	s_waitcnt vmcnt(0)
	s_barrier
	s_waitcnt lgkmcnt(0)
	s_waitcnt lgkmcnt(0)
	v_mfma_f32_16x16x32_bf16 v[98:101], v[212:215], v[24:27], v[232:235]
	v_mfma_f32_16x16x32_bf16 v[24:27], v[224:227], v[24:27], v[176:179]
	v_mfma_f32_16x16x32_bf16 v[122:125], v[160:163], v[28:31], v[24:27]
	v_mfma_f32_16x16x32_bf16 v[24:27], v[212:215], v[40:43], v[84:87]
	v_mfma_f32_16x16x32_bf16 v[118:121], v[220:223], v[28:31], v[98:101]
	v_mfma_f32_16x16x32_bf16 v[98:101], v[220:223], v[44:47], v[24:27]
	v_mfma_f32_16x16x32_bf16 v[24:27], v[224:227], v[40:43], v[80:83]
	v_mfma_f32_16x16x32_bf16 v[102:105], v[160:163], v[44:47], v[24:27]
	v_mfma_f32_16x16x32_bf16 v[24:27], v[212:215], v[56:59], v[180:183]
	v_mfma_f32_16x16x32_bf16 v[80:83], v[220:223], v[64:67], v[24:27]
	v_mfma_f32_16x16x32_bf16 v[24:27], v[224:227], v[56:59], v[196:199]
	v_mfma_f32_16x16x32_bf16 v[84:87], v[160:163], v[64:67], v[24:27]
	v_mfma_f32_16x16x32_bf16 v[24:27], v[212:215], v[204:207], v[68:71]
	v_mfma_f32_16x16x32_bf16 v[64:67], v[220:223], v[208:211], v[24:27]
	v_mfma_f32_16x16x32_bf16 v[24:27], v[224:227], v[204:207], v[200:203]
	v_mfma_f32_16x16x32_bf16 v[68:71], v[160:163], v[208:211], v[24:27]
	s_barrier
	ds_read_b128 v[176:179], v148 offset:49152
	ds_read_b128 v[180:183], v148 offset:50176
	ds_read_b128 v[196:199], v148 offset:51200
	ds_read_b128 v[200:203], v148 offset:52224
	ds_read_b128 v[204:207], v148 offset:53248
	ds_read_b128 v[208:211], v148 offset:54272
	ds_read_b128 v[228:231], v148 offset:55296
	ds_read_b128 v[232:235], v148 offset:56320
	s_barrier
	s_waitcnt lgkmcnt(0)
	s_waitcnt lgkmcnt(0)
	v_mfma_f32_16x16x32_bf16 v[24:27], v[0:3], v[176:179], v[60:63]
	v_mfma_f32_16x16x32_bf16 v[56:59], v[8:11], v[180:183], v[24:27]
	v_mfma_f32_16x16x32_bf16 v[24:27], v[12:15], v[176:179], v[216:219]
	v_mfma_f32_16x16x32_bf16 v[60:63], v[156:159], v[180:183], v[24:27]
	v_mfma_f32_16x16x32_bf16 v[24:27], v[0:3], v[196:199], v[52:55]
	v_mfma_f32_16x16x32_bf16 v[40:43], v[8:11], v[200:203], v[24:27]
	v_mfma_f32_16x16x32_bf16 v[24:27], v[12:15], v[196:199], v[48:51]
	v_mfma_f32_16x16x32_bf16 v[44:47], v[156:159], v[200:203], v[24:27]
	v_mfma_f32_16x16x32_bf16 v[24:27], v[0:3], v[204:207], v[236:239]
	v_mfma_f32_16x16x32_bf16 v[0:3], v[0:3], v[228:231], v[36:39]
	v_mfma_f32_16x16x32_bf16 v[24:27], v[8:11], v[208:211], v[24:27]
	v_mfma_f32_16x16x32_bf16 v[28:31], v[12:15], v[204:207], v[240:243]
	v_mfma_f32_16x16x32_bf16 v[8:11], v[8:11], v[232:235], v[0:3]
	v_mfma_f32_16x16x32_bf16 v[0:3], v[12:15], v[228:231], v[32:35]
	v_mfma_f32_16x16x32_bf16 v[28:31], v[156:159], v[208:211], v[28:31]
	v_mfma_f32_16x16x32_bf16 v[12:15], v[156:159], v[232:235], v[0:3]
	v_mfma_f32_16x16x32_bf16 v[0:3], v[212:215], v[176:179], v[142:145]
	v_mfma_f32_16x16x32_bf16 v[48:51], v[220:223], v[180:183], v[0:3]
	v_mfma_f32_16x16x32_bf16 v[0:3], v[224:227], v[176:179], v[164:167]
	v_mfma_f32_16x16x32_bf16 v[52:55], v[160:163], v[180:183], v[0:3]
	v_mfma_f32_16x16x32_bf16 v[0:3], v[212:215], v[196:199], v[20:23]
	v_mfma_f32_16x16x32_bf16 v[32:35], v[220:223], v[200:203], v[0:3]
	v_mfma_f32_16x16x32_bf16 v[0:3], v[224:227], v[196:199], v[16:19]
	v_mfma_f32_16x16x32_bf16 v[36:39], v[160:163], v[200:203], v[0:3]
	v_mfma_f32_16x16x32_bf16 v[0:3], v[212:215], v[204:207], v[168:171]
	v_mfma_f32_16x16x32_bf16 v[16:19], v[220:223], v[208:211], v[0:3]
	v_mfma_f32_16x16x32_bf16 v[0:3], v[224:227], v[204:207], v[172:175]
	v_mfma_f32_16x16x32_bf16 v[20:23], v[160:163], v[208:211], v[0:3]
	v_mfma_f32_16x16x32_bf16 v[0:3], v[212:215], v[228:231], v[4:7]
	v_mfma_f32_16x16x32_bf16 v[4:7], v[224:227], v[228:231], v[152:155]
	v_mfma_f32_16x16x32_bf16 v[0:3], v[220:223], v[232:235], v[0:3]
	v_mfma_f32_16x16x32_bf16 v[4:7], v[160:163], v[232:235], v[4:7]
	s_andn2_b64 vcc, exec, s[18:19]
	s_barrier
	s_cbranch_vccnz .LBB0_201
	s_barrier

; #define WAIT_V(n) asm volatile("s_waitcnt vmcnt(%0)" ::"n"(n) : "memory")
; #define WAIT_L(n) asm volatile("s_waitcnt lgkmcnt(%0)" ::"n"(n) : "memory")
; #define SBAR() __builtin_amdgcn_sched_barrier(0)
; #define STAGE(P, base, kt) do { _Pragma("unroll") for (int _i = 0; _i < 2; ++_i)                                        \
;       __builtin_amdgcn_global_load_lds((const unsigned*)((base) + (size_t)(sOff[_i] + (unsigned)(kt) * (BK * 2))),        \
;                                        (unsigned*)((P) + wid * 1024 + _i * 8192), 16, 0, 0); } while (0)
; #define LDA(dst, b, h) _Pragma("unroll") for (int m = 0; m < 4; ++m) _Pragma("unroll") for (int k = 0; k < 2; ++k) \
;       dst[m][k] = *(const bf16x8*)(SA(b, h) + aoff + (m * 2048 + k * 1024))
; #define LDB(dst, b, h) _Pragma("unroll") for (int n = 0; n < 2; ++n) _Pragma("unroll") for (int k = 0; k < 2; ++k) \
;       dst[n][k] = *(const bf16x8*)(SB(b, h) + boff + (n * 256 + k * 1024))
; #define BAR __builtin_amdgcn_s_barrier()
; template <int EPI, int N, int K>
; __device__ __forceinline__ void phase_gemm(const Params& p, const u16* __restrict__ A, const u16* __restrict__ Bt, int nM, char* shm,
;                            u16* __restrict__ outp, float* __restrict__ rowss) {
;     ...
;       LDB(B0, 0, 0); SBAR(); LDA(At, 0, 0); STAGE(SA(1, 1), A1, t + 1);
;       WAIT_L(8); BAR; WAIT_L(0); MMA(0, 0, At, B0); BAR; SBAR();
;       LDB(B1, 0, 1); STAGE(SB(0, 0), B0p, t + 2);
;       BAR; WAIT_L(0); MMA(0, 1, At, B1); BAR;
;       LDA(At, 0, 1); STAGE(SA(0, 0), A0, t + 2);
;       BAR; WAIT_L(0); MMA(1, 0, At, B0); BAR; SBAR();
;       STAGE(SB(0, 1), B1p, t + 2);
;       WAIT_V(6); BAR; MMA(1, 1, At, B1); BAR;
.LBB0_379:
	v_or_b32_e32 v131, 0x10000, v150
	v_add_u32_e32 v133, 0x10100, v150
	v_add_u32_e32 v132, 0x10400, v150
	ds_read_b128 v[156:159], v131
	ds_read_b128 v[160:163], v132
	v_add_u32_e32 v146, 0x10500, v150
	ds_read_b128 v[164:167], v133
	ds_read_b128 v[168:171], v146
	v_add_u32_e32 v240, v147, v96
	s_add_i32 s26, s94, 0xc000
	v_add_u32_e32 v148, 0x80, v240
	s_mov_b32 m0, s26
	v_add_u32_e32 v241, v147, v130
	s_add_i32 s25, s94, 0xe000
	ds_read_b128 v[172:175], v151
	ds_read_b128 v[176:179], v151 offset:1024
	ds_read_b128 v[180:183], v151 offset:2048
	ds_read_b128 v[196:199], v151 offset:3072
	ds_read_b128 v[200:203], v151 offset:4096
	ds_read_b128 v[204:207], v151 offset:5120
	ds_read_b128 v[208:211], v151 offset:6144
	ds_read_b128 v[212:215], v151 offset:7168
	global_load_lds_dwordx4 v148, s[6:7]
	v_add_u32_e32 v148, 0x80, v241
	s_mov_b32 m0, s25
	s_nop 0
	global_load_lds_dwordx4 v148, s[6:7]
	v_or_b32_e32 v148, 0x14000, v150
	v_add_u32_e32 v154, 0x14100, v150
	v_add_u32_e32 v149, 0x14400, v150
	ds_read_b128 v[216:219], v148
	ds_read_b128 v[220:223], v149
	v_add_u32_e32 v155, 0x14500, v150
	ds_read_b128 v[224:227], v154
	ds_read_b128 v[228:231], v155
	s_waitcnt lgkmcnt(0)
	s_barrier
	v_mfma_f32_16x16x32_bf16 v[126:129], v[156:159], v[172:175], v[126:129]
	v_mfma_f32_16x16x32_bf16 v[122:125], v[164:167], v[172:175], v[122:125]
	v_mfma_f32_16x16x32_bf16 v[118:121], v[156:159], v[180:183], v[118:121]
	v_mfma_f32_16x16x32_bf16 v[114:117], v[164:167], v[180:183], v[114:117]
	v_mfma_f32_16x16x32_bf16 v[110:113], v[156:159], v[200:203], v[110:113]
	v_mfma_f32_16x16x32_bf16 v[106:109], v[164:167], v[200:203], v[106:109]
	v_mfma_f32_16x16x32_bf16 v[102:105], v[156:159], v[208:211], v[102:105]
	v_mfma_f32_16x16x32_bf16 v[98:101], v[164:167], v[208:211], v[98:101]
	v_mfma_f32_16x16x32_bf16 v[126:129], v[160:163], v[176:179], v[126:129]
	v_mfma_f32_16x16x32_bf16 v[122:125], v[168:171], v[176:179], v[122:125]
	v_mfma_f32_16x16x32_bf16 v[118:121], v[160:163], v[196:199], v[118:121]
	v_mfma_f32_16x16x32_bf16 v[114:117], v[168:171], v[196:199], v[114:117]
	v_mfma_f32_16x16x32_bf16 v[110:113], v[160:163], v[204:207], v[110:113]
	v_mfma_f32_16x16x32_bf16 v[106:109], v[168:171], v[204:207], v[106:109]
	v_mfma_f32_16x16x32_bf16 v[102:105], v[160:163], v[212:215], v[102:105]
	v_mfma_f32_16x16x32_bf16 v[98:101], v[168:171], v[212:215], v[98:101]
	v_mfma_f32_16x16x32_bf16 v[92:95], v[216:219], v[172:175], v[92:95]
	v_mfma_f32_16x16x32_bf16 v[88:91], v[224:227], v[172:175], v[88:91]
	v_mfma_f32_16x16x32_bf16 v[84:87], v[216:219], v[180:183], v[84:87]
	v_mfma_f32_16x16x32_bf16 v[80:83], v[224:227], v[180:183], v[80:83]
	v_mfma_f32_16x16x32_bf16 v[76:79], v[216:219], v[200:203], v[76:79]
	v_mfma_f32_16x16x32_bf16 v[72:75], v[224:227], v[200:203], v[72:75]
	v_mfma_f32_16x16x32_bf16 v[68:71], v[216:219], v[208:211], v[68:71]
	v_mfma_f32_16x16x32_bf16 v[64:67], v[224:227], v[208:211], v[64:67]
	v_mfma_f32_16x16x32_bf16 v[92:95], v[220:223], v[176:179], v[92:95]
	v_mfma_f32_16x16x32_bf16 v[88:91], v[228:231], v[176:179], v[88:91]
	v_mfma_f32_16x16x32_bf16 v[84:87], v[220:223], v[196:199], v[84:87]
	v_mfma_f32_16x16x32_bf16 v[80:83], v[228:231], v[196:199], v[80:83]
	v_mfma_f32_16x16x32_bf16 v[76:79], v[220:223], v[204:207], v[76:79]
	v_mfma_f32_16x16x32_bf16 v[72:75], v[228:231], v[204:207], v[72:75]
	v_mfma_f32_16x16x32_bf16 v[68:71], v[220:223], v[212:215], v[68:71]
	v_mfma_f32_16x16x32_bf16 v[64:67], v[228:231], v[212:215], v[64:67]
	s_barrier
	ds_read_b128 v[172:175], v151 offset:16384
	ds_read_b128 v[176:179], v151 offset:17408
	ds_read_b128 v[180:183], v151 offset:18432
	ds_read_b128 v[196:199], v151 offset:19456
	ds_read_b128 v[200:203], v151 offset:20480
	ds_read_b128 v[204:207], v151 offset:21504
	ds_read_b128 v[208:211], v151 offset:22528
	ds_read_b128 v[212:215], v151 offset:23552
	s_mov_b32 m0, s22
	v_add_u32_e32 v232, 0x100, v240
	global_load_lds_dwordx4 v232, s[16:17]
	v_add_u32_e32 v233, 0x100, v241
	s_mov_b32 m0, s23
	s_nop 0
	global_load_lds_dwordx4 v233, s[16:17]
	s_mov_b32 m0, s94
	s_nop 0
	global_load_lds_dwordx4 v232, s[18:19]
	s_mov_b32 m0, s95
	s_nop 0
	global_load_lds_dwordx4 v233, s[18:19]
	s_mov_b32 m0, s2
	s_nop 0
	global_load_lds_dwordx4 v232, s[8:9]
	s_mov_b32 m0, s3
	s_nop 0
	global_load_lds_dwordx4 v233, s[8:9]
	s_waitcnt vmcnt(6)
	s_waitcnt lgkmcnt(0)
	s_barrier
	v_mfma_f32_16x16x32_bf16 v[60:63], v[156:159], v[172:175], v[60:63]
	v_mfma_f32_16x16x32_bf16 v[56:59], v[164:167], v[172:175], v[56:59]
	v_mfma_f32_16x16x32_bf16 v[52:55], v[156:159], v[180:183], v[52:55]
	v_mfma_f32_16x16x32_bf16 v[48:51], v[164:167], v[180:183], v[48:51]
	v_mfma_f32_16x16x32_bf16 v[44:47], v[156:159], v[200:203], v[44:47]
	v_mfma_f32_16x16x32_bf16 v[40:43], v[164:167], v[200:203], v[40:43]
	v_mfma_f32_16x16x32_bf16 v[36:39], v[156:159], v[208:211], v[36:39]
	v_mfma_f32_16x16x32_bf16 v[32:35], v[164:167], v[208:211], v[32:35]
	v_mfma_f32_16x16x32_bf16 v[60:63], v[160:163], v[176:179], v[60:63]
	v_mfma_f32_16x16x32_bf16 v[56:59], v[168:171], v[176:179], v[56:59]
	v_mfma_f32_16x16x32_bf16 v[52:55], v[160:163], v[196:199], v[52:55]
	v_mfma_f32_16x16x32_bf16 v[48:51], v[168:171], v[196:199], v[48:51]
	v_mfma_f32_16x16x32_bf16 v[44:47], v[160:163], v[204:207], v[44:47]
	v_mfma_f32_16x16x32_bf16 v[40:43], v[168:171], v[204:207], v[40:43]
	v_mfma_f32_16x16x32_bf16 v[36:39], v[160:163], v[212:215], v[36:39]
	v_mfma_f32_16x16x32_bf16 v[32:35], v[168:171], v[212:215], v[32:35]
	v_mfma_f32_16x16x32_bf16 v[28:31], v[216:219], v[172:175], v[28:31]
	v_mfma_f32_16x16x32_bf16 v[24:27], v[224:227], v[172:175], v[24:27]
	v_mfma_f32_16x16x32_bf16 v[20:23], v[216:219], v[180:183], v[20:23]
	v_mfma_f32_16x16x32_bf16 v[16:19], v[224:227], v[180:183], v[16:19]
	v_mfma_f32_16x16x32_bf16 v[12:15], v[216:219], v[200:203], v[12:15]
	v_mfma_f32_16x16x32_bf16 v[8:11], v[224:227], v[200:203], v[8:11]
	v_mfma_f32_16x16x32_bf16 v[4:7], v[216:219], v[208:211], v[4:7]
	v_mfma_f32_16x16x32_bf16 v[0:3], v[224:227], v[208:211], v[0:3]
	v_mfma_f32_16x16x32_bf16 v[28:31], v[220:223], v[176:179], v[28:31]
	v_mfma_f32_16x16x32_bf16 v[24:27], v[228:231], v[176:179], v[24:27]
	v_mfma_f32_16x16x32_bf16 v[20:23], v[220:223], v[196:199], v[20:23]
	v_mfma_f32_16x16x32_bf16 v[16:19], v[228:231], v[196:199], v[16:19]
	v_mfma_f32_16x16x32_bf16 v[12:15], v[220:223], v[204:207], v[12:15]
	v_mfma_f32_16x16x32_bf16 v[8:11], v[228:231], v[204:207], v[8:11]
	v_mfma_f32_16x16x32_bf16 v[4:7], v[220:223], v[212:215], v[4:7]
	v_mfma_f32_16x16x32_bf16 v[0:3], v[228:231], v[212:215], v[0:3]
	v_or_b32_e32 v156, 0x18000, v150
	v_add_u32_e32 v158, 0x18100, v150
	s_barrier
; #define WAIT_V(n) asm volatile("s_waitcnt vmcnt(%0)" ::"n"(n) : "memory")
; #define WAIT_L(n) asm volatile("s_waitcnt lgkmcnt(%0)" ::"n"(n) : "memory")
; #define SBAR() __builtin_amdgcn_sched_barrier(0)
; #define STAGE(P, base, kt) do { _Pragma("unroll") for (int _i = 0; _i < 2; ++_i)                                        \
;       __builtin_amdgcn_global_load_lds((const unsigned*)((base) + (size_t)(sOff[_i] + (unsigned)(kt) * (BK * 2))),        \
;                                        (unsigned*)((P) + wid * 1024 + _i * 8192), 16, 0, 0); } while (0)
; #define LDA(dst, b, h) _Pragma("unroll") for (int m = 0; m < 4; ++m) _Pragma("unroll") for (int k = 0; k < 2; ++k) \
;       dst[m][k] = *(const bf16x8*)(SA(b, h) + aoff + (m * 2048 + k * 1024))
; #define LDB(dst, b, h) _Pragma("unroll") for (int n = 0; n < 2; ++n) _Pragma("unroll") for (int k = 0; k < 2; ++k) \
;       dst[n][k] = *(const bf16x8*)(SB(b, h) + boff + (n * 256 + k * 1024))
; #define BAR __builtin_amdgcn_s_barrier()
; template <int EPI, int N, int K>
; __device__ __forceinline__ void phase_gemm(const Params& p, const u16* __restrict__ A, const u16* __restrict__ Bt, int nM, char* shm,
;                            u16* __restrict__ outp, float* __restrict__ rowss) {
;     ...
;       LDB(B0, 1, 0); SBAR(); LDA(At, 1, 0); STAGE(SA(0, 1), A1, t + 2);
;       WAIT_L(8); BAR; WAIT_L(0); MMA(0, 0, At, B0); BAR; SBAR();
;       LDB(B1, 1, 1); STAGE(SB(1, 0), B0p, t + 3);
;       BAR; WAIT_L(0); MMA(0, 1, At, B1); BAR;
;       LDA(At, 1, 1); STAGE(SA(1, 0), A0, t + 3);
;       BAR; WAIT_L(0); MMA(1, 0, At, B0); BAR; SBAR();
;       STAGE(SB(1, 1), B1p, t + 3);
;       WAIT_V(6); BAR; MMA(1, 1, At, B1); BAR;
	v_add_u32_e32 v157, 0x18400, v150
	ds_read_b128 v[164:167], v156
	ds_read_b128 v[168:171], v157
	v_add_u32_e32 v159, 0x18500, v150
	ds_read_b128 v[172:175], v158
	ds_read_b128 v[176:179], v159
	s_mov_b32 m0, s92
	ds_read_b128 v[180:183], v151 offset:32768
	ds_read_b128 v[196:199], v151 offset:33792
	ds_read_b128 v[200:203], v151 offset:34816
	ds_read_b128 v[204:207], v151 offset:35840
	ds_read_b128 v[208:211], v151 offset:36864
	ds_read_b128 v[212:215], v151 offset:37888
	ds_read_b128 v[216:219], v151 offset:38912
	ds_read_b128 v[220:223], v151 offset:39936
	global_load_lds_dwordx4 v232, s[6:7]
	s_mov_b32 m0, s0
	s_nop 0
	global_load_lds_dwordx4 v233, s[6:7]
	v_or_b32_e32 v160, 0x1c000, v150
	v_add_u32_e32 v162, 0x1c100, v150
	v_add_u32_e32 v161, 0x1c400, v150
	ds_read_b128 v[224:227], v160
	ds_read_b128 v[228:231], v161
	v_add_u32_e32 v163, 0x1c500, v150
	ds_read_b128 v[232:235], v162
	ds_read_b128 v[236:239], v163
	s_waitcnt lgkmcnt(0)
	s_barrier
	v_mfma_f32_16x16x32_bf16 v[126:129], v[164:167], v[180:183], v[126:129]
	v_mfma_f32_16x16x32_bf16 v[122:125], v[172:175], v[180:183], v[122:125]
	v_mfma_f32_16x16x32_bf16 v[118:121], v[164:167], v[200:203], v[118:121]
	v_mfma_f32_16x16x32_bf16 v[114:117], v[172:175], v[200:203], v[114:117]
	v_mfma_f32_16x16x32_bf16 v[110:113], v[164:167], v[208:211], v[110:113]
	v_mfma_f32_16x16x32_bf16 v[106:109], v[172:175], v[208:211], v[106:109]
	v_mfma_f32_16x16x32_bf16 v[102:105], v[164:167], v[216:219], v[102:105]
	v_mfma_f32_16x16x32_bf16 v[98:101], v[172:175], v[216:219], v[98:101]
	v_mfma_f32_16x16x32_bf16 v[126:129], v[168:171], v[196:199], v[126:129]
	v_mfma_f32_16x16x32_bf16 v[122:125], v[176:179], v[196:199], v[122:125]
	v_mfma_f32_16x16x32_bf16 v[118:121], v[168:171], v[204:207], v[118:121]
	v_mfma_f32_16x16x32_bf16 v[114:117], v[176:179], v[204:207], v[114:117]
	v_mfma_f32_16x16x32_bf16 v[110:113], v[168:171], v[212:215], v[110:113]
	v_mfma_f32_16x16x32_bf16 v[106:109], v[176:179], v[212:215], v[106:109]
	v_mfma_f32_16x16x32_bf16 v[102:105], v[168:171], v[220:223], v[102:105]
	v_mfma_f32_16x16x32_bf16 v[98:101], v[176:179], v[220:223], v[98:101]
	v_mfma_f32_16x16x32_bf16 v[92:95], v[224:227], v[180:183], v[92:95]
	v_mfma_f32_16x16x32_bf16 v[88:91], v[232:235], v[180:183], v[88:91]
	v_mfma_f32_16x16x32_bf16 v[84:87], v[224:227], v[200:203], v[84:87]
	v_mfma_f32_16x16x32_bf16 v[80:83], v[232:235], v[200:203], v[80:83]
	v_mfma_f32_16x16x32_bf16 v[76:79], v[224:227], v[208:211], v[76:79]
	v_mfma_f32_16x16x32_bf16 v[72:75], v[232:235], v[208:211], v[72:75]
	v_mfma_f32_16x16x32_bf16 v[68:71], v[224:227], v[216:219], v[68:71]
	v_mfma_f32_16x16x32_bf16 v[64:67], v[232:235], v[216:219], v[64:67]
	v_mfma_f32_16x16x32_bf16 v[92:95], v[228:231], v[196:199], v[92:95]
	v_mfma_f32_16x16x32_bf16 v[88:91], v[236:239], v[196:199], v[88:91]
	v_mfma_f32_16x16x32_bf16 v[84:87], v[228:231], v[204:207], v[84:87]
	v_mfma_f32_16x16x32_bf16 v[80:83], v[236:239], v[204:207], v[80:83]
	v_mfma_f32_16x16x32_bf16 v[76:79], v[228:231], v[212:215], v[76:79]
	v_mfma_f32_16x16x32_bf16 v[72:75], v[236:239], v[212:215], v[72:75]
	v_mfma_f32_16x16x32_bf16 v[68:71], v[228:231], v[220:223], v[68:71]
	v_mfma_f32_16x16x32_bf16 v[64:67], v[236:239], v[220:223], v[64:67]
	s_barrier
	ds_read_b128 v[180:183], v151 offset:49152
	ds_read_b128 v[196:199], v151 offset:50176
	ds_read_b128 v[200:203], v151 offset:51200
	ds_read_b128 v[204:207], v151 offset:52224
	ds_read_b128 v[208:211], v151 offset:53248
	ds_read_b128 v[212:215], v151 offset:54272
	ds_read_b128 v[216:219], v151 offset:55296
	ds_read_b128 v[220:223], v151 offset:56320
	s_mov_b32 m0, s1
	v_add_u32_e32 v240, 0x180, v240
	global_load_lds_dwordx4 v240, s[16:17]
	v_add_u32_e32 v241, 0x180, v241
	s_mov_b32 m0, s12
	s_nop 0
	global_load_lds_dwordx4 v241, s[16:17]
	s_mov_b32 m0, s13
	s_nop 0
	global_load_lds_dwordx4 v240, s[18:19]
	s_mov_b32 m0, s14
	s_nop 0
	global_load_lds_dwordx4 v241, s[18:19]
	s_mov_b32 m0, s15
	s_nop 0
	global_load_lds_dwordx4 v240, s[8:9]
	s_mov_b32 m0, s4
	s_nop 0
	global_load_lds_dwordx4 v241, s[8:9]
	s_waitcnt vmcnt(6)
	s_waitcnt lgkmcnt(0)
	s_barrier
	v_mfma_f32_16x16x32_bf16 v[60:63], v[164:167], v[180:183], v[60:63]
	v_mfma_f32_16x16x32_bf16 v[56:59], v[172:175], v[180:183], v[56:59]
	v_mfma_f32_16x16x32_bf16 v[52:55], v[164:167], v[200:203], v[52:55]
	v_mfma_f32_16x16x32_bf16 v[48:51], v[172:175], v[200:203], v[48:51]
	v_mfma_f32_16x16x32_bf16 v[44:47], v[164:167], v[208:211], v[44:47]
	v_mfma_f32_16x16x32_bf16 v[40:43], v[172:175], v[208:211], v[40:43]
	v_mfma_f32_16x16x32_bf16 v[36:39], v[164:167], v[216:219], v[36:39]
	v_mfma_f32_16x16x32_bf16 v[32:35], v[172:175], v[216:219], v[32:35]
	v_mfma_f32_16x16x32_bf16 v[60:63], v[168:171], v[196:199], v[60:63]
	v_mfma_f32_16x16x32_bf16 v[56:59], v[176:179], v[196:199], v[56:59]
	v_mfma_f32_16x16x32_bf16 v[52:55], v[168:171], v[204:207], v[52:55]
	v_mfma_f32_16x16x32_bf16 v[48:51], v[176:179], v[204:207], v[48:51]
	v_mfma_f32_16x16x32_bf16 v[44:47], v[168:171], v[212:215], v[44:47]
	v_mfma_f32_16x16x32_bf16 v[40:43], v[176:179], v[212:215], v[40:43]
	v_mfma_f32_16x16x32_bf16 v[36:39], v[168:171], v[220:223], v[36:39]
	v_mfma_f32_16x16x32_bf16 v[32:35], v[176:179], v[220:223], v[32:35]
	v_mfma_f32_16x16x32_bf16 v[28:31], v[224:227], v[180:183], v[28:31]
	v_mfma_f32_16x16x32_bf16 v[24:27], v[232:235], v[180:183], v[24:27]
	v_mfma_f32_16x16x32_bf16 v[20:23], v[224:227], v[200:203], v[20:23]
	v_mfma_f32_16x16x32_bf16 v[16:19], v[232:235], v[200:203], v[16:19]
	v_mfma_f32_16x16x32_bf16 v[12:15], v[224:227], v[208:211], v[12:15]
	v_mfma_f32_16x16x32_bf16 v[8:11], v[232:235], v[208:211], v[8:11]
	v_mfma_f32_16x16x32_bf16 v[4:7], v[224:227], v[216:219], v[4:7]
	v_mfma_f32_16x16x32_bf16 v[0:3], v[232:235], v[216:219], v[0:3]
	v_mfma_f32_16x16x32_bf16 v[28:31], v[228:231], v[196:199], v[28:31]
	v_mfma_f32_16x16x32_bf16 v[24:27], v[236:239], v[196:199], v[24:27]
	v_mfma_f32_16x16x32_bf16 v[20:23], v[228:231], v[204:207], v[20:23]
	v_mfma_f32_16x16x32_bf16 v[16:19], v[236:239], v[204:207], v[16:19]
	v_mfma_f32_16x16x32_bf16 v[12:15], v[228:231], v[212:215], v[12:15]
	v_mfma_f32_16x16x32_bf16 v[8:11], v[236:239], v[212:215], v[8:11]
	v_mfma_f32_16x16x32_bf16 v[4:7], v[228:231], v[220:223], v[4:7]
	v_mfma_f32_16x16x32_bf16 v[0:3], v[236:239], v[220:223], v[0:3]
	s_add_i32 s11, s11, 2
	v_add_u32_e32 v130, 0x100, v130
	s_cmp_lt_u32 s11, 12
	v_add_u32_e32 v96, 0x100, v96
	s_barrier
; #define WAIT_V(n) asm volatile("s_waitcnt vmcnt(%0)" ::"n"(n) : "memory")
; #define WAIT_L(n) asm volatile("s_waitcnt lgkmcnt(%0)" ::"n"(n) : "memory")
; #define STAGE(P, base, kt) do { _Pragma("unroll") for (int _i = 0; _i < 2; ++_i)                                        \
;       __builtin_amdgcn_global_load_lds((const unsigned*)((base) + (size_t)(sOff[_i] + (unsigned)(kt) * (BK * 2))),        \
;                                        (unsigned*)((P) + wid * 1024 + _i * 8192), 16, 0, 0); } while (0)
; #define LDA(dst, b, h) _Pragma("unroll") for (int m = 0; m < 4; ++m) _Pragma("unroll") for (int k = 0; k < 2; ++k) \
;       dst[m][k] = *(const bf16x8*)(SA(b, h) + aoff + (m * 2048 + k * 1024))
; #define LDB(dst, b, h) _Pragma("unroll") for (int n = 0; n < 2; ++n) _Pragma("unroll") for (int k = 0; k < 2; ++k) \
;       dst[n][k] = *(const bf16x8*)(SB(b, h) + boff + (n * 256 + k * 1024))
; #define BAR __builtin_amdgcn_s_barrier()
; template <int EPI, int N, int K>
; __device__ __forceinline__ void phase_gemm(const Params& p, const u16* __restrict__ A, const u16* __restrict__ Bt, int nM, char* shm,
;                            u16* __restrict__ outp, float* __restrict__ rowss) {
;     ...
;     }
;     { LDB(B0, 0, 0); LDA(At, 0, 0); STAGE(SA(1, 1), A1, nt - 1);
;       BAR; WAIT_L(0); MMA(0, 0, At, B0); BAR;
;       LDB(B1, 0, 1); BAR; WAIT_L(0); MMA(0, 1, At, B1); BAR;
;       LDA(At, 0, 1); WAIT_V(4); BAR; WAIT_L(0); MMA(1, 0, At, B0); MMA(1, 1, At, B1); BAR; }
	s_cbranch_scc1 .LBB0_379
	s_mov_b32 m0, s26
	v_lshl_add_u64 v[220:221], s[6:7], 0, v[142:143]
	ds_read_b128 v[164:167], v131
	ds_read_b128 v[168:171], v132
	ds_read_b128 v[130:133], v133
	ds_read_b128 v[172:175], v146
	ds_read_b128 v[176:179], v151
	ds_read_b128 v[180:183], v151 offset:1024
	ds_read_b128 v[196:199], v151 offset:2048
	ds_read_b128 v[200:203], v151 offset:3072
	ds_read_b128 v[204:207], v151 offset:4096
	ds_read_b128 v[208:211], v151 offset:5120
	ds_read_b128 v[212:215], v151 offset:6144
	ds_read_b128 v[216:219], v151 offset:7168
	global_load_lds_dwordx4 v[220:221], off
	v_lshl_add_u64 v[220:221], s[6:7], 0, v[144:145]
	s_mov_b32 m0, s25
	s_nop 0
	global_load_lds_dwordx4 v[220:221], off
	s_barrier
	s_waitcnt lgkmcnt(0)
	s_waitcnt lgkmcnt(0)
	v_mfma_f32_16x16x32_bf16 v[126:129], v[164:167], v[176:179], v[126:129]
	v_mfma_f32_16x16x32_bf16 v[122:125], v[130:133], v[176:179], v[122:125]
	v_mfma_f32_16x16x32_bf16 v[118:121], v[164:167], v[196:199], v[118:121]
	v_mfma_f32_16x16x32_bf16 v[114:117], v[130:133], v[196:199], v[114:117]
	v_mfma_f32_16x16x32_bf16 v[102:105], v[164:167], v[212:215], v[102:105]
	v_mfma_f32_16x16x32_bf16 v[98:101], v[130:133], v[212:215], v[98:101]
	v_mfma_f32_16x16x32_bf16 v[126:129], v[168:171], v[180:183], v[126:129]
	v_mfma_f32_16x16x32_bf16 v[122:125], v[172:175], v[180:183], v[122:125]
	v_mfma_f32_16x16x32_bf16 v[118:121], v[168:171], v[200:203], v[118:121]
	v_mfma_f32_16x16x32_bf16 v[114:117], v[172:175], v[200:203], v[114:117]
	v_mfma_f32_16x16x32_bf16 v[110:113], v[164:167], v[204:207], v[110:113]
	v_mfma_f32_16x16x32_bf16 v[106:109], v[130:133], v[204:207], v[106:109]
	v_mfma_f32_16x16x32_bf16 v[102:105], v[168:171], v[216:219], v[102:105]
	v_mfma_f32_16x16x32_bf16 v[98:101], v[172:175], v[216:219], v[98:101]
	v_mfma_f32_16x16x32_bf16 v[220:223], v[168:171], v[208:211], v[110:113]
	v_mfma_f32_16x16x32_bf16 v[224:227], v[172:175], v[208:211], v[106:109]
	s_barrier
	s_nop 1
	ds_read_b128 v[106:109], v148
	ds_read_b128 v[110:113], v149
	ds_read_b128 v[228:231], v154
	ds_read_b128 v[232:235], v155
	s_barrier
	s_waitcnt lgkmcnt(0)
	s_waitcnt lgkmcnt(0)
	v_mfma_f32_16x16x32_bf16 v[84:87], v[106:109], v[196:199], v[84:87]
	v_mfma_f32_16x16x32_bf16 v[80:83], v[228:231], v[196:199], v[80:83]
	v_mfma_f32_16x16x32_bf16 v[68:71], v[106:109], v[212:215], v[68:71]
	v_mfma_f32_16x16x32_bf16 v[64:67], v[228:231], v[212:215], v[64:67]
	v_mfma_f32_16x16x32_bf16 v[92:95], v[106:109], v[176:179], v[92:95]
	v_mfma_f32_16x16x32_bf16 v[88:91], v[228:231], v[176:179], v[88:91]
	v_mfma_f32_16x16x32_bf16 v[84:87], v[110:113], v[200:203], v[84:87]
	v_mfma_f32_16x16x32_bf16 v[80:83], v[232:235], v[200:203], v[80:83]
	v_mfma_f32_16x16x32_bf16 v[76:79], v[106:109], v[204:207], v[76:79]
	v_mfma_f32_16x16x32_bf16 v[72:75], v[228:231], v[204:207], v[72:75]
	v_mfma_f32_16x16x32_bf16 v[68:71], v[110:113], v[216:219], v[68:71]
	v_mfma_f32_16x16x32_bf16 v[64:67], v[232:235], v[216:219], v[64:67]
	v_mfma_f32_16x16x32_bf16 v[236:239], v[110:113], v[180:183], v[92:95]
	v_mfma_f32_16x16x32_bf16 v[176:179], v[232:235], v[180:183], v[88:91]
	v_mfma_f32_16x16x32_bf16 v[180:183], v[110:113], v[208:211], v[76:79]
	v_mfma_f32_16x16x32_bf16 v[196:199], v[232:235], v[208:211], v[72:75]
	s_barrier
	s_nop 0
	ds_read_b128 v[72:75], v151 offset:16384
	ds_read_b128 v[76:79], v151 offset:17408
	ds_read_b128 v[88:91], v151 offset:18432
	ds_read_b128 v[92:95], v151 offset:19456
	ds_read_b128 v[200:203], v151 offset:20480
	ds_read_b128 v[204:207], v151 offset:21504
	ds_read_b128 v[208:211], v151 offset:22528
	ds_read_b128 v[212:215], v151 offset:23552
	s_waitcnt vmcnt(4)
	s_barrier
	s_waitcnt lgkmcnt(0)
	s_waitcnt lgkmcnt(0)
	v_mfma_f32_16x16x32_bf16 v[60:63], v[164:167], v[72:75], v[60:63]
	v_mfma_f32_16x16x32_bf16 v[56:59], v[130:133], v[72:75], v[56:59]
	v_mfma_f32_16x16x32_bf16 v[52:55], v[164:167], v[88:91], v[52:55]
	v_mfma_f32_16x16x32_bf16 v[48:51], v[130:133], v[88:91], v[48:51]
	v_mfma_f32_16x16x32_bf16 v[36:39], v[164:167], v[208:211], v[36:39]
	v_mfma_f32_16x16x32_bf16 v[32:35], v[130:133], v[208:211], v[32:35]
	v_mfma_f32_16x16x32_bf16 v[60:63], v[168:171], v[76:79], v[60:63]
	v_mfma_f32_16x16x32_bf16 v[56:59], v[172:175], v[76:79], v[56:59]
	v_mfma_f32_16x16x32_bf16 v[52:55], v[168:171], v[92:95], v[52:55]
	v_mfma_f32_16x16x32_bf16 v[48:51], v[172:175], v[92:95], v[48:51]
	v_mfma_f32_16x16x32_bf16 v[44:47], v[164:167], v[200:203], v[44:47]
	v_mfma_f32_16x16x32_bf16 v[40:43], v[130:133], v[200:203], v[40:43]
	v_mfma_f32_16x16x32_bf16 v[36:39], v[168:171], v[212:215], v[36:39]
	v_mfma_f32_16x16x32_bf16 v[32:35], v[172:175], v[212:215], v[32:35]
	v_mfma_f32_16x16x32_bf16 v[216:219], v[168:171], v[204:207], v[44:47]
	v_mfma_f32_16x16x32_bf16 v[240:243], v[172:175], v[204:207], v[40:43]
	v_mfma_f32_16x16x32_bf16 v[20:23], v[106:109], v[88:91], v[20:23]
	v_mfma_f32_16x16x32_bf16 v[16:19], v[228:231], v[88:91], v[16:19]
	v_mfma_f32_16x16x32_bf16 v[4:7], v[106:109], v[208:211], v[4:7]
	v_mfma_f32_16x16x32_bf16 v[0:3], v[228:231], v[208:211], v[0:3]
	v_mfma_f32_16x16x32_bf16 v[28:31], v[106:109], v[72:75], v[28:31]
	v_mfma_f32_16x16x32_bf16 v[24:27], v[228:231], v[72:75], v[24:27]
	v_mfma_f32_16x16x32_bf16 v[20:23], v[110:113], v[92:95], v[20:23]
	v_mfma_f32_16x16x32_bf16 v[16:19], v[232:235], v[92:95], v[16:19]
	v_mfma_f32_16x16x32_bf16 v[12:15], v[106:109], v[200:203], v[12:15]
	v_mfma_f32_16x16x32_bf16 v[8:11], v[228:231], v[200:203], v[8:11]
	v_mfma_f32_16x16x32_bf16 v[4:7], v[110:113], v[212:215], v[4:7]
	v_mfma_f32_16x16x32_bf16 v[0:3], v[232:235], v[212:215], v[0:3]
	v_mfma_f32_16x16x32_bf16 v[130:133], v[110:113], v[76:79], v[28:31]
	v_mfma_f32_16x16x32_bf16 v[164:167], v[232:235], v[76:79], v[24:27]
	v_mfma_f32_16x16x32_bf16 v[168:171], v[110:113], v[204:207], v[12:15]
	v_mfma_f32_16x16x32_bf16 v[172:175], v[232:235], v[204:207], v[8:11]
	s_barrier
; #define WAIT_V(n) asm volatile("s_waitcnt vmcnt(%0)" ::"n"(n) : "memory")
; #define WAIT_L(n) asm volatile("s_waitcnt lgkmcnt(%0)" ::"n"(n) : "memory")
; #define LDA(dst, b, h) _Pragma("unroll") for (int m = 0; m < 4; ++m) _Pragma("unroll") for (int k = 0; k < 2; ++k) \
;       dst[m][k] = *(const bf16x8*)(SA(b, h) + aoff + (m * 2048 + k * 1024))
; #define LDB(dst, b, h) _Pragma("unroll") for (int n = 0; n < 2; ++n) _Pragma("unroll") for (int k = 0; k < 2; ++k) \
;       dst[n][k] = *(const bf16x8*)(SB(b, h) + boff + (n * 256 + k * 1024))
; #define BAR __builtin_amdgcn_s_barrier()
; template <int EPI, int N, int K>
; __device__ __forceinline__ void phase_gemm(const Params& p, const u16* __restrict__ A, const u16* __restrict__ Bt, int nM, char* shm,
;                            u16* __restrict__ outp, float* __restrict__ rowss) {
;     ...
;     { LDB(B0, 1, 0); LDA(At, 1, 0); WAIT_V(2); BAR; WAIT_L(0); MMA(0, 0, At, B0); BAR;
;       LDB(B1, 1, 1); WAIT_V(0); BAR; WAIT_L(0); MMA(0, 1, At, B1); BAR;
;       LDA(At, 1, 1); BAR; WAIT_L(0); MMA(1, 0, At, B0); MMA(1, 1, At, B1); BAR; }
;     if (wr == 0) BAR;
	s_nop 0
	ds_read_b128 v[8:11], v156
	ds_read_b128 v[12:15], v157
	ds_read_b128 v[154:157], v158
	ds_read_b128 v[200:203], v159
	ds_read_b128 v[24:27], v151 offset:32768
	ds_read_b128 v[28:31], v151 offset:33792
	ds_read_b128 v[40:43], v151 offset:34816
	ds_read_b128 v[44:47], v151 offset:35840
	ds_read_b128 v[204:207], v151 offset:36864
	ds_read_b128 v[208:211], v151 offset:37888
	ds_read_b128 v[212:215], v151 offset:38912
	ds_read_b128 v[228:231], v151 offset:39936
	s_waitcnt vmcnt(2)
	s_barrier
	s_waitcnt lgkmcnt(0)
	s_waitcnt lgkmcnt(0)
	v_mfma_f32_16x16x32_bf16 v[72:75], v[8:11], v[24:27], v[126:129]
	v_mfma_f32_16x16x32_bf16 v[126:129], v[12:15], v[28:31], v[72:75]
	v_mfma_f32_16x16x32_bf16 v[72:75], v[154:157], v[24:27], v[122:125]
	v_mfma_f32_16x16x32_bf16 v[122:125], v[200:203], v[28:31], v[72:75]
	v_mfma_f32_16x16x32_bf16 v[72:75], v[8:11], v[40:43], v[118:121]
	v_mfma_f32_16x16x32_bf16 v[110:113], v[12:15], v[44:47], v[72:75]
	v_mfma_f32_16x16x32_bf16 v[72:75], v[154:157], v[40:43], v[114:117]
	v_mfma_f32_16x16x32_bf16 v[106:109], v[200:203], v[44:47], v[72:75]
	v_mfma_f32_16x16x32_bf16 v[72:75], v[8:11], v[204:207], v[220:223]
	v_mfma_f32_16x16x32_bf16 v[92:95], v[12:15], v[208:211], v[72:75]
	v_mfma_f32_16x16x32_bf16 v[72:75], v[154:157], v[204:207], v[224:227]
	v_mfma_f32_16x16x32_bf16 v[88:91], v[200:203], v[208:211], v[72:75]
	v_mfma_f32_16x16x32_bf16 v[72:75], v[8:11], v[212:215], v[102:105]
	v_mfma_f32_16x16x32_bf16 v[76:79], v[12:15], v[228:231], v[72:75]
	v_mfma_f32_16x16x32_bf16 v[72:75], v[154:157], v[212:215], v[98:101]
	v_mfma_f32_16x16x32_bf16 v[72:75], v[200:203], v[228:231], v[72:75]
	s_barrier
	ds_read_b128 v[220:223], v160
	ds_read_b128 v[158:161], v161
	ds_read_b128 v[224:227], v162
	ds_read_b128 v[232:235], v163
	s_waitcnt vmcnt(0)
	s_barrier
	s_waitcnt lgkmcnt(0)
	s_waitcnt lgkmcnt(0)
	v_mfma_f32_16x16x32_bf16 v[98:101], v[220:223], v[24:27], v[236:239]
	v_mfma_f32_16x16x32_bf16 v[24:27], v[224:227], v[24:27], v[176:179]
	v_mfma_f32_16x16x32_bf16 v[114:117], v[232:235], v[28:31], v[24:27]
	v_mfma_f32_16x16x32_bf16 v[24:27], v[220:223], v[40:43], v[84:87]
	v_mfma_f32_16x16x32_bf16 v[102:105], v[158:161], v[44:47], v[24:27]
	v_mfma_f32_16x16x32_bf16 v[24:27], v[224:227], v[40:43], v[80:83]
	v_mfma_f32_16x16x32_bf16 v[118:121], v[158:161], v[28:31], v[98:101]
	v_mfma_f32_16x16x32_bf16 v[98:101], v[232:235], v[44:47], v[24:27]
	v_mfma_f32_16x16x32_bf16 v[24:27], v[220:223], v[204:207], v[180:183]
	v_mfma_f32_16x16x32_bf16 v[84:87], v[158:161], v[208:211], v[24:27]
	v_mfma_f32_16x16x32_bf16 v[24:27], v[224:227], v[204:207], v[196:199]
	v_mfma_f32_16x16x32_bf16 v[80:83], v[232:235], v[208:211], v[24:27]
	v_mfma_f32_16x16x32_bf16 v[24:27], v[220:223], v[212:215], v[68:71]
	v_mfma_f32_16x16x32_bf16 v[68:71], v[158:161], v[228:231], v[24:27]
	v_mfma_f32_16x16x32_bf16 v[24:27], v[224:227], v[212:215], v[64:67]
	v_mfma_f32_16x16x32_bf16 v[64:67], v[232:235], v[228:231], v[24:27]
	s_barrier
	ds_read_b128 v[176:179], v151 offset:49152
	ds_read_b128 v[180:183], v151 offset:50176
	ds_read_b128 v[196:199], v151 offset:51200
	ds_read_b128 v[204:207], v151 offset:52224
	ds_read_b128 v[208:211], v151 offset:53248
	ds_read_b128 v[212:215], v151 offset:54272
	ds_read_b128 v[228:231], v151 offset:55296
	ds_read_b128 v[236:239], v151 offset:56320
	s_barrier
	s_waitcnt lgkmcnt(0)
	s_waitcnt lgkmcnt(0)
	v_mfma_f32_16x16x32_bf16 v[24:27], v[8:11], v[176:179], v[60:63]
	v_mfma_f32_16x16x32_bf16 v[60:63], v[12:15], v[180:183], v[24:27]
	v_mfma_f32_16x16x32_bf16 v[24:27], v[154:157], v[176:179], v[56:59]
	v_mfma_f32_16x16x32_bf16 v[56:59], v[200:203], v[180:183], v[24:27]
	v_mfma_f32_16x16x32_bf16 v[24:27], v[8:11], v[196:199], v[52:55]
	v_mfma_f32_16x16x32_bf16 v[44:47], v[12:15], v[204:207], v[24:27]
	v_mfma_f32_16x16x32_bf16 v[24:27], v[154:157], v[196:199], v[48:51]
	v_mfma_f32_16x16x32_bf16 v[40:43], v[200:203], v[204:207], v[24:27]
	v_mfma_f32_16x16x32_bf16 v[24:27], v[8:11], v[208:211], v[216:219]
	v_mfma_f32_16x16x32_bf16 v[8:11], v[8:11], v[228:231], v[36:39]
	v_mfma_f32_16x16x32_bf16 v[28:31], v[12:15], v[212:215], v[24:27]
	v_mfma_f32_16x16x32_bf16 v[24:27], v[154:157], v[208:211], v[240:243]
	v_mfma_f32_16x16x32_bf16 v[12:15], v[12:15], v[236:239], v[8:11]
	v_mfma_f32_16x16x32_bf16 v[8:11], v[154:157], v[228:231], v[32:35]
	v_mfma_f32_16x16x32_bf16 v[24:27], v[200:203], v[212:215], v[24:27]
	v_mfma_f32_16x16x32_bf16 v[8:11], v[200:203], v[236:239], v[8:11]
	v_mfma_f32_16x16x32_bf16 v[32:35], v[220:223], v[176:179], v[130:133]
	v_mfma_f32_16x16x32_bf16 v[52:55], v[158:161], v[180:183], v[32:35]
	v_mfma_f32_16x16x32_bf16 v[32:35], v[224:227], v[176:179], v[164:167]
	v_mfma_f32_16x16x32_bf16 v[16:19], v[224:227], v[196:199], v[16:19]
	v_mfma_f32_16x16x32_bf16 v[48:51], v[232:235], v[180:183], v[32:35]
	v_mfma_f32_16x16x32_bf16 v[20:23], v[220:223], v[196:199], v[20:23]
	v_mfma_f32_16x16x32_bf16 v[32:35], v[232:235], v[204:207], v[16:19]
	v_mfma_f32_16x16x32_bf16 v[16:19], v[220:223], v[208:211], v[168:171]
	v_mfma_f32_16x16x32_bf16 v[36:39], v[158:161], v[204:207], v[20:23]
	v_mfma_f32_16x16x32_bf16 v[20:23], v[158:161], v[212:215], v[16:19]
	v_mfma_f32_16x16x32_bf16 v[16:19], v[224:227], v[208:211], v[172:175]
	v_mfma_f32_16x16x32_bf16 v[4:7], v[220:223], v[228:231], v[4:7]
	v_mfma_f32_16x16x32_bf16 v[0:3], v[224:227], v[228:231], v[0:3]
	v_mfma_f32_16x16x32_bf16 v[16:19], v[232:235], v[212:215], v[16:19]
	v_mfma_f32_16x16x32_bf16 v[4:7], v[158:161], v[236:239], v[4:7]
	v_mfma_f32_16x16x32_bf16 v[0:3], v[232:235], v[236:239], v[0:3]
	s_andn2_b64 vcc, exec, s[62:63]
	s_barrier
	s_cbranch_vccnz .LBB0_382
	s_barrier

; #define WAIT_V(n) asm volatile("s_waitcnt vmcnt(%0)" ::"n"(n) : "memory")
; #define WAIT_L(n) asm volatile("s_waitcnt lgkmcnt(%0)" ::"n"(n) : "memory")
; #define SBAR() __builtin_amdgcn_sched_barrier(0)
; #define STAGE(P, base, kt) do { _Pragma("unroll") for (int _i = 0; _i < 2; ++_i)                                        \
;       __builtin_amdgcn_global_load_lds((const unsigned*)((base) + (size_t)(sOff[_i] + (unsigned)(kt) * (BK * 2))),        \
;                                        (unsigned*)((P) + wid * 1024 + _i * 8192), 16, 0, 0); } while (0)
; #define LDA(dst, b, h) _Pragma("unroll") for (int m = 0; m < 4; ++m) _Pragma("unroll") for (int k = 0; k < 2; ++k) \
;       dst[m][k] = *(const bf16x8*)(SA(b, h) + aoff + (m * 2048 + k * 1024))
; #define LDB(dst, b, h) _Pragma("unroll") for (int n = 0; n < 2; ++n) _Pragma("unroll") for (int k = 0; k < 2; ++k) \
;       dst[n][k] = *(const bf16x8*)(SB(b, h) + boff + (n * 256 + k * 1024))
; #define BAR __builtin_amdgcn_s_barrier()
; template <int EPI, int N, int K>
; __device__ __forceinline__ void phase_gemm(const Params& p, const u16* __restrict__ A, const u16* __restrict__ Bt, int nM, char* shm,
;                            u16* __restrict__ outp, float* __restrict__ rowss) {
;     ...
;     for (int t = 0; t < nt - 2; t += 2) {
;       LDB(B0, 0, 0); SBAR(); LDA(At, 0, 0); STAGE(SA(1, 1), A1, t + 1);
;       WAIT_L(8); BAR; WAIT_L(0); MMA(0, 0, At, B0); BAR; SBAR();
;       LDB(B1, 0, 1); STAGE(SB(0, 0), B0p, t + 2);
;       BAR; WAIT_L(0); MMA(0, 1, At, B1); BAR;
;       LDA(At, 0, 1); STAGE(SA(0, 0), A0, t + 2);
;       BAR; WAIT_L(0); MMA(1, 0, At, B0); BAR; SBAR();
;       STAGE(SB(0, 1), B1p, t + 2);
;       WAIT_V(6); BAR; MMA(1, 1, At, B1); BAR;
.LBB0_433:
	v_or_b32_e32 v143, 0x10000, v145
	v_add_u32_e32 v150, 0x10100, v145
	v_add_u32_e32 v149, 0x10400, v145
	ds_read_b128 v[156:159], v143
	ds_read_b128 v[160:163], v149
	v_add_u32_e32 v151, 0x10500, v145
	ds_read_b128 v[164:167], v150
	ds_read_b128 v[168:171], v151
	v_add_u32_e32 v204, v144, v96
	s_add_i32 s62, s5, 0xc000
	v_add_u32_e32 v152, 0x80, v204
	s_mov_b32 m0, s62
	v_add_u32_e32 v205, v144, v142
	s_add_i32 s23, s5, 0xe000
	ds_read_b128 v[172:175], v146
	ds_read_b128 v[176:179], v146 offset:1024
	ds_read_b128 v[180:183], v146 offset:2048
	ds_read_b128 v[196:199], v146 offset:3072
	ds_read_b128 v[200:203], v146 offset:4096
	ds_read_b128 v[208:211], v146 offset:5120
	ds_read_b128 v[212:215], v146 offset:6144
	ds_read_b128 v[216:219], v146 offset:7168
	global_load_lds_dwordx4 v152, s[16:17]
	v_add_u32_e32 v152, 0x80, v205
	s_mov_b32 m0, s23
	s_nop 0
	global_load_lds_dwordx4 v152, s[16:17]
	v_or_b32_e32 v152, 0x14000, v145
	v_add_u32_e32 v154, 0x14100, v145
	v_add_u32_e32 v153, 0x14400, v145
	ds_read_b128 v[220:223], v152
	ds_read_b128 v[224:227], v153
	v_add_u32_e32 v155, 0x14500, v145
	ds_read_b128 v[228:231], v154
	ds_read_b128 v[232:235], v155
	s_waitcnt lgkmcnt(0)
	s_barrier
	v_mfma_f32_16x16x32_bf16 v[126:129], v[156:159], v[172:175], v[126:129]
	v_mfma_f32_16x16x32_bf16 v[122:125], v[164:167], v[172:175], v[122:125]
	v_mfma_f32_16x16x32_bf16 v[118:121], v[156:159], v[180:183], v[118:121]
	v_mfma_f32_16x16x32_bf16 v[114:117], v[164:167], v[180:183], v[114:117]
	v_mfma_f32_16x16x32_bf16 v[110:113], v[156:159], v[200:203], v[110:113]
	v_mfma_f32_16x16x32_bf16 v[106:109], v[164:167], v[200:203], v[106:109]
	v_mfma_f32_16x16x32_bf16 v[102:105], v[156:159], v[212:215], v[102:105]
	v_mfma_f32_16x16x32_bf16 v[98:101], v[164:167], v[212:215], v[98:101]
	v_mfma_f32_16x16x32_bf16 v[126:129], v[160:163], v[176:179], v[126:129]
	v_mfma_f32_16x16x32_bf16 v[122:125], v[168:171], v[176:179], v[122:125]
	v_mfma_f32_16x16x32_bf16 v[118:121], v[160:163], v[196:199], v[118:121]
	v_mfma_f32_16x16x32_bf16 v[114:117], v[168:171], v[196:199], v[114:117]
	v_mfma_f32_16x16x32_bf16 v[110:113], v[160:163], v[208:211], v[110:113]
	v_mfma_f32_16x16x32_bf16 v[106:109], v[168:171], v[208:211], v[106:109]
	v_mfma_f32_16x16x32_bf16 v[102:105], v[160:163], v[216:219], v[102:105]
	v_mfma_f32_16x16x32_bf16 v[98:101], v[168:171], v[216:219], v[98:101]
	v_mfma_f32_16x16x32_bf16 v[92:95], v[220:223], v[172:175], v[92:95]
	v_mfma_f32_16x16x32_bf16 v[88:91], v[228:231], v[172:175], v[88:91]
	v_mfma_f32_16x16x32_bf16 v[84:87], v[220:223], v[180:183], v[84:87]
	v_mfma_f32_16x16x32_bf16 v[80:83], v[228:231], v[180:183], v[80:83]
	v_mfma_f32_16x16x32_bf16 v[76:79], v[220:223], v[200:203], v[76:79]
	v_mfma_f32_16x16x32_bf16 v[72:75], v[228:231], v[200:203], v[72:75]
	v_mfma_f32_16x16x32_bf16 v[68:71], v[220:223], v[212:215], v[68:71]
	v_mfma_f32_16x16x32_bf16 v[64:67], v[228:231], v[212:215], v[64:67]
	v_mfma_f32_16x16x32_bf16 v[92:95], v[224:227], v[176:179], v[92:95]
	v_mfma_f32_16x16x32_bf16 v[88:91], v[232:235], v[176:179], v[88:91]
	v_mfma_f32_16x16x32_bf16 v[84:87], v[224:227], v[196:199], v[84:87]
	v_mfma_f32_16x16x32_bf16 v[80:83], v[232:235], v[196:199], v[80:83]
	v_mfma_f32_16x16x32_bf16 v[76:79], v[224:227], v[208:211], v[76:79]
	v_mfma_f32_16x16x32_bf16 v[72:75], v[232:235], v[208:211], v[72:75]
	v_mfma_f32_16x16x32_bf16 v[68:71], v[224:227], v[216:219], v[68:71]
	v_mfma_f32_16x16x32_bf16 v[64:67], v[232:235], v[216:219], v[64:67]
	s_barrier
	ds_read_b128 v[172:175], v146 offset:16384
	ds_read_b128 v[176:179], v146 offset:17408
	ds_read_b128 v[180:183], v146 offset:18432
	ds_read_b128 v[196:199], v146 offset:19456
	ds_read_b128 v[200:203], v146 offset:20480
	ds_read_b128 v[208:211], v146 offset:21504
	ds_read_b128 v[212:215], v146 offset:22528
	ds_read_b128 v[216:219], v146 offset:23552
	s_mov_b32 m0, s25
	v_add_u32_e32 v206, 0x100, v204
	global_load_lds_dwordx4 v206, s[8:9]
	v_add_u32_e32 v207, 0x100, v205
	s_mov_b32 m0, s26
	s_nop 0
	global_load_lds_dwordx4 v207, s[8:9]
	s_mov_b32 m0, s5
	s_nop 0
	global_load_lds_dwordx4 v206, s[10:11]
	s_mov_b32 m0, s24
	s_nop 0
	global_load_lds_dwordx4 v207, s[10:11]
	s_mov_b32 m0, s27
	s_nop 0
	global_load_lds_dwordx4 v206, s[18:19]
	s_mov_b32 m0, s28
	s_nop 0
	global_load_lds_dwordx4 v207, s[18:19]
	s_waitcnt vmcnt(6)
	s_waitcnt lgkmcnt(0)
	s_barrier
	v_mfma_f32_16x16x32_bf16 v[60:63], v[156:159], v[172:175], v[60:63]
	v_mfma_f32_16x16x32_bf16 v[56:59], v[164:167], v[172:175], v[56:59]
	v_mfma_f32_16x16x32_bf16 v[52:55], v[156:159], v[180:183], v[52:55]
	v_mfma_f32_16x16x32_bf16 v[48:51], v[164:167], v[180:183], v[48:51]
	v_mfma_f32_16x16x32_bf16 v[44:47], v[156:159], v[200:203], v[44:47]
	v_mfma_f32_16x16x32_bf16 v[40:43], v[164:167], v[200:203], v[40:43]
	v_mfma_f32_16x16x32_bf16 v[36:39], v[156:159], v[212:215], v[36:39]
	v_mfma_f32_16x16x32_bf16 v[32:35], v[164:167], v[212:215], v[32:35]
	v_mfma_f32_16x16x32_bf16 v[60:63], v[160:163], v[176:179], v[60:63]
	v_mfma_f32_16x16x32_bf16 v[56:59], v[168:171], v[176:179], v[56:59]
	v_mfma_f32_16x16x32_bf16 v[52:55], v[160:163], v[196:199], v[52:55]
	v_mfma_f32_16x16x32_bf16 v[48:51], v[168:171], v[196:199], v[48:51]
	v_mfma_f32_16x16x32_bf16 v[44:47], v[160:163], v[208:211], v[44:47]
	v_mfma_f32_16x16x32_bf16 v[40:43], v[168:171], v[208:211], v[40:43]
	v_mfma_f32_16x16x32_bf16 v[36:39], v[160:163], v[216:219], v[36:39]
	v_mfma_f32_16x16x32_bf16 v[32:35], v[168:171], v[216:219], v[32:35]
	v_mfma_f32_16x16x32_bf16 v[28:31], v[220:223], v[172:175], v[28:31]
	v_mfma_f32_16x16x32_bf16 v[24:27], v[228:231], v[172:175], v[24:27]
	v_mfma_f32_16x16x32_bf16 v[20:23], v[220:223], v[180:183], v[20:23]
	v_mfma_f32_16x16x32_bf16 v[16:19], v[228:231], v[180:183], v[16:19]
	v_mfma_f32_16x16x32_bf16 v[12:15], v[220:223], v[200:203], v[12:15]
	v_mfma_f32_16x16x32_bf16 v[8:11], v[228:231], v[200:203], v[8:11]
	v_mfma_f32_16x16x32_bf16 v[4:7], v[220:223], v[212:215], v[4:7]
	v_mfma_f32_16x16x32_bf16 v[0:3], v[228:231], v[212:215], v[0:3]
	v_mfma_f32_16x16x32_bf16 v[28:31], v[224:227], v[176:179], v[28:31]
	v_mfma_f32_16x16x32_bf16 v[24:27], v[232:235], v[176:179], v[24:27]
	v_mfma_f32_16x16x32_bf16 v[20:23], v[224:227], v[196:199], v[20:23]
	v_mfma_f32_16x16x32_bf16 v[16:19], v[232:235], v[196:199], v[16:19]
	v_mfma_f32_16x16x32_bf16 v[12:15], v[224:227], v[208:211], v[12:15]
	v_mfma_f32_16x16x32_bf16 v[8:11], v[232:235], v[208:211], v[8:11]
	v_mfma_f32_16x16x32_bf16 v[4:7], v[224:227], v[216:219], v[4:7]
	v_mfma_f32_16x16x32_bf16 v[0:3], v[232:235], v[216:219], v[0:3]
	v_or_b32_e32 v156, 0x18000, v145
	v_add_u32_e32 v158, 0x18100, v145
	s_barrier
; #define WAIT_V(n) asm volatile("s_waitcnt vmcnt(%0)" ::"n"(n) : "memory")
; #define WAIT_L(n) asm volatile("s_waitcnt lgkmcnt(%0)" ::"n"(n) : "memory")
; #define SBAR() __builtin_amdgcn_sched_barrier(0)
; #define STAGE(P, base, kt) do { _Pragma("unroll") for (int _i = 0; _i < 2; ++_i)                                        \
;       __builtin_amdgcn_global_load_lds((const unsigned*)((base) + (size_t)(sOff[_i] + (unsigned)(kt) * (BK * 2))),        \
;                                        (unsigned*)((P) + wid * 1024 + _i * 8192), 16, 0, 0); } while (0)
; #define LDA(dst, b, h) _Pragma("unroll") for (int m = 0; m < 4; ++m) _Pragma("unroll") for (int k = 0; k < 2; ++k) \
;       dst[m][k] = *(const bf16x8*)(SA(b, h) + aoff + (m * 2048 + k * 1024))
; #define LDB(dst, b, h) _Pragma("unroll") for (int n = 0; n < 2; ++n) _Pragma("unroll") for (int k = 0; k < 2; ++k) \
;       dst[n][k] = *(const bf16x8*)(SB(b, h) + boff + (n * 256 + k * 1024))
; #define BAR __builtin_amdgcn_s_barrier()
; template <int EPI, int N, int K>
; __device__ __forceinline__ void phase_gemm(const Params& p, const u16* __restrict__ A, const u16* __restrict__ Bt, int nM, char* shm,
;                            u16* __restrict__ outp, float* __restrict__ rowss) {
;     ...
;       LDB(B0, 1, 0); SBAR(); LDA(At, 1, 0); STAGE(SA(0, 1), A1, t + 2);
;       WAIT_L(8); BAR; WAIT_L(0); MMA(0, 0, At, B0); BAR; SBAR();
;       LDB(B1, 1, 1); STAGE(SB(1, 0), B0p, t + 3);
;       BAR; WAIT_L(0); MMA(0, 1, At, B1); BAR;
;       LDA(At, 1, 1); STAGE(SA(1, 0), A0, t + 3);
;       BAR; WAIT_L(0); MMA(1, 0, At, B0); BAR; SBAR();
;       STAGE(SB(1, 1), B1p, t + 3);
;       WAIT_V(6); BAR; MMA(1, 1, At, B1); BAR;
;     }
	v_add_u32_e32 v157, 0x18400, v145
	ds_read_b128 v[164:167], v156
	ds_read_b128 v[168:171], v157
	v_add_u32_e32 v159, 0x18500, v145
	ds_read_b128 v[172:175], v158
	ds_read_b128 v[176:179], v159
	s_mov_b32 m0, s29
	ds_read_b128 v[180:183], v146 offset:32768
	ds_read_b128 v[196:199], v146 offset:33792
	ds_read_b128 v[200:203], v146 offset:34816
	ds_read_b128 v[208:211], v146 offset:35840
	ds_read_b128 v[212:215], v146 offset:36864
	ds_read_b128 v[216:219], v146 offset:37888
	ds_read_b128 v[220:223], v146 offset:38912
	ds_read_b128 v[224:227], v146 offset:39936
	global_load_lds_dwordx4 v206, s[16:17]
	s_mov_b32 m0, s30
	s_nop 0
	global_load_lds_dwordx4 v207, s[16:17]
	v_or_b32_e32 v160, 0x1c000, v145
	v_add_u32_e32 v162, 0x1c100, v145
	v_add_u32_e32 v161, 0x1c400, v145
	ds_read_b128 v[228:231], v160
	ds_read_b128 v[232:235], v161
	v_add_u32_e32 v163, 0x1c500, v145
	ds_read_b128 v[236:239], v162
	ds_read_b128 v[240:243], v163
	s_waitcnt lgkmcnt(0)
	s_barrier
	v_mfma_f32_16x16x32_bf16 v[126:129], v[164:167], v[180:183], v[126:129]
	v_mfma_f32_16x16x32_bf16 v[122:125], v[172:175], v[180:183], v[122:125]
	v_mfma_f32_16x16x32_bf16 v[118:121], v[164:167], v[200:203], v[118:121]
	v_mfma_f32_16x16x32_bf16 v[114:117], v[172:175], v[200:203], v[114:117]
	v_mfma_f32_16x16x32_bf16 v[110:113], v[164:167], v[212:215], v[110:113]
	v_mfma_f32_16x16x32_bf16 v[106:109], v[172:175], v[212:215], v[106:109]
	v_mfma_f32_16x16x32_bf16 v[102:105], v[164:167], v[220:223], v[102:105]
	v_mfma_f32_16x16x32_bf16 v[98:101], v[172:175], v[220:223], v[98:101]
	v_mfma_f32_16x16x32_bf16 v[126:129], v[168:171], v[196:199], v[126:129]
	v_mfma_f32_16x16x32_bf16 v[122:125], v[176:179], v[196:199], v[122:125]
	v_mfma_f32_16x16x32_bf16 v[118:121], v[168:171], v[208:211], v[118:121]
	v_mfma_f32_16x16x32_bf16 v[114:117], v[176:179], v[208:211], v[114:117]
	v_mfma_f32_16x16x32_bf16 v[110:113], v[168:171], v[216:219], v[110:113]
	v_mfma_f32_16x16x32_bf16 v[106:109], v[176:179], v[216:219], v[106:109]
	v_mfma_f32_16x16x32_bf16 v[102:105], v[168:171], v[224:227], v[102:105]
	v_mfma_f32_16x16x32_bf16 v[98:101], v[176:179], v[224:227], v[98:101]
	v_mfma_f32_16x16x32_bf16 v[92:95], v[228:231], v[180:183], v[92:95]
	v_mfma_f32_16x16x32_bf16 v[88:91], v[236:239], v[180:183], v[88:91]
	v_mfma_f32_16x16x32_bf16 v[84:87], v[228:231], v[200:203], v[84:87]
	v_mfma_f32_16x16x32_bf16 v[80:83], v[236:239], v[200:203], v[80:83]
	v_mfma_f32_16x16x32_bf16 v[76:79], v[228:231], v[212:215], v[76:79]
	v_mfma_f32_16x16x32_bf16 v[72:75], v[236:239], v[212:215], v[72:75]
	v_mfma_f32_16x16x32_bf16 v[68:71], v[228:231], v[220:223], v[68:71]
	v_mfma_f32_16x16x32_bf16 v[64:67], v[236:239], v[220:223], v[64:67]
	v_mfma_f32_16x16x32_bf16 v[92:95], v[232:235], v[196:199], v[92:95]
	v_mfma_f32_16x16x32_bf16 v[88:91], v[240:243], v[196:199], v[88:91]
	v_mfma_f32_16x16x32_bf16 v[84:87], v[232:235], v[208:211], v[84:87]
	v_mfma_f32_16x16x32_bf16 v[80:83], v[240:243], v[208:211], v[80:83]
	v_mfma_f32_16x16x32_bf16 v[76:79], v[232:235], v[216:219], v[76:79]
	v_mfma_f32_16x16x32_bf16 v[72:75], v[240:243], v[216:219], v[72:75]
	v_mfma_f32_16x16x32_bf16 v[68:71], v[232:235], v[224:227], v[68:71]
	v_mfma_f32_16x16x32_bf16 v[64:67], v[240:243], v[224:227], v[64:67]
	s_barrier
	ds_read_b128 v[180:183], v146 offset:49152
	ds_read_b128 v[196:199], v146 offset:50176
	ds_read_b128 v[200:203], v146 offset:51200
	ds_read_b128 v[208:211], v146 offset:52224
	ds_read_b128 v[212:215], v146 offset:53248
	ds_read_b128 v[216:219], v146 offset:54272
	ds_read_b128 v[220:223], v146 offset:55296
	ds_read_b128 v[224:227], v146 offset:56320
	s_mov_b32 m0, s31
	v_add_u32_e32 v204, 0x180, v204
	global_load_lds_dwordx4 v204, s[8:9]
	v_add_u32_e32 v205, 0x180, v205
	s_mov_b32 m0, s33
	s_nop 0
	global_load_lds_dwordx4 v205, s[8:9]
	s_mov_b32 m0, s35
	s_nop 0
	global_load_lds_dwordx4 v204, s[10:11]
	s_mov_b32 m0, s52
	s_nop 0
	global_load_lds_dwordx4 v205, s[10:11]
	s_mov_b32 m0, s53
	s_nop 0
	global_load_lds_dwordx4 v204, s[18:19]
	s_mov_b32 m0, s54
	s_nop 0
	global_load_lds_dwordx4 v205, s[18:19]
	s_waitcnt vmcnt(6)
	s_waitcnt lgkmcnt(0)
	s_barrier
	v_mfma_f32_16x16x32_bf16 v[60:63], v[164:167], v[180:183], v[60:63]
	v_mfma_f32_16x16x32_bf16 v[56:59], v[172:175], v[180:183], v[56:59]
	v_mfma_f32_16x16x32_bf16 v[52:55], v[164:167], v[200:203], v[52:55]
	v_mfma_f32_16x16x32_bf16 v[48:51], v[172:175], v[200:203], v[48:51]
	v_mfma_f32_16x16x32_bf16 v[44:47], v[164:167], v[212:215], v[44:47]
	v_mfma_f32_16x16x32_bf16 v[40:43], v[172:175], v[212:215], v[40:43]
	v_mfma_f32_16x16x32_bf16 v[36:39], v[164:167], v[220:223], v[36:39]
	v_mfma_f32_16x16x32_bf16 v[32:35], v[172:175], v[220:223], v[32:35]
	v_mfma_f32_16x16x32_bf16 v[60:63], v[168:171], v[196:199], v[60:63]
	v_mfma_f32_16x16x32_bf16 v[56:59], v[176:179], v[196:199], v[56:59]
	v_mfma_f32_16x16x32_bf16 v[52:55], v[168:171], v[208:211], v[52:55]
	v_mfma_f32_16x16x32_bf16 v[48:51], v[176:179], v[208:211], v[48:51]
	v_mfma_f32_16x16x32_bf16 v[44:47], v[168:171], v[216:219], v[44:47]
	v_mfma_f32_16x16x32_bf16 v[40:43], v[176:179], v[216:219], v[40:43]
	v_mfma_f32_16x16x32_bf16 v[36:39], v[168:171], v[224:227], v[36:39]
	v_mfma_f32_16x16x32_bf16 v[32:35], v[176:179], v[224:227], v[32:35]
	v_mfma_f32_16x16x32_bf16 v[28:31], v[228:231], v[180:183], v[28:31]
	v_mfma_f32_16x16x32_bf16 v[24:27], v[236:239], v[180:183], v[24:27]
	v_mfma_f32_16x16x32_bf16 v[20:23], v[228:231], v[200:203], v[20:23]
	v_mfma_f32_16x16x32_bf16 v[16:19], v[236:239], v[200:203], v[16:19]
	v_mfma_f32_16x16x32_bf16 v[12:15], v[228:231], v[212:215], v[12:15]
	v_mfma_f32_16x16x32_bf16 v[8:11], v[236:239], v[212:215], v[8:11]
	v_mfma_f32_16x16x32_bf16 v[4:7], v[228:231], v[220:223], v[4:7]
	v_mfma_f32_16x16x32_bf16 v[0:3], v[236:239], v[220:223], v[0:3]
	v_mfma_f32_16x16x32_bf16 v[28:31], v[232:235], v[196:199], v[28:31]
	v_mfma_f32_16x16x32_bf16 v[24:27], v[240:243], v[196:199], v[24:27]
	v_mfma_f32_16x16x32_bf16 v[20:23], v[232:235], v[208:211], v[20:23]
	v_mfma_f32_16x16x32_bf16 v[16:19], v[240:243], v[208:211], v[16:19]
	v_mfma_f32_16x16x32_bf16 v[12:15], v[232:235], v[216:219], v[12:15]
	v_mfma_f32_16x16x32_bf16 v[8:11], v[240:243], v[216:219], v[8:11]
	v_mfma_f32_16x16x32_bf16 v[4:7], v[232:235], v[224:227], v[4:7]
	v_mfma_f32_16x16x32_bf16 v[0:3], v[240:243], v[224:227], v[0:3]
	s_add_i32 s22, s22, 2
	v_add_u32_e32 v142, 0x100, v142
	s_cmp_lt_u32 s22, 12
	v_add_u32_e32 v96, 0x100, v96
	s_barrier
; #define WAIT_V(n) asm volatile("s_waitcnt vmcnt(%0)" ::"n"(n) : "memory")
; #define WAIT_L(n) asm volatile("s_waitcnt lgkmcnt(%0)" ::"n"(n) : "memory")
; #define STAGE(P, base, kt) do { _Pragma("unroll") for (int _i = 0; _i < 2; ++_i)                                        \
;       __builtin_amdgcn_global_load_lds((const unsigned*)((base) + (size_t)(sOff[_i] + (unsigned)(kt) * (BK * 2))),        \
;                                        (unsigned*)((P) + wid * 1024 + _i * 8192), 16, 0, 0); } while (0)
; #define LDA(dst, b, h) _Pragma("unroll") for (int m = 0; m < 4; ++m) _Pragma("unroll") for (int k = 0; k < 2; ++k) \
;       dst[m][k] = *(const bf16x8*)(SA(b, h) + aoff + (m * 2048 + k * 1024))
; #define LDB(dst, b, h) _Pragma("unroll") for (int n = 0; n < 2; ++n) _Pragma("unroll") for (int k = 0; k < 2; ++k) \
;       dst[n][k] = *(const bf16x8*)(SB(b, h) + boff + (n * 256 + k * 1024))
; #define BAR __builtin_amdgcn_s_barrier()
; template <int EPI, int N, int K>
; __device__ __forceinline__ void phase_gemm(const Params& p, const u16* __restrict__ A, const u16* __restrict__ Bt, int nM, char* shm,
;                            u16* __restrict__ outp, float* __restrict__ rowss) {
;     ...
;     }
;     { LDB(B0, 0, 0); LDA(At, 0, 0); STAGE(SA(1, 1), A1, nt - 1);
;       BAR; WAIT_L(0); MMA(0, 0, At, B0); BAR;
;       LDB(B1, 0, 1); BAR; WAIT_L(0); MMA(0, 1, At, B1); BAR;
;       LDA(At, 0, 1); WAIT_V(4); BAR; WAIT_L(0); MMA(1, 0, At, B0); MMA(1, 1, At, B1); BAR; }
	s_cbranch_scc1 .LBB0_433
	s_mov_b32 m0, s62
	ds_read_b128 v[164:167], v143
	ds_read_b128 v[168:171], v149
	ds_read_b128 v[172:175], v150
	ds_read_b128 v[176:179], v151
	ds_read_b128 v[180:183], v146
	ds_read_b128 v[196:199], v146 offset:1024
	ds_read_b128 v[200:203], v146 offset:2048
	ds_read_b128 v[208:211], v146 offset:3072
	ds_read_b128 v[212:215], v146 offset:4096
	ds_read_b128 v[216:219], v146 offset:5120
	ds_read_b128 v[220:223], v146 offset:6144
	ds_read_b128 v[224:227], v146 offset:7168
	v_lshl_add_u64 v[142:143], s[16:17], 0, v[138:139]
	global_load_lds_dwordx4 v[142:143], off
	v_lshl_add_u64 v[142:143], s[16:17], 0, v[140:141]
	s_mov_b32 m0, s23
	s_nop 0
	global_load_lds_dwordx4 v[142:143], off
	s_barrier
	s_waitcnt lgkmcnt(0)
	s_waitcnt lgkmcnt(0)
	v_mfma_f32_16x16x32_bf16 v[126:129], v[164:167], v[180:183], v[126:129]
	v_mfma_f32_16x16x32_bf16 v[122:125], v[172:175], v[180:183], v[122:125]
	v_mfma_f32_16x16x32_bf16 v[110:113], v[164:167], v[212:215], v[110:113]
	v_mfma_f32_16x16x32_bf16 v[106:109], v[172:175], v[212:215], v[106:109]
	v_mfma_f32_16x16x32_bf16 v[126:129], v[168:171], v[196:199], v[126:129]
	v_mfma_f32_16x16x32_bf16 v[122:125], v[176:179], v[196:199], v[122:125]
	v_mfma_f32_16x16x32_bf16 v[118:121], v[164:167], v[200:203], v[118:121]
	v_mfma_f32_16x16x32_bf16 v[114:117], v[172:175], v[200:203], v[114:117]
	v_mfma_f32_16x16x32_bf16 v[110:113], v[168:171], v[216:219], v[110:113]
	v_mfma_f32_16x16x32_bf16 v[106:109], v[176:179], v[216:219], v[106:109]
	v_mfma_f32_16x16x32_bf16 v[102:105], v[164:167], v[220:223], v[102:105]
	v_mfma_f32_16x16x32_bf16 v[98:101], v[172:175], v[220:223], v[98:101]
	v_mfma_f32_16x16x32_bf16 v[228:231], v[168:171], v[208:211], v[118:121]
	v_mfma_f32_16x16x32_bf16 v[232:235], v[176:179], v[208:211], v[114:117]
	v_mfma_f32_16x16x32_bf16 v[236:239], v[168:171], v[224:227], v[102:105]
	v_mfma_f32_16x16x32_bf16 v[240:243], v[176:179], v[224:227], v[98:101]
	s_barrier
	s_nop 1
	ds_read_b128 v[98:101], v152
	ds_read_b128 v[102:105], v153
	ds_read_b128 v[114:117], v154
	ds_read_b128 v[118:121], v155
	s_barrier
	s_waitcnt lgkmcnt(0)
	s_waitcnt lgkmcnt(0)
	v_mfma_f32_16x16x32_bf16 v[92:95], v[98:101], v[180:183], v[92:95]
	v_mfma_f32_16x16x32_bf16 v[88:91], v[114:117], v[180:183], v[88:91]
	v_mfma_f32_16x16x32_bf16 v[76:79], v[98:101], v[212:215], v[76:79]
	v_mfma_f32_16x16x32_bf16 v[72:75], v[114:117], v[212:215], v[72:75]
	v_mfma_f32_16x16x32_bf16 v[68:71], v[98:101], v[220:223], v[68:71]
	v_mfma_f32_16x16x32_bf16 v[64:67], v[114:117], v[220:223], v[64:67]
	v_mfma_f32_16x16x32_bf16 v[92:95], v[102:105], v[196:199], v[92:95]
	v_mfma_f32_16x16x32_bf16 v[88:91], v[118:121], v[196:199], v[88:91]
	v_mfma_f32_16x16x32_bf16 v[84:87], v[98:101], v[200:203], v[84:87]
	v_mfma_f32_16x16x32_bf16 v[80:83], v[114:117], v[200:203], v[80:83]
	v_mfma_f32_16x16x32_bf16 v[76:79], v[102:105], v[216:219], v[76:79]
	v_mfma_f32_16x16x32_bf16 v[72:75], v[118:121], v[216:219], v[72:75]
	v_mfma_f32_16x16x32_bf16 v[68:71], v[102:105], v[224:227], v[68:71]
	v_mfma_f32_16x16x32_bf16 v[64:67], v[118:121], v[224:227], v[64:67]
	v_mfma_f32_16x16x32_bf16 v[150:153], v[102:105], v[208:211], v[84:87]
	v_mfma_f32_16x16x32_bf16 v[180:183], v[118:121], v[208:211], v[80:83]
	s_barrier
	s_nop 0
	ds_read_b128 v[80:83], v146 offset:16384
	ds_read_b128 v[84:87], v146 offset:17408
	ds_read_b128 v[196:199], v146 offset:18432
	ds_read_b128 v[200:203], v146 offset:19456
	ds_read_b128 v[208:211], v146 offset:20480
	ds_read_b128 v[212:215], v146 offset:21504
	ds_read_b128 v[216:219], v146 offset:22528
	ds_read_b128 v[220:223], v146 offset:23552
	s_waitcnt vmcnt(4)
	s_barrier
	s_waitcnt lgkmcnt(0)
	s_waitcnt lgkmcnt(0)
	v_mfma_f32_16x16x32_bf16 v[56:59], v[172:175], v[80:83], v[56:59]
	v_mfma_f32_16x16x32_bf16 v[52:55], v[164:167], v[196:199], v[52:55]
	v_mfma_f32_16x16x32_bf16 v[40:43], v[172:175], v[208:211], v[40:43]
	v_mfma_f32_16x16x32_bf16 v[32:35], v[172:175], v[216:219], v[32:35]
	v_mfma_f32_16x16x32_bf16 v[60:63], v[164:167], v[80:83], v[60:63]
	v_mfma_f32_16x16x32_bf16 v[56:59], v[176:179], v[84:87], v[56:59]
	v_mfma_f32_16x16x32_bf16 v[52:55], v[168:171], v[200:203], v[52:55]
	v_mfma_f32_16x16x32_bf16 v[48:51], v[172:175], v[196:199], v[48:51]
	v_mfma_f32_16x16x32_bf16 v[44:47], v[164:167], v[208:211], v[44:47]
	v_mfma_f32_16x16x32_bf16 v[40:43], v[176:179], v[212:215], v[40:43]
	v_mfma_f32_16x16x32_bf16 v[36:39], v[164:167], v[216:219], v[36:39]
	v_mfma_f32_16x16x32_bf16 v[32:35], v[176:179], v[220:223], v[32:35]
	v_mfma_f32_16x16x32_bf16 v[224:227], v[168:171], v[84:87], v[60:63]
	v_mfma_f32_16x16x32_bf16 v[244:247], v[176:179], v[200:203], v[48:51]
	v_mfma_f32_16x16x32_bf16 v[248:251], v[168:171], v[212:215], v[44:47]
	v_mfma_f32_16x16x32_bf16 v[164:167], v[168:171], v[220:223], v[36:39]
	v_mfma_f32_16x16x32_bf16 v[24:27], v[114:117], v[80:83], v[24:27]
	v_mfma_f32_16x16x32_bf16 v[16:19], v[114:117], v[196:199], v[16:19]
	v_mfma_f32_16x16x32_bf16 v[8:11], v[114:117], v[208:211], v[8:11]
	v_mfma_f32_16x16x32_bf16 v[0:3], v[114:117], v[216:219], v[0:3]
	v_mfma_f32_16x16x32_bf16 v[28:31], v[98:101], v[80:83], v[28:31]
	v_mfma_f32_16x16x32_bf16 v[24:27], v[118:121], v[84:87], v[24:27]
	v_mfma_f32_16x16x32_bf16 v[20:23], v[98:101], v[196:199], v[20:23]
	v_mfma_f32_16x16x32_bf16 v[16:19], v[118:121], v[200:203], v[16:19]
	v_mfma_f32_16x16x32_bf16 v[12:15], v[98:101], v[208:211], v[12:15]
	v_mfma_f32_16x16x32_bf16 v[8:11], v[118:121], v[212:215], v[8:11]
	v_mfma_f32_16x16x32_bf16 v[4:7], v[98:101], v[216:219], v[4:7]
	v_mfma_f32_16x16x32_bf16 v[0:3], v[118:121], v[220:223], v[0:3]
	v_mfma_f32_16x16x32_bf16 v[168:171], v[102:105], v[84:87], v[28:31]
	v_mfma_f32_16x16x32_bf16 v[172:175], v[102:105], v[200:203], v[20:23]
	v_mfma_f32_16x16x32_bf16 v[176:179], v[102:105], v[212:215], v[12:15]
	v_mfma_f32_16x16x32_bf16 v[196:199], v[102:105], v[220:223], v[4:7]
	s_barrier
; #define WAIT_V(n) asm volatile("s_waitcnt vmcnt(%0)" ::"n"(n) : "memory")
; #define WAIT_L(n) asm volatile("s_waitcnt lgkmcnt(%0)" ::"n"(n) : "memory")
; #define LDA(dst, b, h) _Pragma("unroll") for (int m = 0; m < 4; ++m) _Pragma("unroll") for (int k = 0; k < 2; ++k) \
;       dst[m][k] = *(const bf16x8*)(SA(b, h) + aoff + (m * 2048 + k * 1024))
; #define LDB(dst, b, h) _Pragma("unroll") for (int n = 0; n < 2; ++n) _Pragma("unroll") for (int k = 0; k < 2; ++k) \
;       dst[n][k] = *(const bf16x8*)(SB(b, h) + boff + (n * 256 + k * 1024))
; #define BAR __builtin_amdgcn_s_barrier()
; template <int EPI, int N, int K>
; __device__ __forceinline__ void phase_gemm(const Params& p, const u16* __restrict__ A, const u16* __restrict__ Bt, int nM, char* shm,
;                            u16* __restrict__ outp, float* __restrict__ rowss) {
;     ...
;     { LDB(B0, 1, 0); LDA(At, 1, 0); WAIT_V(2); BAR; WAIT_L(0); MMA(0, 0, At, B0); BAR;
;       LDB(B1, 1, 1); WAIT_V(0); BAR; WAIT_L(0); MMA(0, 1, At, B1); BAR;
;       LDA(At, 1, 1); BAR; WAIT_L(0); MMA(1, 0, At, B0); MMA(1, 1, At, B1); BAR; }
;     if (wr == 0) BAR;
	s_nop 0
	ds_read_b128 v[4:7], v156
	ds_read_b128 v[12:15], v157
	ds_read_b128 v[154:157], v158
	ds_read_b128 v[200:203], v159
	ds_read_b128 v[20:23], v146 offset:32768
	ds_read_b128 v[28:31], v146 offset:33792
	ds_read_b128 v[36:39], v146 offset:34816
	ds_read_b128 v[44:47], v146 offset:35840
	ds_read_b128 v[208:211], v146 offset:36864
	ds_read_b128 v[212:215], v146 offset:37888
	ds_read_b128 v[216:219], v146 offset:38912
	ds_read_b128 v[220:223], v146 offset:39936
	s_waitcnt vmcnt(2)
	s_barrier
	s_waitcnt lgkmcnt(0)
	s_waitcnt lgkmcnt(0)
	v_mfma_f32_16x16x32_bf16 v[48:51], v[4:7], v[20:23], v[126:129]
	v_mfma_f32_16x16x32_bf16 v[118:121], v[12:15], v[28:31], v[48:51]
	v_mfma_f32_16x16x32_bf16 v[48:51], v[154:157], v[20:23], v[122:125]
	v_mfma_f32_16x16x32_bf16 v[114:117], v[200:203], v[28:31], v[48:51]
	v_mfma_f32_16x16x32_bf16 v[48:51], v[4:7], v[36:39], v[228:231]
	v_mfma_f32_16x16x32_bf16 v[102:105], v[12:15], v[44:47], v[48:51]
	v_mfma_f32_16x16x32_bf16 v[48:51], v[154:157], v[36:39], v[232:235]
	v_mfma_f32_16x16x32_bf16 v[98:101], v[200:203], v[44:47], v[48:51]
	v_mfma_f32_16x16x32_bf16 v[48:51], v[4:7], v[208:211], v[110:113]
	v_mfma_f32_16x16x32_bf16 v[84:87], v[12:15], v[212:215], v[48:51]
	v_mfma_f32_16x16x32_bf16 v[48:51], v[154:157], v[208:211], v[106:109]
	v_mfma_f32_16x16x32_bf16 v[80:83], v[200:203], v[212:215], v[48:51]
	v_mfma_f32_16x16x32_bf16 v[48:51], v[4:7], v[216:219], v[236:239]
	v_mfma_f32_16x16x32_bf16 v[60:63], v[12:15], v[220:223], v[48:51]
	v_mfma_f32_16x16x32_bf16 v[48:51], v[154:157], v[216:219], v[240:243]
	v_mfma_f32_16x16x32_bf16 v[48:51], v[200:203], v[220:223], v[48:51]
	s_barrier
	ds_read_b128 v[228:231], v160
	ds_read_b128 v[158:161], v161
	ds_read_b128 v[232:235], v162
	ds_read_b128 v[236:239], v163
	s_waitcnt vmcnt(0)
	s_barrier
	s_waitcnt lgkmcnt(0)
	s_waitcnt lgkmcnt(0)
	v_mfma_f32_16x16x32_bf16 v[92:95], v[228:231], v[20:23], v[92:95]
	v_mfma_f32_16x16x32_bf16 v[20:23], v[232:235], v[20:23], v[88:91]
	v_mfma_f32_16x16x32_bf16 v[122:125], v[236:239], v[28:31], v[20:23]
	v_mfma_f32_16x16x32_bf16 v[20:23], v[228:231], v[36:39], v[150:153]
	v_mfma_f32_16x16x32_bf16 v[110:113], v[158:161], v[44:47], v[20:23]
	v_mfma_f32_16x16x32_bf16 v[20:23], v[232:235], v[36:39], v[180:183]
	v_mfma_f32_16x16x32_bf16 v[106:109], v[236:239], v[44:47], v[20:23]
	v_mfma_f32_16x16x32_bf16 v[20:23], v[228:231], v[208:211], v[76:79]
	v_mfma_f32_16x16x32_bf16 v[126:129], v[158:161], v[28:31], v[92:95]
	v_mfma_f32_16x16x32_bf16 v[92:95], v[158:161], v[212:215], v[20:23]
	v_mfma_f32_16x16x32_bf16 v[20:23], v[232:235], v[208:211], v[72:75]
	v_mfma_f32_16x16x32_bf16 v[88:91], v[236:239], v[212:215], v[20:23]
	v_mfma_f32_16x16x32_bf16 v[20:23], v[228:231], v[216:219], v[68:71]
	v_mfma_f32_16x16x32_bf16 v[76:79], v[158:161], v[220:223], v[20:23]
	v_mfma_f32_16x16x32_bf16 v[20:23], v[232:235], v[216:219], v[64:67]
	v_mfma_f32_16x16x32_bf16 v[64:67], v[236:239], v[220:223], v[20:23]
	s_barrier
	ds_read_b128 v[150:153], v146 offset:49152
	ds_read_b128 v[180:183], v146 offset:50176
	ds_read_b128 v[208:211], v146 offset:51200
	ds_read_b128 v[212:215], v146 offset:52224
	ds_read_b128 v[216:219], v146 offset:53248
	ds_read_b128 v[220:223], v146 offset:54272
	ds_read_b128 v[240:243], v146 offset:55296
	ds_read_b128 v[204:207], v146 offset:56320
	s_barrier
	s_waitcnt lgkmcnt(0)
	s_waitcnt lgkmcnt(0)
	v_mfma_f32_16x16x32_bf16 v[20:23], v[4:7], v[150:153], v[224:227]
	v_mfma_f32_16x16x32_bf16 v[72:75], v[12:15], v[180:183], v[20:23]
	v_mfma_f32_16x16x32_bf16 v[20:23], v[154:157], v[150:153], v[56:59]
	v_mfma_f32_16x16x32_bf16 v[56:59], v[200:203], v[180:183], v[20:23]
	v_mfma_f32_16x16x32_bf16 v[20:23], v[4:7], v[208:211], v[52:55]
	v_mfma_f32_16x16x32_bf16 v[44:47], v[12:15], v[212:215], v[20:23]
	v_mfma_f32_16x16x32_bf16 v[20:23], v[154:157], v[208:211], v[244:247]
	v_mfma_f32_16x16x32_bf16 v[36:39], v[200:203], v[212:215], v[20:23]
	v_mfma_f32_16x16x32_bf16 v[20:23], v[4:7], v[216:219], v[248:251]
	v_mfma_f32_16x16x32_bf16 v[4:7], v[4:7], v[240:243], v[164:167]
	v_mfma_f32_16x16x32_bf16 v[28:31], v[12:15], v[220:223], v[20:23]
	v_mfma_f32_16x16x32_bf16 v[20:23], v[154:157], v[216:219], v[40:43]
	v_mfma_f32_16x16x32_bf16 v[12:15], v[12:15], v[204:207], v[4:7]
	v_mfma_f32_16x16x32_bf16 v[4:7], v[154:157], v[240:243], v[32:35]
	v_mfma_f32_16x16x32_bf16 v[20:23], v[200:203], v[220:223], v[20:23]
	v_mfma_f32_16x16x32_bf16 v[4:7], v[200:203], v[204:207], v[4:7]
	v_mfma_f32_16x16x32_bf16 v[32:35], v[228:231], v[150:153], v[168:171]
	v_mfma_f32_16x16x32_bf16 v[24:27], v[232:235], v[150:153], v[24:27]
	v_mfma_f32_16x16x32_bf16 v[16:19], v[232:235], v[208:211], v[16:19]
	v_mfma_f32_16x16x32_bf16 v[68:71], v[158:161], v[180:183], v[32:35]
	v_mfma_f32_16x16x32_bf16 v[52:55], v[236:239], v[180:183], v[24:27]
	v_mfma_f32_16x16x32_bf16 v[24:27], v[228:231], v[208:211], v[172:175]
	v_mfma_f32_16x16x32_bf16 v[32:35], v[236:239], v[212:215], v[16:19]
	v_mfma_f32_16x16x32_bf16 v[16:19], v[228:231], v[216:219], v[176:179]
	v_mfma_f32_16x16x32_bf16 v[8:11], v[232:235], v[216:219], v[8:11]
	v_mfma_f32_16x16x32_bf16 v[40:43], v[158:161], v[212:215], v[24:27]
	v_mfma_f32_16x16x32_bf16 v[24:27], v[158:161], v[220:223], v[16:19]
	v_mfma_f32_16x16x32_bf16 v[16:19], v[236:239], v[220:223], v[8:11]
	v_mfma_f32_16x16x32_bf16 v[8:11], v[228:231], v[240:243], v[196:199]
	v_mfma_f32_16x16x32_bf16 v[0:3], v[232:235], v[240:243], v[0:3]
	v_mfma_f32_16x16x32_bf16 v[8:11], v[158:161], v[204:207], v[8:11]
	v_mfma_f32_16x16x32_bf16 v[0:3], v[236:239], v[204:207], v[0:3]
	s_andn2_b64 vcc, exec, s[56:57]
	s_barrier
	s_cbranch_vccnz .LBB0_436
	s_barrier

; #define WAIT_V(n) asm volatile("s_waitcnt vmcnt(%0)" ::"n"(n) : "memory")
; #define WAIT_L(n) asm volatile("s_waitcnt lgkmcnt(%0)" ::"n"(n) : "memory")
; #define SBAR() __builtin_amdgcn_sched_barrier(0)
; #define STAGE(P, base, kt) do { _Pragma("unroll") for (int _i = 0; _i < 2; ++_i)                                        \
;       __builtin_amdgcn_global_load_lds((const unsigned*)((base) + (size_t)(sOff[_i] + (unsigned)(kt) * (BK * 2))),        \
;                                        (unsigned*)((P) + wid * 1024 + _i * 8192), 16, 0, 0); } while (0)
; #define LDA(dst, b, h) _Pragma("unroll") for (int m = 0; m < 4; ++m) _Pragma("unroll") for (int k = 0; k < 2; ++k) \
;       dst[m][k] = *(const bf16x8*)(SA(b, h) + aoff + (m * 2048 + k * 1024))
; #define LDB(dst, b, h) _Pragma("unroll") for (int n = 0; n < 2; ++n) _Pragma("unroll") for (int k = 0; k < 2; ++k) \
;       dst[n][k] = *(const bf16x8*)(SB(b, h) + boff + (n * 256 + k * 1024))
; #define BAR __builtin_amdgcn_s_barrier()
; template <int EPI, int N, int K>
; __device__ __forceinline__ void phase_gemm(const Params& p, const u16* __restrict__ A, const u16* __restrict__ Bt, int nM, char* shm,
;                            u16* __restrict__ outp, float* __restrict__ rowss) {
;     ...
;     for (int t = 0; t < nt - 2; t += 2) {
;       LDB(B0, 0, 0); SBAR(); LDA(At, 0, 0); STAGE(SA(1, 1), A1, t + 1);
;       WAIT_L(8); BAR; WAIT_L(0); MMA(0, 0, At, B0); BAR; SBAR();
;       LDB(B1, 0, 1); STAGE(SB(0, 0), B0p, t + 2);
;       BAR; WAIT_L(0); MMA(0, 1, At, B1); BAR;
;       LDA(At, 0, 1); STAGE(SA(0, 0), A0, t + 2);
;       BAR; WAIT_L(0); MMA(1, 0, At, B0); BAR; SBAR();
;       STAGE(SB(0, 1), B1p, t + 2);
;       WAIT_V(6); BAR; MMA(1, 1, At, B1); BAR;
.LBB0_517:
	v_or_b32_e32 v143, 0x10000, v146
	v_add_u32_e32 v145, 0x10100, v146
	v_add_u32_e32 v144, 0x10400, v146
	ds_read_b128 v[156:159], v143
	ds_read_b128 v[160:163], v144
	v_add_u32_e32 v151, 0x10500, v146
	ds_read_b128 v[164:167], v145
	ds_read_b128 v[168:171], v151
	v_add_u32_e32 v204, v148, v96
	s_add_i32 s60, s25, 0xc000
	v_add_u32_e32 v152, 0x80, v204
	s_mov_b32 m0, s60
	v_add_u32_e32 v205, v148, v142
	s_add_i32 s59, s25, 0xe000
	ds_read_b128 v[172:175], v147
	ds_read_b128 v[176:179], v147 offset:1024
	ds_read_b128 v[180:183], v147 offset:2048
	ds_read_b128 v[196:199], v147 offset:3072
	ds_read_b128 v[200:203], v147 offset:4096
	ds_read_b128 v[208:211], v147 offset:5120
	ds_read_b128 v[212:215], v147 offset:6144
	ds_read_b128 v[216:219], v147 offset:7168
	global_load_lds_dwordx4 v152, s[4:5]
	v_add_u32_e32 v152, 0x80, v205
	s_mov_b32 m0, s59
	s_nop 0
	global_load_lds_dwordx4 v152, s[4:5]
	v_or_b32_e32 v152, 0x14000, v146
	v_add_u32_e32 v154, 0x14100, v146
	v_add_u32_e32 v153, 0x14400, v146
	ds_read_b128 v[220:223], v152
	ds_read_b128 v[224:227], v153
	v_add_u32_e32 v155, 0x14500, v146
	ds_read_b128 v[228:231], v154
	ds_read_b128 v[232:235], v155
	s_waitcnt lgkmcnt(0)
	s_barrier
	v_mfma_f32_16x16x32_bf16 v[126:129], v[156:159], v[172:175], v[126:129]
	v_mfma_f32_16x16x32_bf16 v[122:125], v[164:167], v[172:175], v[122:125]
	v_mfma_f32_16x16x32_bf16 v[118:121], v[156:159], v[180:183], v[118:121]
	v_mfma_f32_16x16x32_bf16 v[114:117], v[164:167], v[180:183], v[114:117]
	v_mfma_f32_16x16x32_bf16 v[110:113], v[156:159], v[200:203], v[110:113]
	v_mfma_f32_16x16x32_bf16 v[106:109], v[164:167], v[200:203], v[106:109]
	v_mfma_f32_16x16x32_bf16 v[102:105], v[156:159], v[212:215], v[102:105]
	v_mfma_f32_16x16x32_bf16 v[98:101], v[164:167], v[212:215], v[98:101]
	v_mfma_f32_16x16x32_bf16 v[126:129], v[160:163], v[176:179], v[126:129]
	v_mfma_f32_16x16x32_bf16 v[122:125], v[168:171], v[176:179], v[122:125]
	v_mfma_f32_16x16x32_bf16 v[118:121], v[160:163], v[196:199], v[118:121]
	v_mfma_f32_16x16x32_bf16 v[114:117], v[168:171], v[196:199], v[114:117]
	v_mfma_f32_16x16x32_bf16 v[110:113], v[160:163], v[208:211], v[110:113]
	v_mfma_f32_16x16x32_bf16 v[106:109], v[168:171], v[208:211], v[106:109]
	v_mfma_f32_16x16x32_bf16 v[102:105], v[160:163], v[216:219], v[102:105]
	v_mfma_f32_16x16x32_bf16 v[98:101], v[168:171], v[216:219], v[98:101]
	v_mfma_f32_16x16x32_bf16 v[92:95], v[220:223], v[172:175], v[92:95]
	v_mfma_f32_16x16x32_bf16 v[88:91], v[228:231], v[172:175], v[88:91]
	v_mfma_f32_16x16x32_bf16 v[84:87], v[220:223], v[180:183], v[84:87]
	v_mfma_f32_16x16x32_bf16 v[80:83], v[228:231], v[180:183], v[80:83]
	v_mfma_f32_16x16x32_bf16 v[76:79], v[220:223], v[200:203], v[76:79]
	v_mfma_f32_16x16x32_bf16 v[72:75], v[228:231], v[200:203], v[72:75]
	v_mfma_f32_16x16x32_bf16 v[68:71], v[220:223], v[212:215], v[68:71]
	v_mfma_f32_16x16x32_bf16 v[64:67], v[228:231], v[212:215], v[64:67]
	v_mfma_f32_16x16x32_bf16 v[92:95], v[224:227], v[176:179], v[92:95]
	v_mfma_f32_16x16x32_bf16 v[88:91], v[232:235], v[176:179], v[88:91]
	v_mfma_f32_16x16x32_bf16 v[84:87], v[224:227], v[196:199], v[84:87]
	v_mfma_f32_16x16x32_bf16 v[80:83], v[232:235], v[196:199], v[80:83]
	v_mfma_f32_16x16x32_bf16 v[76:79], v[224:227], v[208:211], v[76:79]
	v_mfma_f32_16x16x32_bf16 v[72:75], v[232:235], v[208:211], v[72:75]
	v_mfma_f32_16x16x32_bf16 v[68:71], v[224:227], v[216:219], v[68:71]
	v_mfma_f32_16x16x32_bf16 v[64:67], v[232:235], v[216:219], v[64:67]
	s_barrier
	ds_read_b128 v[172:175], v147 offset:16384
	ds_read_b128 v[176:179], v147 offset:17408
	ds_read_b128 v[180:183], v147 offset:18432
	ds_read_b128 v[196:199], v147 offset:19456
	ds_read_b128 v[200:203], v147 offset:20480
	ds_read_b128 v[208:211], v147 offset:21504
	ds_read_b128 v[212:215], v147 offset:22528
	ds_read_b128 v[216:219], v147 offset:23552
	s_mov_b32 m0, s28
	v_add_u32_e32 v206, 0x100, v204
	global_load_lds_dwordx4 v206, s[10:11]
	v_add_u32_e32 v207, 0x100, v205
	s_mov_b32 m0, s29
	s_nop 0
	global_load_lds_dwordx4 v207, s[10:11]
	s_mov_b32 m0, s25
	s_nop 0
	global_load_lds_dwordx4 v206, s[12:13]
	s_mov_b32 m0, s26
	s_nop 0
	global_load_lds_dwordx4 v207, s[12:13]
	s_mov_b32 m0, s30
	s_nop 0
	global_load_lds_dwordx4 v206, s[18:19]
	s_mov_b32 m0, s31
	s_nop 0
	global_load_lds_dwordx4 v207, s[18:19]
	s_waitcnt vmcnt(6)
	s_waitcnt lgkmcnt(0)
	s_barrier
	v_mfma_f32_16x16x32_bf16 v[60:63], v[156:159], v[172:175], v[60:63]
	v_mfma_f32_16x16x32_bf16 v[56:59], v[164:167], v[172:175], v[56:59]
	v_mfma_f32_16x16x32_bf16 v[52:55], v[156:159], v[180:183], v[52:55]
	v_mfma_f32_16x16x32_bf16 v[48:51], v[164:167], v[180:183], v[48:51]
	v_mfma_f32_16x16x32_bf16 v[44:47], v[156:159], v[200:203], v[44:47]
	v_mfma_f32_16x16x32_bf16 v[40:43], v[164:167], v[200:203], v[40:43]
	v_mfma_f32_16x16x32_bf16 v[36:39], v[156:159], v[212:215], v[36:39]
	v_mfma_f32_16x16x32_bf16 v[32:35], v[164:167], v[212:215], v[32:35]
	v_mfma_f32_16x16x32_bf16 v[60:63], v[160:163], v[176:179], v[60:63]
	v_mfma_f32_16x16x32_bf16 v[56:59], v[168:171], v[176:179], v[56:59]
	v_mfma_f32_16x16x32_bf16 v[52:55], v[160:163], v[196:199], v[52:55]
	v_mfma_f32_16x16x32_bf16 v[48:51], v[168:171], v[196:199], v[48:51]
	v_mfma_f32_16x16x32_bf16 v[44:47], v[160:163], v[208:211], v[44:47]
	v_mfma_f32_16x16x32_bf16 v[40:43], v[168:171], v[208:211], v[40:43]
	v_mfma_f32_16x16x32_bf16 v[36:39], v[160:163], v[216:219], v[36:39]
	v_mfma_f32_16x16x32_bf16 v[32:35], v[168:171], v[216:219], v[32:35]
	v_mfma_f32_16x16x32_bf16 v[28:31], v[220:223], v[172:175], v[28:31]
	v_mfma_f32_16x16x32_bf16 v[24:27], v[228:231], v[172:175], v[24:27]
	v_mfma_f32_16x16x32_bf16 v[20:23], v[220:223], v[180:183], v[20:23]
	v_mfma_f32_16x16x32_bf16 v[16:19], v[228:231], v[180:183], v[16:19]
	v_mfma_f32_16x16x32_bf16 v[12:15], v[220:223], v[200:203], v[12:15]
	v_mfma_f32_16x16x32_bf16 v[8:11], v[228:231], v[200:203], v[8:11]
	v_mfma_f32_16x16x32_bf16 v[4:7], v[220:223], v[212:215], v[4:7]
	v_mfma_f32_16x16x32_bf16 v[0:3], v[228:231], v[212:215], v[0:3]
	v_mfma_f32_16x16x32_bf16 v[28:31], v[224:227], v[176:179], v[28:31]
	v_mfma_f32_16x16x32_bf16 v[24:27], v[232:235], v[176:179], v[24:27]
	v_mfma_f32_16x16x32_bf16 v[20:23], v[224:227], v[196:199], v[20:23]
	v_mfma_f32_16x16x32_bf16 v[16:19], v[232:235], v[196:199], v[16:19]
	v_mfma_f32_16x16x32_bf16 v[12:15], v[224:227], v[208:211], v[12:15]
	v_mfma_f32_16x16x32_bf16 v[8:11], v[232:235], v[208:211], v[8:11]
	v_mfma_f32_16x16x32_bf16 v[4:7], v[224:227], v[216:219], v[4:7]
	v_mfma_f32_16x16x32_bf16 v[0:3], v[232:235], v[216:219], v[0:3]
	v_or_b32_e32 v156, 0x18000, v146
	v_add_u32_e32 v158, 0x18100, v146
	s_barrier
; #define WAIT_V(n) asm volatile("s_waitcnt vmcnt(%0)" ::"n"(n) : "memory")
; #define WAIT_L(n) asm volatile("s_waitcnt lgkmcnt(%0)" ::"n"(n) : "memory")
; #define SBAR() __builtin_amdgcn_sched_barrier(0)
; #define STAGE(P, base, kt) do { _Pragma("unroll") for (int _i = 0; _i < 2; ++_i)                                        \
;       __builtin_amdgcn_global_load_lds((const unsigned*)((base) + (size_t)(sOff[_i] + (unsigned)(kt) * (BK * 2))),        \
;                                        (unsigned*)((P) + wid * 1024 + _i * 8192), 16, 0, 0); } while (0)
; #define LDA(dst, b, h) _Pragma("unroll") for (int m = 0; m < 4; ++m) _Pragma("unroll") for (int k = 0; k < 2; ++k) \
;       dst[m][k] = *(const bf16x8*)(SA(b, h) + aoff + (m * 2048 + k * 1024))
; #define LDB(dst, b, h) _Pragma("unroll") for (int n = 0; n < 2; ++n) _Pragma("unroll") for (int k = 0; k < 2; ++k) \
;       dst[n][k] = *(const bf16x8*)(SB(b, h) + boff + (n * 256 + k * 1024))
; #define BAR __builtin_amdgcn_s_barrier()
; template <int EPI, int N, int K>
; __device__ __forceinline__ void phase_gemm(const Params& p, const u16* __restrict__ A, const u16* __restrict__ Bt, int nM, char* shm,
;                            u16* __restrict__ outp, float* __restrict__ rowss) {
;     ...
;       LDB(B0, 1, 0); SBAR(); LDA(At, 1, 0); STAGE(SA(0, 1), A1, t + 2);
;       WAIT_L(8); BAR; WAIT_L(0); MMA(0, 0, At, B0); BAR; SBAR();
;       LDB(B1, 1, 1); STAGE(SB(1, 0), B0p, t + 3);
;       BAR; WAIT_L(0); MMA(0, 1, At, B1); BAR;
;       LDA(At, 1, 1); STAGE(SA(1, 0), A0, t + 3);
;       BAR; WAIT_L(0); MMA(1, 0, At, B0); BAR; SBAR();
;       STAGE(SB(1, 1), B1p, t + 3);
;       WAIT_V(6); BAR; MMA(1, 1, At, B1); BAR;
;     }
	v_add_u32_e32 v157, 0x18400, v146
	ds_read_b128 v[164:167], v156
	ds_read_b128 v[168:171], v157
	v_add_u32_e32 v159, 0x18500, v146
	ds_read_b128 v[172:175], v158
	ds_read_b128 v[176:179], v159
	s_mov_b32 m0, s33
	ds_read_b128 v[180:183], v147 offset:32768
	ds_read_b128 v[196:199], v147 offset:33792
	ds_read_b128 v[200:203], v147 offset:34816
	ds_read_b128 v[208:211], v147 offset:35840
	ds_read_b128 v[212:215], v147 offset:36864
	ds_read_b128 v[216:219], v147 offset:37888
	ds_read_b128 v[220:223], v147 offset:38912
	ds_read_b128 v[224:227], v147 offset:39936
	global_load_lds_dwordx4 v206, s[4:5]
	s_mov_b32 m0, s35
	s_nop 0
	global_load_lds_dwordx4 v207, s[4:5]
	v_or_b32_e32 v160, 0x1c000, v146
	v_add_u32_e32 v162, 0x1c100, v146
	v_add_u32_e32 v161, 0x1c400, v146
	ds_read_b128 v[228:231], v160
	ds_read_b128 v[232:235], v161
	v_add_u32_e32 v163, 0x1c500, v146
	ds_read_b128 v[236:239], v162
	ds_read_b128 v[240:243], v163
	s_waitcnt lgkmcnt(0)
	s_barrier
	v_mfma_f32_16x16x32_bf16 v[126:129], v[164:167], v[180:183], v[126:129]
	v_mfma_f32_16x16x32_bf16 v[122:125], v[172:175], v[180:183], v[122:125]
	v_mfma_f32_16x16x32_bf16 v[118:121], v[164:167], v[200:203], v[118:121]
	v_mfma_f32_16x16x32_bf16 v[114:117], v[172:175], v[200:203], v[114:117]
	v_mfma_f32_16x16x32_bf16 v[110:113], v[164:167], v[212:215], v[110:113]
	v_mfma_f32_16x16x32_bf16 v[106:109], v[172:175], v[212:215], v[106:109]
	v_mfma_f32_16x16x32_bf16 v[102:105], v[164:167], v[220:223], v[102:105]
	v_mfma_f32_16x16x32_bf16 v[98:101], v[172:175], v[220:223], v[98:101]
	v_mfma_f32_16x16x32_bf16 v[126:129], v[168:171], v[196:199], v[126:129]
	v_mfma_f32_16x16x32_bf16 v[122:125], v[176:179], v[196:199], v[122:125]
	v_mfma_f32_16x16x32_bf16 v[118:121], v[168:171], v[208:211], v[118:121]
	v_mfma_f32_16x16x32_bf16 v[114:117], v[176:179], v[208:211], v[114:117]
	v_mfma_f32_16x16x32_bf16 v[110:113], v[168:171], v[216:219], v[110:113]
	v_mfma_f32_16x16x32_bf16 v[106:109], v[176:179], v[216:219], v[106:109]
	v_mfma_f32_16x16x32_bf16 v[102:105], v[168:171], v[224:227], v[102:105]
	v_mfma_f32_16x16x32_bf16 v[98:101], v[176:179], v[224:227], v[98:101]
	v_mfma_f32_16x16x32_bf16 v[92:95], v[228:231], v[180:183], v[92:95]
	v_mfma_f32_16x16x32_bf16 v[88:91], v[236:239], v[180:183], v[88:91]
	v_mfma_f32_16x16x32_bf16 v[84:87], v[228:231], v[200:203], v[84:87]
	v_mfma_f32_16x16x32_bf16 v[80:83], v[236:239], v[200:203], v[80:83]
	v_mfma_f32_16x16x32_bf16 v[76:79], v[228:231], v[212:215], v[76:79]
	v_mfma_f32_16x16x32_bf16 v[72:75], v[236:239], v[212:215], v[72:75]
	v_mfma_f32_16x16x32_bf16 v[68:71], v[228:231], v[220:223], v[68:71]
	v_mfma_f32_16x16x32_bf16 v[64:67], v[236:239], v[220:223], v[64:67]
	v_mfma_f32_16x16x32_bf16 v[92:95], v[232:235], v[196:199], v[92:95]
	v_mfma_f32_16x16x32_bf16 v[88:91], v[240:243], v[196:199], v[88:91]
	v_mfma_f32_16x16x32_bf16 v[84:87], v[232:235], v[208:211], v[84:87]
	v_mfma_f32_16x16x32_bf16 v[80:83], v[240:243], v[208:211], v[80:83]
	v_mfma_f32_16x16x32_bf16 v[76:79], v[232:235], v[216:219], v[76:79]
	v_mfma_f32_16x16x32_bf16 v[72:75], v[240:243], v[216:219], v[72:75]
	v_mfma_f32_16x16x32_bf16 v[68:71], v[232:235], v[224:227], v[68:71]
	v_mfma_f32_16x16x32_bf16 v[64:67], v[240:243], v[224:227], v[64:67]
	s_barrier
	ds_read_b128 v[180:183], v147 offset:49152
	ds_read_b128 v[196:199], v147 offset:50176
	ds_read_b128 v[200:203], v147 offset:51200
	ds_read_b128 v[208:211], v147 offset:52224
	ds_read_b128 v[212:215], v147 offset:53248
	ds_read_b128 v[216:219], v147 offset:54272
	ds_read_b128 v[220:223], v147 offset:55296
	ds_read_b128 v[224:227], v147 offset:56320
	s_mov_b32 m0, s92
	v_add_u32_e32 v204, 0x180, v204
	global_load_lds_dwordx4 v204, s[10:11]
	v_add_u32_e32 v205, 0x180, v205
	s_mov_b32 m0, s93
	s_nop 0
	global_load_lds_dwordx4 v205, s[10:11]
	s_mov_b32 m0, s94
	s_nop 0
	global_load_lds_dwordx4 v204, s[12:13]
	s_mov_b32 m0, s52
	s_nop 0
	global_load_lds_dwordx4 v205, s[12:13]
	s_mov_b32 m0, s53
	s_nop 0
	global_load_lds_dwordx4 v204, s[18:19]
	s_mov_b32 m0, s54
	s_nop 0
	global_load_lds_dwordx4 v205, s[18:19]
	s_waitcnt vmcnt(6)
	s_waitcnt lgkmcnt(0)
	s_barrier
	v_mfma_f32_16x16x32_bf16 v[60:63], v[164:167], v[180:183], v[60:63]
	v_mfma_f32_16x16x32_bf16 v[56:59], v[172:175], v[180:183], v[56:59]
	v_mfma_f32_16x16x32_bf16 v[52:55], v[164:167], v[200:203], v[52:55]
	v_mfma_f32_16x16x32_bf16 v[48:51], v[172:175], v[200:203], v[48:51]
	v_mfma_f32_16x16x32_bf16 v[44:47], v[164:167], v[212:215], v[44:47]
	v_mfma_f32_16x16x32_bf16 v[40:43], v[172:175], v[212:215], v[40:43]
	v_mfma_f32_16x16x32_bf16 v[36:39], v[164:167], v[220:223], v[36:39]
	v_mfma_f32_16x16x32_bf16 v[32:35], v[172:175], v[220:223], v[32:35]
	v_mfma_f32_16x16x32_bf16 v[60:63], v[168:171], v[196:199], v[60:63]
	v_mfma_f32_16x16x32_bf16 v[56:59], v[176:179], v[196:199], v[56:59]
	v_mfma_f32_16x16x32_bf16 v[52:55], v[168:171], v[208:211], v[52:55]
	v_mfma_f32_16x16x32_bf16 v[48:51], v[176:179], v[208:211], v[48:51]
	v_mfma_f32_16x16x32_bf16 v[44:47], v[168:171], v[216:219], v[44:47]
	v_mfma_f32_16x16x32_bf16 v[40:43], v[176:179], v[216:219], v[40:43]
	v_mfma_f32_16x16x32_bf16 v[36:39], v[168:171], v[224:227], v[36:39]
	v_mfma_f32_16x16x32_bf16 v[32:35], v[176:179], v[224:227], v[32:35]
	v_mfma_f32_16x16x32_bf16 v[28:31], v[228:231], v[180:183], v[28:31]
	v_mfma_f32_16x16x32_bf16 v[24:27], v[236:239], v[180:183], v[24:27]
	v_mfma_f32_16x16x32_bf16 v[20:23], v[228:231], v[200:203], v[20:23]
	v_mfma_f32_16x16x32_bf16 v[16:19], v[236:239], v[200:203], v[16:19]
	v_mfma_f32_16x16x32_bf16 v[12:15], v[228:231], v[212:215], v[12:15]
	v_mfma_f32_16x16x32_bf16 v[8:11], v[236:239], v[212:215], v[8:11]
	v_mfma_f32_16x16x32_bf16 v[4:7], v[228:231], v[220:223], v[4:7]
	v_mfma_f32_16x16x32_bf16 v[0:3], v[236:239], v[220:223], v[0:3]
	v_mfma_f32_16x16x32_bf16 v[28:31], v[232:235], v[196:199], v[28:31]
	v_mfma_f32_16x16x32_bf16 v[24:27], v[240:243], v[196:199], v[24:27]
	v_mfma_f32_16x16x32_bf16 v[20:23], v[232:235], v[208:211], v[20:23]
	v_mfma_f32_16x16x32_bf16 v[16:19], v[240:243], v[208:211], v[16:19]
	v_mfma_f32_16x16x32_bf16 v[12:15], v[232:235], v[216:219], v[12:15]
	v_mfma_f32_16x16x32_bf16 v[8:11], v[240:243], v[216:219], v[8:11]
	v_mfma_f32_16x16x32_bf16 v[4:7], v[232:235], v[224:227], v[4:7]
	v_mfma_f32_16x16x32_bf16 v[0:3], v[240:243], v[224:227], v[0:3]
	s_add_i32 s58, s58, 2
	v_add_u32_e32 v142, 0x100, v142
	s_cmp_lt_u32 s58, 40
	v_add_u32_e32 v96, 0x100, v96
	s_barrier
; #define WAIT_V(n) asm volatile("s_waitcnt vmcnt(%0)" ::"n"(n) : "memory")
; #define WAIT_L(n) asm volatile("s_waitcnt lgkmcnt(%0)" ::"n"(n) : "memory")
; #define STAGE(P, base, kt) do { _Pragma("unroll") for (int _i = 0; _i < 2; ++_i)                                        \
;       __builtin_amdgcn_global_load_lds((const unsigned*)((base) + (size_t)(sOff[_i] + (unsigned)(kt) * (BK * 2))),        \
;                                        (unsigned*)((P) + wid * 1024 + _i * 8192), 16, 0, 0); } while (0)
; #define LDA(dst, b, h) _Pragma("unroll") for (int m = 0; m < 4; ++m) _Pragma("unroll") for (int k = 0; k < 2; ++k) \
;       dst[m][k] = *(const bf16x8*)(SA(b, h) + aoff + (m * 2048 + k * 1024))
; #define LDB(dst, b, h) _Pragma("unroll") for (int n = 0; n < 2; ++n) _Pragma("unroll") for (int k = 0; k < 2; ++k) \
;       dst[n][k] = *(const bf16x8*)(SB(b, h) + boff + (n * 256 + k * 1024))
; #define BAR __builtin_amdgcn_s_barrier()
; template <int EPI, int N, int K>
; __device__ __forceinline__ void phase_gemm(const Params& p, const u16* __restrict__ A, const u16* __restrict__ Bt, int nM, char* shm,
;                            u16* __restrict__ outp, float* __restrict__ rowss) {
;     ...
;     }
;     { LDB(B0, 0, 0); LDA(At, 0, 0); STAGE(SA(1, 1), A1, nt - 1);
;       BAR; WAIT_L(0); MMA(0, 0, At, B0); BAR;
;       LDB(B1, 0, 1); BAR; WAIT_L(0); MMA(0, 1, At, B1); BAR;
;       LDA(At, 0, 1); WAIT_V(4); BAR; WAIT_L(0); MMA(1, 0, At, B0); MMA(1, 1, At, B1); BAR; }
	s_cbranch_scc1 .LBB0_517
	s_mov_b32 m0, s60
	v_lshl_add_u64 v[204:205], s[4:5], 0, v[138:139]
	ds_read_b128 v[164:167], v143
	ds_read_b128 v[168:171], v144
	ds_read_b128 v[142:145], v145
	ds_read_b128 v[172:175], v151
	ds_read_b128 v[176:179], v147
	ds_read_b128 v[180:183], v147 offset:1024
	ds_read_b128 v[196:199], v147 offset:2048
	ds_read_b128 v[200:203], v147 offset:3072
	ds_read_b128 v[208:211], v147 offset:4096
	ds_read_b128 v[212:215], v147 offset:5120
	ds_read_b128 v[216:219], v147 offset:6144
	ds_read_b128 v[220:223], v147 offset:7168
	global_load_lds_dwordx4 v[204:205], off
	v_lshl_add_u64 v[204:205], s[4:5], 0, v[140:141]
	s_mov_b32 m0, s59
	s_nop 0
	global_load_lds_dwordx4 v[204:205], off
	s_barrier
	s_waitcnt lgkmcnt(0)
	s_waitcnt lgkmcnt(0)
	v_mfma_f32_16x16x32_bf16 v[126:129], v[164:167], v[176:179], v[126:129]
	v_mfma_f32_16x16x32_bf16 v[122:125], v[142:145], v[176:179], v[122:125]
	v_mfma_f32_16x16x32_bf16 v[118:121], v[164:167], v[196:199], v[118:121]
	v_mfma_f32_16x16x32_bf16 v[102:105], v[164:167], v[216:219], v[102:105]
	v_mfma_f32_16x16x32_bf16 v[98:101], v[142:145], v[216:219], v[98:101]
	v_mfma_f32_16x16x32_bf16 v[126:129], v[168:171], v[180:183], v[126:129]
	v_mfma_f32_16x16x32_bf16 v[122:125], v[172:175], v[180:183], v[122:125]
	v_mfma_f32_16x16x32_bf16 v[118:121], v[168:171], v[200:203], v[118:121]
	v_mfma_f32_16x16x32_bf16 v[114:117], v[142:145], v[196:199], v[114:117]
	v_mfma_f32_16x16x32_bf16 v[110:113], v[164:167], v[208:211], v[110:113]
	v_mfma_f32_16x16x32_bf16 v[106:109], v[142:145], v[208:211], v[106:109]
	v_mfma_f32_16x16x32_bf16 v[102:105], v[168:171], v[220:223], v[102:105]
	v_mfma_f32_16x16x32_bf16 v[98:101], v[172:175], v[220:223], v[98:101]
	v_mfma_f32_16x16x32_bf16 v[224:227], v[172:175], v[200:203], v[114:117]
	v_mfma_f32_16x16x32_bf16 v[228:231], v[168:171], v[212:215], v[110:113]
	v_mfma_f32_16x16x32_bf16 v[232:235], v[172:175], v[212:215], v[106:109]
	s_barrier
	s_nop 0
	ds_read_b128 v[106:109], v152
	ds_read_b128 v[110:113], v153
	ds_read_b128 v[114:117], v154
	ds_read_b128 v[152:155], v155
	s_barrier
	s_waitcnt lgkmcnt(0)
	s_waitcnt lgkmcnt(0)
	v_mfma_f32_16x16x32_bf16 v[84:87], v[106:109], v[196:199], v[84:87]
	v_mfma_f32_16x16x32_bf16 v[80:83], v[114:117], v[196:199], v[80:83]
	v_mfma_f32_16x16x32_bf16 v[68:71], v[106:109], v[216:219], v[68:71]
	v_mfma_f32_16x16x32_bf16 v[92:95], v[106:109], v[176:179], v[92:95]
	v_mfma_f32_16x16x32_bf16 v[88:91], v[114:117], v[176:179], v[88:91]
	v_mfma_f32_16x16x32_bf16 v[84:87], v[110:113], v[200:203], v[84:87]
	v_mfma_f32_16x16x32_bf16 v[80:83], v[152:155], v[200:203], v[80:83]
	v_mfma_f32_16x16x32_bf16 v[76:79], v[106:109], v[208:211], v[76:79]
	v_mfma_f32_16x16x32_bf16 v[72:75], v[114:117], v[208:211], v[72:75]
	v_mfma_f32_16x16x32_bf16 v[68:71], v[110:113], v[220:223], v[68:71]
	v_mfma_f32_16x16x32_bf16 v[64:67], v[114:117], v[216:219], v[64:67]
	v_mfma_f32_16x16x32_bf16 v[236:239], v[110:113], v[180:183], v[92:95]
	v_mfma_f32_16x16x32_bf16 v[176:179], v[152:155], v[180:183], v[88:91]
	v_mfma_f32_16x16x32_bf16 v[180:183], v[110:113], v[212:215], v[76:79]
	v_mfma_f32_16x16x32_bf16 v[196:199], v[152:155], v[212:215], v[72:75]
	v_mfma_f32_16x16x32_bf16 v[200:203], v[152:155], v[220:223], v[64:67]
	s_barrier
	s_nop 0
	ds_read_b128 v[64:67], v147 offset:16384
	ds_read_b128 v[72:75], v147 offset:17408
	ds_read_b128 v[76:79], v147 offset:18432
	ds_read_b128 v[88:91], v147 offset:19456
	ds_read_b128 v[92:95], v147 offset:20480
	ds_read_b128 v[208:211], v147 offset:21504
	ds_read_b128 v[212:215], v147 offset:22528
	ds_read_b128 v[216:219], v147 offset:23552
	s_waitcnt vmcnt(4)
	s_barrier
	s_waitcnt lgkmcnt(0)
	s_waitcnt lgkmcnt(0)
	v_mfma_f32_16x16x32_bf16 v[60:63], v[164:167], v[64:67], v[60:63]
	v_mfma_f32_16x16x32_bf16 v[52:55], v[164:167], v[76:79], v[52:55]
	v_mfma_f32_16x16x32_bf16 v[48:51], v[142:145], v[76:79], v[48:51]
	v_mfma_f32_16x16x32_bf16 v[36:39], v[164:167], v[212:215], v[36:39]
	v_mfma_f32_16x16x32_bf16 v[32:35], v[142:145], v[212:215], v[32:35]
	v_mfma_f32_16x16x32_bf16 v[60:63], v[168:171], v[72:75], v[60:63]
	v_mfma_f32_16x16x32_bf16 v[56:59], v[142:145], v[64:67], v[56:59]
	v_mfma_f32_16x16x32_bf16 v[52:55], v[168:171], v[88:91], v[52:55]
	v_mfma_f32_16x16x32_bf16 v[48:51], v[172:175], v[88:91], v[48:51]
	v_mfma_f32_16x16x32_bf16 v[44:47], v[164:167], v[92:95], v[44:47]
	v_mfma_f32_16x16x32_bf16 v[40:43], v[142:145], v[92:95], v[40:43]
	v_mfma_f32_16x16x32_bf16 v[36:39], v[168:171], v[216:219], v[36:39]
	v_mfma_f32_16x16x32_bf16 v[32:35], v[172:175], v[216:219], v[32:35]
	v_mfma_f32_16x16x32_bf16 v[220:223], v[172:175], v[72:75], v[56:59]
	v_mfma_f32_16x16x32_bf16 v[240:243], v[168:171], v[208:211], v[44:47]
	v_mfma_f32_16x16x32_bf16 v[244:247], v[172:175], v[208:211], v[40:43]
	v_mfma_f32_16x16x32_bf16 v[20:23], v[106:109], v[76:79], v[20:23]
	v_mfma_f32_16x16x32_bf16 v[16:19], v[114:117], v[76:79], v[16:19]
	v_mfma_f32_16x16x32_bf16 v[4:7], v[106:109], v[212:215], v[4:7]
	v_mfma_f32_16x16x32_bf16 v[28:31], v[106:109], v[64:67], v[28:31]
	v_mfma_f32_16x16x32_bf16 v[24:27], v[114:117], v[64:67], v[24:27]
	v_mfma_f32_16x16x32_bf16 v[20:23], v[110:113], v[88:91], v[20:23]
	v_mfma_f32_16x16x32_bf16 v[16:19], v[152:155], v[88:91], v[16:19]
	v_mfma_f32_16x16x32_bf16 v[12:15], v[106:109], v[92:95], v[12:15]
	v_mfma_f32_16x16x32_bf16 v[8:11], v[114:117], v[92:95], v[8:11]
	v_mfma_f32_16x16x32_bf16 v[4:7], v[110:113], v[216:219], v[4:7]
	v_mfma_f32_16x16x32_bf16 v[0:3], v[114:117], v[212:215], v[0:3]
	v_mfma_f32_16x16x32_bf16 v[142:145], v[110:113], v[72:75], v[28:31]
	v_mfma_f32_16x16x32_bf16 v[164:167], v[152:155], v[72:75], v[24:27]
	v_mfma_f32_16x16x32_bf16 v[168:171], v[110:113], v[208:211], v[12:15]
	v_mfma_f32_16x16x32_bf16 v[172:175], v[152:155], v[208:211], v[8:11]
	v_mfma_f32_16x16x32_bf16 v[152:155], v[152:155], v[216:219], v[0:3]
	s_barrier
; #define WAIT_V(n) asm volatile("s_waitcnt vmcnt(%0)" ::"n"(n) : "memory")
; #define WAIT_L(n) asm volatile("s_waitcnt lgkmcnt(%0)" ::"n"(n) : "memory")
; #define LDA(dst, b, h) _Pragma("unroll") for (int m = 0; m < 4; ++m) _Pragma("unroll") for (int k = 0; k < 2; ++k) \
;       dst[m][k] = *(const bf16x8*)(SA(b, h) + aoff + (m * 2048 + k * 1024))
; #define LDB(dst, b, h) _Pragma("unroll") for (int n = 0; n < 2; ++n) _Pragma("unroll") for (int k = 0; k < 2; ++k) \
;       dst[n][k] = *(const bf16x8*)(SB(b, h) + boff + (n * 256 + k * 1024))
; #define BAR __builtin_amdgcn_s_barrier()
; template <int EPI, int N, int K>
; __device__ __forceinline__ void phase_gemm(const Params& p, const u16* __restrict__ A, const u16* __restrict__ Bt, int nM, char* shm,
;                            u16* __restrict__ outp, float* __restrict__ rowss) {
;     ...
;     { LDB(B0, 1, 0); LDA(At, 1, 0); WAIT_V(2); BAR; WAIT_L(0); MMA(0, 0, At, B0); BAR;
;       LDB(B1, 1, 1); WAIT_V(0); BAR; WAIT_L(0); MMA(0, 1, At, B1); BAR;
;       LDA(At, 1, 1); BAR; WAIT_L(0); MMA(1, 0, At, B0); MMA(1, 1, At, B1); BAR; }
;     if (wr == 0) BAR;
	s_nop 0
	ds_read_b128 v[0:3], v156
	ds_read_b128 v[8:11], v157
	ds_read_b128 v[12:15], v158
	ds_read_b128 v[156:159], v159
	ds_read_b128 v[24:27], v147 offset:32768
	ds_read_b128 v[28:31], v147 offset:33792
	ds_read_b128 v[40:43], v147 offset:34816
	ds_read_b128 v[44:47], v147 offset:35840
	ds_read_b128 v[56:59], v147 offset:36864
	ds_read_b128 v[64:67], v147 offset:37888
	ds_read_b128 v[208:211], v147 offset:38912
	ds_read_b128 v[212:215], v147 offset:39936
	s_waitcnt vmcnt(2)
	s_barrier
	s_waitcnt lgkmcnt(0)
	s_waitcnt lgkmcnt(0)
	v_mfma_f32_16x16x32_bf16 v[72:75], v[0:3], v[24:27], v[126:129]
	v_mfma_f32_16x16x32_bf16 v[126:129], v[8:11], v[28:31], v[72:75]
	v_mfma_f32_16x16x32_bf16 v[72:75], v[12:15], v[24:27], v[122:125]
	v_mfma_f32_16x16x32_bf16 v[114:117], v[156:159], v[28:31], v[72:75]
	v_mfma_f32_16x16x32_bf16 v[72:75], v[0:3], v[40:43], v[118:121]
	v_mfma_f32_16x16x32_bf16 v[106:109], v[8:11], v[44:47], v[72:75]
	v_mfma_f32_16x16x32_bf16 v[72:75], v[12:15], v[40:43], v[224:227]
	v_mfma_f32_16x16x32_bf16 v[110:113], v[156:159], v[44:47], v[72:75]
	v_mfma_f32_16x16x32_bf16 v[72:75], v[0:3], v[56:59], v[228:231]
	v_mfma_f32_16x16x32_bf16 v[88:91], v[8:11], v[64:67], v[72:75]
	v_mfma_f32_16x16x32_bf16 v[72:75], v[12:15], v[56:59], v[232:235]
	v_mfma_f32_16x16x32_bf16 v[92:95], v[156:159], v[64:67], v[72:75]
	v_mfma_f32_16x16x32_bf16 v[72:75], v[0:3], v[208:211], v[102:105]
	v_mfma_f32_16x16x32_bf16 v[76:79], v[12:15], v[208:211], v[98:101]
	v_mfma_f32_16x16x32_bf16 v[72:75], v[8:11], v[212:215], v[72:75]
	v_mfma_f32_16x16x32_bf16 v[76:79], v[156:159], v[212:215], v[76:79]
	s_barrier
	ds_read_b128 v[216:219], v160
	ds_read_b128 v[224:227], v161
	ds_read_b128 v[228:231], v162
	ds_read_b128 v[160:163], v163
	s_waitcnt vmcnt(0)
	s_barrier
	s_waitcnt lgkmcnt(0)
	s_waitcnt lgkmcnt(0)
	v_mfma_f32_16x16x32_bf16 v[98:101], v[216:219], v[24:27], v[236:239]
	v_mfma_f32_16x16x32_bf16 v[24:27], v[228:231], v[24:27], v[176:179]
	v_mfma_f32_16x16x32_bf16 v[122:125], v[160:163], v[28:31], v[24:27]
	v_mfma_f32_16x16x32_bf16 v[24:27], v[216:219], v[40:43], v[84:87]
	v_mfma_f32_16x16x32_bf16 v[118:121], v[224:227], v[28:31], v[98:101]
	v_mfma_f32_16x16x32_bf16 v[98:101], v[224:227], v[44:47], v[24:27]
	v_mfma_f32_16x16x32_bf16 v[24:27], v[228:231], v[40:43], v[80:83]
	v_mfma_f32_16x16x32_bf16 v[102:105], v[160:163], v[44:47], v[24:27]
	v_mfma_f32_16x16x32_bf16 v[24:27], v[216:219], v[56:59], v[180:183]
	v_mfma_f32_16x16x32_bf16 v[80:83], v[224:227], v[64:67], v[24:27]
	v_mfma_f32_16x16x32_bf16 v[24:27], v[228:231], v[56:59], v[196:199]
	v_mfma_f32_16x16x32_bf16 v[84:87], v[160:163], v[64:67], v[24:27]
	v_mfma_f32_16x16x32_bf16 v[24:27], v[216:219], v[208:211], v[68:71]
	v_mfma_f32_16x16x32_bf16 v[64:67], v[224:227], v[212:215], v[24:27]
	v_mfma_f32_16x16x32_bf16 v[24:27], v[228:231], v[208:211], v[200:203]
	v_mfma_f32_16x16x32_bf16 v[68:71], v[160:163], v[212:215], v[24:27]
	s_barrier
	ds_read_b128 v[176:179], v147 offset:49152
	ds_read_b128 v[180:183], v147 offset:50176
	ds_read_b128 v[196:199], v147 offset:51200
	ds_read_b128 v[200:203], v147 offset:52224
	ds_read_b128 v[208:211], v147 offset:53248
	ds_read_b128 v[212:215], v147 offset:54272
	ds_read_b128 v[232:235], v147 offset:55296
	ds_read_b128 v[236:239], v147 offset:56320
	s_barrier
	s_waitcnt lgkmcnt(0)
	s_waitcnt lgkmcnt(0)
	v_mfma_f32_16x16x32_bf16 v[24:27], v[0:3], v[176:179], v[60:63]
	v_mfma_f32_16x16x32_bf16 v[56:59], v[8:11], v[180:183], v[24:27]
	v_mfma_f32_16x16x32_bf16 v[24:27], v[12:15], v[176:179], v[220:223]
	v_mfma_f32_16x16x32_bf16 v[60:63], v[156:159], v[180:183], v[24:27]
	v_mfma_f32_16x16x32_bf16 v[24:27], v[0:3], v[196:199], v[52:55]
	v_mfma_f32_16x16x32_bf16 v[40:43], v[8:11], v[200:203], v[24:27]
	v_mfma_f32_16x16x32_bf16 v[24:27], v[12:15], v[196:199], v[48:51]
	v_mfma_f32_16x16x32_bf16 v[44:47], v[156:159], v[200:203], v[24:27]
	v_mfma_f32_16x16x32_bf16 v[24:27], v[0:3], v[208:211], v[240:243]
	v_mfma_f32_16x16x32_bf16 v[0:3], v[0:3], v[232:235], v[36:39]
	v_mfma_f32_16x16x32_bf16 v[24:27], v[8:11], v[212:215], v[24:27]
	v_mfma_f32_16x16x32_bf16 v[28:31], v[12:15], v[208:211], v[244:247]
	v_mfma_f32_16x16x32_bf16 v[8:11], v[8:11], v[236:239], v[0:3]
	v_mfma_f32_16x16x32_bf16 v[0:3], v[12:15], v[232:235], v[32:35]
	v_mfma_f32_16x16x32_bf16 v[28:31], v[156:159], v[212:215], v[28:31]
	v_mfma_f32_16x16x32_bf16 v[12:15], v[156:159], v[236:239], v[0:3]
	v_mfma_f32_16x16x32_bf16 v[0:3], v[216:219], v[176:179], v[142:145]
	v_mfma_f32_16x16x32_bf16 v[48:51], v[224:227], v[180:183], v[0:3]
	v_mfma_f32_16x16x32_bf16 v[0:3], v[228:231], v[176:179], v[164:167]
	v_mfma_f32_16x16x32_bf16 v[52:55], v[160:163], v[180:183], v[0:3]
	v_mfma_f32_16x16x32_bf16 v[0:3], v[216:219], v[196:199], v[20:23]
	v_mfma_f32_16x16x32_bf16 v[32:35], v[224:227], v[200:203], v[0:3]
	v_mfma_f32_16x16x32_bf16 v[0:3], v[228:231], v[196:199], v[16:19]
	v_mfma_f32_16x16x32_bf16 v[36:39], v[160:163], v[200:203], v[0:3]
	v_mfma_f32_16x16x32_bf16 v[0:3], v[216:219], v[208:211], v[168:171]
	v_mfma_f32_16x16x32_bf16 v[16:19], v[224:227], v[212:215], v[0:3]
	v_mfma_f32_16x16x32_bf16 v[0:3], v[228:231], v[208:211], v[172:175]
	v_mfma_f32_16x16x32_bf16 v[20:23], v[160:163], v[212:215], v[0:3]
	v_mfma_f32_16x16x32_bf16 v[0:3], v[216:219], v[232:235], v[4:7]
	v_mfma_f32_16x16x32_bf16 v[4:7], v[228:231], v[232:235], v[152:155]
	v_mfma_f32_16x16x32_bf16 v[0:3], v[224:227], v[236:239], v[0:3]
	v_mfma_f32_16x16x32_bf16 v[4:7], v[160:163], v[236:239], v[4:7]
	s_andn2_b64 vcc, exec, s[16:17]
	s_barrier
	s_cbranch_vccnz .LBB0_520
	s_barrier

; #define WAIT_V(n) asm volatile("s_waitcnt vmcnt(%0)" ::"n"(n) : "memory")
; #define WAIT_L(n) asm volatile("s_waitcnt lgkmcnt(%0)" ::"n"(n) : "memory")
; #define SBAR() __builtin_amdgcn_sched_barrier(0)
; #define STAGE(P, base, kt) do { _Pragma("unroll") for (int _i = 0; _i < 2; ++_i)                                        \
;       __builtin_amdgcn_global_load_lds((const unsigned*)((base) + (size_t)(sOff[_i] + (unsigned)(kt) * (BK * 2))),        \
;                                        (unsigned*)((P) + wid * 1024 + _i * 8192), 16, 0, 0); } while (0)
; #define LDA(dst, b, h) _Pragma("unroll") for (int m = 0; m < 4; ++m) _Pragma("unroll") for (int k = 0; k < 2; ++k) \
;       dst[m][k] = *(const bf16x8*)(SA(b, h) + aoff + (m * 2048 + k * 1024))
; #define LDB(dst, b, h) _Pragma("unroll") for (int n = 0; n < 2; ++n) _Pragma("unroll") for (int k = 0; k < 2; ++k) \
;       dst[n][k] = *(const bf16x8*)(SB(b, h) + boff + (n * 256 + k * 1024))
; #define BAR __builtin_amdgcn_s_barrier()
; template <int EPI, int N, int K>
; __device__ __forceinline__ void phase_gemm(const Params& p, const u16* __restrict__ A, const u16* __restrict__ Bt, int nM, char* shm,
;                            u16* __restrict__ outp, float* __restrict__ rowss) {
;     ...
;     for (int t = 0; t < nt - 2; t += 2) {
;       LDB(B0, 0, 0); SBAR(); LDA(At, 0, 0); STAGE(SA(1, 1), A1, t + 1);
;       WAIT_L(8); BAR; WAIT_L(0); MMA(0, 0, At, B0); BAR; SBAR();
;       LDB(B1, 0, 1); STAGE(SB(0, 0), B0p, t + 2);
;       BAR; WAIT_L(0); MMA(0, 1, At, B1); BAR;
;       LDA(At, 0, 1); STAGE(SA(0, 0), A0, t + 2);
;       BAR; WAIT_L(0); MMA(1, 0, At, B0); BAR; SBAR();
;       STAGE(SB(0, 1), B1p, t + 2);
;       WAIT_V(6); BAR; MMA(1, 1, At, B1); BAR;
.LBB0_553:
	v_or_b32_e32 v147, 0x10000, v143
	v_add_u32_e32 v149, 0x10100, v143
	v_add_u32_e32 v148, 0x10400, v143
	ds_read_b128 v[156:159], v147
	ds_read_b128 v[160:163], v148
	v_add_u32_e32 v150, 0x10500, v143
	ds_read_b128 v[164:167], v149
	ds_read_b128 v[168:171], v150
	v_add_u32_e32 v196, v142, v140
	s_add_i32 s55, s19, 0xc000
	v_add_u32_e32 v151, 0x80, v196
	s_mov_b32 m0, s55
	v_add_u32_e32 v197, v142, v141
	s_add_i32 s54, s19, 0xe000
	ds_read_b128 v[172:175], v144
	ds_read_b128 v[176:179], v144 offset:1024
	ds_read_b128 v[180:183], v144 offset:2048
	ds_read_b128 v[208:211], v144 offset:3072
	ds_read_b128 v[212:215], v144 offset:4096
	ds_read_b128 v[216:219], v144 offset:5120
	ds_read_b128 v[220:223], v144 offset:6144
	ds_read_b128 v[224:227], v144 offset:7168
	global_load_lds_dwordx4 v151, s[14:15]
	v_add_u32_e32 v151, 0x80, v197
	s_mov_b32 m0, s54
	s_nop 0
	global_load_lds_dwordx4 v151, s[14:15]
	v_or_b32_e32 v151, 0x14000, v143
	v_add_u32_e32 v153, 0x14100, v143
	v_add_u32_e32 v152, 0x14400, v143
	ds_read_b128 v[228:231], v151
	ds_read_b128 v[232:235], v152
	v_add_u32_e32 v154, 0x14500, v143
	ds_read_b128 v[236:239], v153
	ds_read_b128 v[240:243], v154
	s_waitcnt lgkmcnt(0)
	s_barrier
	v_mfma_f32_16x16x32_bf16 v[126:129], v[156:159], v[172:175], v[126:129]
	v_mfma_f32_16x16x32_bf16 v[122:125], v[164:167], v[172:175], v[122:125]
	v_mfma_f32_16x16x32_bf16 v[118:121], v[156:159], v[180:183], v[118:121]
	v_mfma_f32_16x16x32_bf16 v[114:117], v[164:167], v[180:183], v[114:117]
	v_mfma_f32_16x16x32_bf16 v[110:113], v[156:159], v[212:215], v[110:113]
	v_mfma_f32_16x16x32_bf16 v[106:109], v[164:167], v[212:215], v[106:109]
	v_mfma_f32_16x16x32_bf16 v[102:105], v[156:159], v[220:223], v[102:105]
	v_mfma_f32_16x16x32_bf16 v[98:101], v[164:167], v[220:223], v[98:101]
	v_mfma_f32_16x16x32_bf16 v[126:129], v[160:163], v[176:179], v[126:129]
	v_mfma_f32_16x16x32_bf16 v[122:125], v[168:171], v[176:179], v[122:125]
	v_mfma_f32_16x16x32_bf16 v[118:121], v[160:163], v[208:211], v[118:121]
	v_mfma_f32_16x16x32_bf16 v[114:117], v[168:171], v[208:211], v[114:117]
	v_mfma_f32_16x16x32_bf16 v[110:113], v[160:163], v[216:219], v[110:113]
	v_mfma_f32_16x16x32_bf16 v[106:109], v[168:171], v[216:219], v[106:109]
	v_mfma_f32_16x16x32_bf16 v[102:105], v[160:163], v[224:227], v[102:105]
	v_mfma_f32_16x16x32_bf16 v[98:101], v[168:171], v[224:227], v[98:101]
	v_mfma_f32_16x16x32_bf16 v[92:95], v[228:231], v[172:175], v[92:95]
	v_mfma_f32_16x16x32_bf16 v[88:91], v[236:239], v[172:175], v[88:91]
	v_mfma_f32_16x16x32_bf16 v[84:87], v[228:231], v[180:183], v[84:87]
	v_mfma_f32_16x16x32_bf16 v[80:83], v[236:239], v[180:183], v[80:83]
	v_mfma_f32_16x16x32_bf16 v[76:79], v[228:231], v[212:215], v[76:79]
	v_mfma_f32_16x16x32_bf16 v[72:75], v[236:239], v[212:215], v[72:75]
	v_mfma_f32_16x16x32_bf16 v[68:71], v[228:231], v[220:223], v[68:71]
	v_mfma_f32_16x16x32_bf16 v[64:67], v[236:239], v[220:223], v[64:67]
	v_mfma_f32_16x16x32_bf16 v[92:95], v[232:235], v[176:179], v[92:95]
	v_mfma_f32_16x16x32_bf16 v[88:91], v[240:243], v[176:179], v[88:91]
	v_mfma_f32_16x16x32_bf16 v[84:87], v[232:235], v[208:211], v[84:87]
	v_mfma_f32_16x16x32_bf16 v[80:83], v[240:243], v[208:211], v[80:83]
	v_mfma_f32_16x16x32_bf16 v[76:79], v[232:235], v[216:219], v[76:79]
	v_mfma_f32_16x16x32_bf16 v[72:75], v[240:243], v[216:219], v[72:75]
	v_mfma_f32_16x16x32_bf16 v[68:71], v[232:235], v[224:227], v[68:71]
	v_mfma_f32_16x16x32_bf16 v[64:67], v[240:243], v[224:227], v[64:67]
	s_barrier
	ds_read_b128 v[172:175], v144 offset:16384
	ds_read_b128 v[176:179], v144 offset:17408
	ds_read_b128 v[180:183], v144 offset:18432
	ds_read_b128 v[208:211], v144 offset:19456
	ds_read_b128 v[212:215], v144 offset:20480
	ds_read_b128 v[216:219], v144 offset:21504
	ds_read_b128 v[220:223], v144 offset:22528
	ds_read_b128 v[224:227], v144 offset:23552
	s_mov_b32 m0, s23
	v_add_u32_e32 v198, 0x100, v196
	global_load_lds_dwordx4 v198, s[6:7]
	v_add_u32_e32 v199, 0x100, v197
	s_mov_b32 m0, s92
	s_nop 0
	global_load_lds_dwordx4 v199, s[6:7]
	s_mov_b32 m0, s19
	s_nop 0
	global_load_lds_dwordx4 v198, s[8:9]
	s_mov_b32 m0, s22
	s_nop 0
	global_load_lds_dwordx4 v199, s[8:9]
	s_mov_b32 m0, s94
	s_nop 0
	global_load_lds_dwordx4 v198, s[16:17]
	s_mov_b32 m0, s95
	s_nop 0
	global_load_lds_dwordx4 v199, s[16:17]
	s_waitcnt vmcnt(6)
	s_waitcnt lgkmcnt(0)
	s_barrier
	v_mfma_f32_16x16x32_bf16 v[60:63], v[156:159], v[172:175], v[60:63]
	v_mfma_f32_16x16x32_bf16 v[56:59], v[164:167], v[172:175], v[56:59]
	v_mfma_f32_16x16x32_bf16 v[52:55], v[156:159], v[180:183], v[52:55]
	v_mfma_f32_16x16x32_bf16 v[48:51], v[164:167], v[180:183], v[48:51]
	v_mfma_f32_16x16x32_bf16 v[44:47], v[156:159], v[212:215], v[44:47]
	v_mfma_f32_16x16x32_bf16 v[40:43], v[164:167], v[212:215], v[40:43]
	v_mfma_f32_16x16x32_bf16 v[36:39], v[156:159], v[220:223], v[36:39]
	v_mfma_f32_16x16x32_bf16 v[32:35], v[164:167], v[220:223], v[32:35]
	v_mfma_f32_16x16x32_bf16 v[60:63], v[160:163], v[176:179], v[60:63]
	v_mfma_f32_16x16x32_bf16 v[56:59], v[168:171], v[176:179], v[56:59]
	v_mfma_f32_16x16x32_bf16 v[52:55], v[160:163], v[208:211], v[52:55]
	v_mfma_f32_16x16x32_bf16 v[48:51], v[168:171], v[208:211], v[48:51]
	v_mfma_f32_16x16x32_bf16 v[44:47], v[160:163], v[216:219], v[44:47]
	v_mfma_f32_16x16x32_bf16 v[40:43], v[168:171], v[216:219], v[40:43]
	v_mfma_f32_16x16x32_bf16 v[36:39], v[160:163], v[224:227], v[36:39]
	v_mfma_f32_16x16x32_bf16 v[32:35], v[168:171], v[224:227], v[32:35]
	v_mfma_f32_16x16x32_bf16 v[28:31], v[228:231], v[172:175], v[28:31]
	v_mfma_f32_16x16x32_bf16 v[24:27], v[236:239], v[172:175], v[24:27]
	v_mfma_f32_16x16x32_bf16 v[20:23], v[228:231], v[180:183], v[20:23]
	v_mfma_f32_16x16x32_bf16 v[16:19], v[236:239], v[180:183], v[16:19]
	v_mfma_f32_16x16x32_bf16 v[12:15], v[228:231], v[212:215], v[12:15]
	v_mfma_f32_16x16x32_bf16 v[8:11], v[236:239], v[212:215], v[8:11]
	v_mfma_f32_16x16x32_bf16 v[4:7], v[228:231], v[220:223], v[4:7]
	v_mfma_f32_16x16x32_bf16 v[0:3], v[236:239], v[220:223], v[0:3]
	v_mfma_f32_16x16x32_bf16 v[28:31], v[232:235], v[176:179], v[28:31]
	v_mfma_f32_16x16x32_bf16 v[24:27], v[240:243], v[176:179], v[24:27]
	v_mfma_f32_16x16x32_bf16 v[20:23], v[232:235], v[208:211], v[20:23]
	v_mfma_f32_16x16x32_bf16 v[16:19], v[240:243], v[208:211], v[16:19]
	v_mfma_f32_16x16x32_bf16 v[12:15], v[232:235], v[216:219], v[12:15]
	v_mfma_f32_16x16x32_bf16 v[8:11], v[240:243], v[216:219], v[8:11]
	v_mfma_f32_16x16x32_bf16 v[4:7], v[232:235], v[224:227], v[4:7]
	v_mfma_f32_16x16x32_bf16 v[0:3], v[240:243], v[224:227], v[0:3]
	v_or_b32_e32 v155, 0x18000, v143
	v_add_u32_e32 v157, 0x18100, v143
	s_barrier
; #define WAIT_V(n) asm volatile("s_waitcnt vmcnt(%0)" ::"n"(n) : "memory")
; #define WAIT_L(n) asm volatile("s_waitcnt lgkmcnt(%0)" ::"n"(n) : "memory")
; #define SBAR() __builtin_amdgcn_sched_barrier(0)
; #define STAGE(P, base, kt) do { _Pragma("unroll") for (int _i = 0; _i < 2; ++_i)                                        \
;       __builtin_amdgcn_global_load_lds((const unsigned*)((base) + (size_t)(sOff[_i] + (unsigned)(kt) * (BK * 2))),        \
;                                        (unsigned*)((P) + wid * 1024 + _i * 8192), 16, 0, 0); } while (0)
; #define LDA(dst, b, h) _Pragma("unroll") for (int m = 0; m < 4; ++m) _Pragma("unroll") for (int k = 0; k < 2; ++k) \
;       dst[m][k] = *(const bf16x8*)(SA(b, h) + aoff + (m * 2048 + k * 1024))
; #define LDB(dst, b, h) _Pragma("unroll") for (int n = 0; n < 2; ++n) _Pragma("unroll") for (int k = 0; k < 2; ++k) \
;       dst[n][k] = *(const bf16x8*)(SB(b, h) + boff + (n * 256 + k * 1024))
; #define BAR __builtin_amdgcn_s_barrier()
; template <int EPI, int N, int K>
; __device__ __forceinline__ void phase_gemm(const Params& p, const u16* __restrict__ A, const u16* __restrict__ Bt, int nM, char* shm,
;                            u16* __restrict__ outp, float* __restrict__ rowss) {
;     ...
;       LDB(B0, 1, 0); SBAR(); LDA(At, 1, 0); STAGE(SA(0, 1), A1, t + 2);
;       WAIT_L(8); BAR; WAIT_L(0); MMA(0, 0, At, B0); BAR; SBAR();
;       LDB(B1, 1, 1); STAGE(SB(1, 0), B0p, t + 3);
;       BAR; WAIT_L(0); MMA(0, 1, At, B1); BAR;
;       LDA(At, 1, 1); STAGE(SA(1, 0), A0, t + 3);
;       BAR; WAIT_L(0); MMA(1, 0, At, B0); BAR; SBAR();
;       STAGE(SB(1, 1), B1p, t + 3);
;       WAIT_V(6); BAR; MMA(1, 1, At, B1); BAR;
;     }
	v_add_u32_e32 v156, 0x18400, v143
	ds_read_b128 v[164:167], v155
	ds_read_b128 v[168:171], v156
	v_add_u32_e32 v158, 0x18500, v143
	ds_read_b128 v[172:175], v157
	ds_read_b128 v[176:179], v158
	s_mov_b32 m0, s96
	ds_read_b128 v[180:183], v144 offset:32768
	ds_read_b128 v[208:211], v144 offset:33792
	ds_read_b128 v[212:215], v144 offset:34816
	ds_read_b128 v[216:219], v144 offset:35840
	ds_read_b128 v[220:223], v144 offset:36864
	ds_read_b128 v[224:227], v144 offset:37888
	ds_read_b128 v[228:231], v144 offset:38912
	ds_read_b128 v[232:235], v144 offset:39936
	global_load_lds_dwordx4 v198, s[14:15]
	s_mov_b32 m0, s33
	s_nop 0
	global_load_lds_dwordx4 v199, s[14:15]
	v_or_b32_e32 v159, 0x1c000, v143
	v_add_u32_e32 v161, 0x1c100, v143
	v_add_u32_e32 v160, 0x1c400, v143
	ds_read_b128 v[236:239], v159
	ds_read_b128 v[240:243], v160
	v_add_u32_e32 v162, 0x1c500, v143
	ds_read_b128 v[244:247], v161
	ds_read_b128 v[248:251], v162
	s_waitcnt lgkmcnt(0)
	s_barrier
	v_mfma_f32_16x16x32_bf16 v[126:129], v[164:167], v[180:183], v[126:129]
	v_mfma_f32_16x16x32_bf16 v[122:125], v[172:175], v[180:183], v[122:125]
	v_mfma_f32_16x16x32_bf16 v[118:121], v[164:167], v[212:215], v[118:121]
	v_mfma_f32_16x16x32_bf16 v[114:117], v[172:175], v[212:215], v[114:117]
	v_mfma_f32_16x16x32_bf16 v[110:113], v[164:167], v[220:223], v[110:113]
	v_mfma_f32_16x16x32_bf16 v[106:109], v[172:175], v[220:223], v[106:109]
	v_mfma_f32_16x16x32_bf16 v[102:105], v[164:167], v[228:231], v[102:105]
	v_mfma_f32_16x16x32_bf16 v[98:101], v[172:175], v[228:231], v[98:101]
	v_mfma_f32_16x16x32_bf16 v[126:129], v[168:171], v[208:211], v[126:129]
	v_mfma_f32_16x16x32_bf16 v[122:125], v[176:179], v[208:211], v[122:125]
	v_mfma_f32_16x16x32_bf16 v[118:121], v[168:171], v[216:219], v[118:121]
	v_mfma_f32_16x16x32_bf16 v[114:117], v[176:179], v[216:219], v[114:117]
	v_mfma_f32_16x16x32_bf16 v[110:113], v[168:171], v[224:227], v[110:113]
	v_mfma_f32_16x16x32_bf16 v[106:109], v[176:179], v[224:227], v[106:109]
	v_mfma_f32_16x16x32_bf16 v[102:105], v[168:171], v[232:235], v[102:105]
	v_mfma_f32_16x16x32_bf16 v[98:101], v[176:179], v[232:235], v[98:101]
	v_mfma_f32_16x16x32_bf16 v[92:95], v[236:239], v[180:183], v[92:95]
	v_mfma_f32_16x16x32_bf16 v[88:91], v[244:247], v[180:183], v[88:91]
	v_mfma_f32_16x16x32_bf16 v[84:87], v[236:239], v[212:215], v[84:87]
	v_mfma_f32_16x16x32_bf16 v[80:83], v[244:247], v[212:215], v[80:83]
	v_mfma_f32_16x16x32_bf16 v[76:79], v[236:239], v[220:223], v[76:79]
	v_mfma_f32_16x16x32_bf16 v[72:75], v[244:247], v[220:223], v[72:75]
	v_mfma_f32_16x16x32_bf16 v[68:71], v[236:239], v[228:231], v[68:71]
	v_mfma_f32_16x16x32_bf16 v[64:67], v[244:247], v[228:231], v[64:67]
	v_mfma_f32_16x16x32_bf16 v[92:95], v[240:243], v[208:211], v[92:95]
	v_mfma_f32_16x16x32_bf16 v[88:91], v[248:251], v[208:211], v[88:91]
	v_mfma_f32_16x16x32_bf16 v[84:87], v[240:243], v[216:219], v[84:87]
	v_mfma_f32_16x16x32_bf16 v[80:83], v[248:251], v[216:219], v[80:83]
	v_mfma_f32_16x16x32_bf16 v[76:79], v[240:243], v[224:227], v[76:79]
	v_mfma_f32_16x16x32_bf16 v[72:75], v[248:251], v[224:227], v[72:75]
	v_mfma_f32_16x16x32_bf16 v[68:71], v[240:243], v[232:235], v[68:71]
	v_mfma_f32_16x16x32_bf16 v[64:67], v[248:251], v[232:235], v[64:67]
	s_barrier
	ds_read_b128 v[180:183], v144 offset:49152
	ds_read_b128 v[208:211], v144 offset:50176
	ds_read_b128 v[212:215], v144 offset:51200
	ds_read_b128 v[216:219], v144 offset:52224
	ds_read_b128 v[220:223], v144 offset:53248
	ds_read_b128 v[224:227], v144 offset:54272
	ds_read_b128 v[228:231], v144 offset:55296
	ds_read_b128 v[232:235], v144 offset:56320
	s_mov_b32 m0, s35
	v_add_u32_e32 v163, 0x180, v196
	global_load_lds_dwordx4 v163, s[6:7]
	v_add_u32_e32 v196, 0x180, v197
	s_mov_b32 m0, s93
	s_nop 0
	global_load_lds_dwordx4 v196, s[6:7]
	s_mov_b32 m0, s24
	s_nop 0
	global_load_lds_dwordx4 v163, s[8:9]
	s_mov_b32 m0, s25
	s_nop 0
	global_load_lds_dwordx4 v196, s[8:9]
	s_mov_b32 m0, s26
	s_nop 0
	global_load_lds_dwordx4 v163, s[16:17]
	s_mov_b32 m0, s27
	s_nop 0
	global_load_lds_dwordx4 v196, s[16:17]
	s_waitcnt vmcnt(6)
	s_waitcnt lgkmcnt(0)
	s_barrier
	v_mfma_f32_16x16x32_bf16 v[60:63], v[164:167], v[180:183], v[60:63]
	v_mfma_f32_16x16x32_bf16 v[56:59], v[172:175], v[180:183], v[56:59]
	v_mfma_f32_16x16x32_bf16 v[52:55], v[164:167], v[212:215], v[52:55]
	v_mfma_f32_16x16x32_bf16 v[48:51], v[172:175], v[212:215], v[48:51]
	v_mfma_f32_16x16x32_bf16 v[44:47], v[164:167], v[220:223], v[44:47]
	v_mfma_f32_16x16x32_bf16 v[40:43], v[172:175], v[220:223], v[40:43]
	v_mfma_f32_16x16x32_bf16 v[36:39], v[164:167], v[228:231], v[36:39]
	v_mfma_f32_16x16x32_bf16 v[32:35], v[172:175], v[228:231], v[32:35]
	v_mfma_f32_16x16x32_bf16 v[60:63], v[168:171], v[208:211], v[60:63]
	v_mfma_f32_16x16x32_bf16 v[56:59], v[176:179], v[208:211], v[56:59]
	v_mfma_f32_16x16x32_bf16 v[52:55], v[168:171], v[216:219], v[52:55]
	v_mfma_f32_16x16x32_bf16 v[48:51], v[176:179], v[216:219], v[48:51]
	v_mfma_f32_16x16x32_bf16 v[44:47], v[168:171], v[224:227], v[44:47]
	v_mfma_f32_16x16x32_bf16 v[40:43], v[176:179], v[224:227], v[40:43]
	v_mfma_f32_16x16x32_bf16 v[36:39], v[168:171], v[232:235], v[36:39]
	v_mfma_f32_16x16x32_bf16 v[32:35], v[176:179], v[232:235], v[32:35]
	v_mfma_f32_16x16x32_bf16 v[28:31], v[236:239], v[180:183], v[28:31]
	v_mfma_f32_16x16x32_bf16 v[24:27], v[244:247], v[180:183], v[24:27]
	v_mfma_f32_16x16x32_bf16 v[20:23], v[236:239], v[212:215], v[20:23]
	v_mfma_f32_16x16x32_bf16 v[16:19], v[244:247], v[212:215], v[16:19]
	v_mfma_f32_16x16x32_bf16 v[12:15], v[236:239], v[220:223], v[12:15]
	v_mfma_f32_16x16x32_bf16 v[8:11], v[244:247], v[220:223], v[8:11]
	v_mfma_f32_16x16x32_bf16 v[4:7], v[236:239], v[228:231], v[4:7]
	v_mfma_f32_16x16x32_bf16 v[0:3], v[244:247], v[228:231], v[0:3]
	v_mfma_f32_16x16x32_bf16 v[28:31], v[240:243], v[208:211], v[28:31]
	v_mfma_f32_16x16x32_bf16 v[24:27], v[248:251], v[208:211], v[24:27]
	v_mfma_f32_16x16x32_bf16 v[20:23], v[240:243], v[216:219], v[20:23]
	v_mfma_f32_16x16x32_bf16 v[16:19], v[248:251], v[216:219], v[16:19]
	v_mfma_f32_16x16x32_bf16 v[12:15], v[240:243], v[224:227], v[12:15]
	v_mfma_f32_16x16x32_bf16 v[8:11], v[248:251], v[224:227], v[8:11]
	v_mfma_f32_16x16x32_bf16 v[4:7], v[240:243], v[232:235], v[4:7]
	v_mfma_f32_16x16x32_bf16 v[0:3], v[248:251], v[232:235], v[0:3]
	s_add_i32 s53, s53, 2
	v_add_u32_e32 v141, 0x100, v141
	s_cmp_lt_u32 s53, 12
	v_add_u32_e32 v140, 0x100, v140
	s_barrier
; #define WAIT_V(n) asm volatile("s_waitcnt vmcnt(%0)" ::"n"(n) : "memory")
; #define WAIT_L(n) asm volatile("s_waitcnt lgkmcnt(%0)" ::"n"(n) : "memory")
; #define STAGE(P, base, kt) do { _Pragma("unroll") for (int _i = 0; _i < 2; ++_i)                                        \
;       __builtin_amdgcn_global_load_lds((const unsigned*)((base) + (size_t)(sOff[_i] + (unsigned)(kt) * (BK * 2))),        \
;                                        (unsigned*)((P) + wid * 1024 + _i * 8192), 16, 0, 0); } while (0)
; #define LDA(dst, b, h) _Pragma("unroll") for (int m = 0; m < 4; ++m) _Pragma("unroll") for (int k = 0; k < 2; ++k) \
;       dst[m][k] = *(const bf16x8*)(SA(b, h) + aoff + (m * 2048 + k * 1024))
; #define LDB(dst, b, h) _Pragma("unroll") for (int n = 0; n < 2; ++n) _Pragma("unroll") for (int k = 0; k < 2; ++k) \
;       dst[n][k] = *(const bf16x8*)(SB(b, h) + boff + (n * 256 + k * 1024))
; #define BAR __builtin_amdgcn_s_barrier()
; template <int EPI, int N, int K>
; __device__ __forceinline__ void phase_gemm(const Params& p, const u16* __restrict__ A, const u16* __restrict__ Bt, int nM, char* shm,
;                            u16* __restrict__ outp, float* __restrict__ rowss) {
;     ...
;     }
;     { LDB(B0, 0, 0); LDA(At, 0, 0); STAGE(SA(1, 1), A1, nt - 1);
;       BAR; WAIT_L(0); MMA(0, 0, At, B0); BAR;
;       LDB(B1, 0, 1); BAR; WAIT_L(0); MMA(0, 1, At, B1); BAR;
;       LDA(At, 0, 1); WAIT_V(4); BAR; WAIT_L(0); MMA(1, 0, At, B0); MMA(1, 1, At, B1); BAR; }
	s_cbranch_scc1 .LBB0_553
	s_mov_b32 m0, s55
	v_lshl_add_u64 v[140:141], s[14:15], 0, v[136:137]
	ds_read_b128 v[164:167], v147
	ds_read_b128 v[168:171], v148
	ds_read_b128 v[172:175], v149
	ds_read_b128 v[176:179], v150
	ds_read_b128 v[180:183], v144
	ds_read_b128 v[208:211], v144 offset:1024
	ds_read_b128 v[212:215], v144 offset:2048
	ds_read_b128 v[216:219], v144 offset:3072
	ds_read_b128 v[220:223], v144 offset:4096
	ds_read_b128 v[224:227], v144 offset:5120
	ds_read_b128 v[228:231], v144 offset:6144
	ds_read_b128 v[232:235], v144 offset:7168
	global_load_lds_dwordx4 v[140:141], off
	v_lshl_add_u64 v[140:141], s[14:15], 0, v[138:139]
	s_mov_b32 m0, s54
	s_nop 0
	global_load_lds_dwordx4 v[140:141], off
	s_barrier
	s_waitcnt lgkmcnt(0)
	s_waitcnt lgkmcnt(0)
	v_mfma_f32_16x16x32_bf16 v[126:129], v[164:167], v[180:183], v[126:129]
	v_mfma_f32_16x16x32_bf16 v[118:121], v[164:167], v[212:215], v[118:121]
	v_mfma_f32_16x16x32_bf16 v[110:113], v[164:167], v[220:223], v[110:113]
	v_mfma_f32_16x16x32_bf16 v[102:105], v[164:167], v[228:231], v[102:105]
	v_mfma_f32_16x16x32_bf16 v[126:129], v[168:171], v[208:211], v[126:129]
	v_mfma_f32_16x16x32_bf16 v[122:125], v[172:175], v[180:183], v[122:125]
	v_mfma_f32_16x16x32_bf16 v[118:121], v[168:171], v[216:219], v[118:121]
	v_mfma_f32_16x16x32_bf16 v[114:117], v[172:175], v[212:215], v[114:117]
	v_mfma_f32_16x16x32_bf16 v[110:113], v[168:171], v[224:227], v[110:113]
	v_mfma_f32_16x16x32_bf16 v[106:109], v[172:175], v[220:223], v[106:109]
	v_mfma_f32_16x16x32_bf16 v[102:105], v[168:171], v[232:235], v[102:105]
	v_mfma_f32_16x16x32_bf16 v[98:101], v[172:175], v[228:231], v[98:101]
	v_mfma_f32_16x16x32_bf16 v[236:239], v[176:179], v[208:211], v[122:125]
	v_mfma_f32_16x16x32_bf16 v[240:243], v[176:179], v[216:219], v[114:117]
	v_mfma_f32_16x16x32_bf16 v[244:247], v[176:179], v[224:227], v[106:109]
	v_mfma_f32_16x16x32_bf16 v[248:251], v[176:179], v[232:235], v[98:101]
	s_barrier
	s_nop 1
	ds_read_b128 v[98:101], v151
	ds_read_b128 v[106:109], v152
	ds_read_b128 v[114:117], v153
	ds_read_b128 v[122:125], v154
	s_barrier
	s_waitcnt lgkmcnt(0)
	s_waitcnt lgkmcnt(0)
	v_mfma_f32_16x16x32_bf16 v[92:95], v[98:101], v[180:183], v[92:95]
	v_mfma_f32_16x16x32_bf16 v[84:87], v[98:101], v[212:215], v[84:87]
	v_mfma_f32_16x16x32_bf16 v[76:79], v[98:101], v[220:223], v[76:79]
	v_mfma_f32_16x16x32_bf16 v[68:71], v[98:101], v[228:231], v[68:71]
	v_mfma_f32_16x16x32_bf16 v[92:95], v[106:109], v[208:211], v[92:95]
	v_mfma_f32_16x16x32_bf16 v[88:91], v[114:117], v[180:183], v[88:91]
	v_mfma_f32_16x16x32_bf16 v[84:87], v[106:109], v[216:219], v[84:87]
	v_mfma_f32_16x16x32_bf16 v[80:83], v[114:117], v[212:215], v[80:83]
	v_mfma_f32_16x16x32_bf16 v[76:79], v[106:109], v[224:227], v[76:79]
	v_mfma_f32_16x16x32_bf16 v[72:75], v[114:117], v[220:223], v[72:75]
	v_mfma_f32_16x16x32_bf16 v[68:71], v[106:109], v[232:235], v[68:71]
	v_mfma_f32_16x16x32_bf16 v[64:67], v[114:117], v[228:231], v[64:67]
	v_mfma_f32_16x16x32_bf16 v[148:151], v[122:125], v[208:211], v[88:91]
	v_mfma_f32_16x16x32_bf16 v[180:183], v[122:125], v[216:219], v[80:83]
	v_mfma_f32_16x16x32_bf16 v[208:211], v[122:125], v[224:227], v[72:75]
	v_mfma_f32_16x16x32_bf16 v[212:215], v[122:125], v[232:235], v[64:67]
	s_barrier
	s_nop 1
	ds_read_b128 v[64:67], v144 offset:16384
	ds_read_b128 v[72:75], v144 offset:17408
	ds_read_b128 v[80:83], v144 offset:18432
	ds_read_b128 v[88:91], v144 offset:19456
	ds_read_b128 v[216:219], v144 offset:20480
	ds_read_b128 v[220:223], v144 offset:21504
	ds_read_b128 v[224:227], v144 offset:22528
	ds_read_b128 v[228:231], v144 offset:23552
	s_waitcnt vmcnt(4)
	s_barrier
	s_waitcnt lgkmcnt(0)
	s_waitcnt lgkmcnt(0)
	v_mfma_f32_16x16x32_bf16 v[60:63], v[164:167], v[64:67], v[60:63]
	v_mfma_f32_16x16x32_bf16 v[52:55], v[164:167], v[80:83], v[52:55]
	v_mfma_f32_16x16x32_bf16 v[44:47], v[164:167], v[216:219], v[44:47]
	v_mfma_f32_16x16x32_bf16 v[36:39], v[164:167], v[224:227], v[36:39]
	v_mfma_f32_16x16x32_bf16 v[60:63], v[168:171], v[72:75], v[60:63]
	v_mfma_f32_16x16x32_bf16 v[56:59], v[172:175], v[64:67], v[56:59]
	v_mfma_f32_16x16x32_bf16 v[52:55], v[168:171], v[88:91], v[52:55]
	v_mfma_f32_16x16x32_bf16 v[48:51], v[172:175], v[80:83], v[48:51]
	v_mfma_f32_16x16x32_bf16 v[44:47], v[168:171], v[220:223], v[44:47]
	v_mfma_f32_16x16x32_bf16 v[40:43], v[172:175], v[216:219], v[40:43]
	v_mfma_f32_16x16x32_bf16 v[36:39], v[168:171], v[228:231], v[36:39]
	v_mfma_f32_16x16x32_bf16 v[32:35], v[172:175], v[224:227], v[32:35]
	v_mfma_f32_16x16x32_bf16 v[232:235], v[176:179], v[72:75], v[56:59]
	v_mfma_f32_16x16x32_bf16 v[196:199], v[176:179], v[88:91], v[48:51]
	v_mfma_f32_16x16x32_bf16 v[200:203], v[176:179], v[220:223], v[40:43]
	v_mfma_f32_16x16x32_bf16 v[164:167], v[176:179], v[228:231], v[32:35]
	v_mfma_f32_16x16x32_bf16 v[28:31], v[98:101], v[64:67], v[28:31]
	v_mfma_f32_16x16x32_bf16 v[20:23], v[98:101], v[80:83], v[20:23]
	v_mfma_f32_16x16x32_bf16 v[12:15], v[98:101], v[216:219], v[12:15]
	v_mfma_f32_16x16x32_bf16 v[4:7], v[98:101], v[224:227], v[4:7]
	v_mfma_f32_16x16x32_bf16 v[28:31], v[106:109], v[72:75], v[28:31]
	v_mfma_f32_16x16x32_bf16 v[24:27], v[114:117], v[64:67], v[24:27]
	v_mfma_f32_16x16x32_bf16 v[20:23], v[106:109], v[88:91], v[20:23]
	v_mfma_f32_16x16x32_bf16 v[16:19], v[114:117], v[80:83], v[16:19]
	v_mfma_f32_16x16x32_bf16 v[12:15], v[106:109], v[220:223], v[12:15]
	v_mfma_f32_16x16x32_bf16 v[8:11], v[114:117], v[216:219], v[8:11]
	v_mfma_f32_16x16x32_bf16 v[4:7], v[106:109], v[228:231], v[4:7]
	v_mfma_f32_16x16x32_bf16 v[0:3], v[114:117], v[224:227], v[0:3]
	v_mfma_f32_16x16x32_bf16 v[168:171], v[122:125], v[72:75], v[24:27]
	v_mfma_f32_16x16x32_bf16 v[172:175], v[122:125], v[88:91], v[16:19]
	v_mfma_f32_16x16x32_bf16 v[176:179], v[122:125], v[220:223], v[8:11]
	v_mfma_f32_16x16x32_bf16 v[216:219], v[122:125], v[228:231], v[0:3]
	s_barrier
; #define WAIT_V(n) asm volatile("s_waitcnt vmcnt(%0)" ::"n"(n) : "memory")
; #define WAIT_L(n) asm volatile("s_waitcnt lgkmcnt(%0)" ::"n"(n) : "memory")
; #define LDA(dst, b, h) _Pragma("unroll") for (int m = 0; m < 4; ++m) _Pragma("unroll") for (int k = 0; k < 2; ++k) \
;       dst[m][k] = *(const bf16x8*)(SA(b, h) + aoff + (m * 2048 + k * 1024))
; #define LDB(dst, b, h) _Pragma("unroll") for (int n = 0; n < 2; ++n) _Pragma("unroll") for (int k = 0; k < 2; ++k) \
;       dst[n][k] = *(const bf16x8*)(SB(b, h) + boff + (n * 256 + k * 1024))
; #define BAR __builtin_amdgcn_s_barrier()
; template <int EPI, int N, int K>
; __device__ __forceinline__ void phase_gemm(const Params& p, const u16* __restrict__ A, const u16* __restrict__ Bt, int nM, char* shm,
;                            u16* __restrict__ outp, float* __restrict__ rowss) {
;     ...
;     { LDB(B0, 1, 0); LDA(At, 1, 0); WAIT_V(2); BAR; WAIT_L(0); MMA(0, 0, At, B0); BAR;
;       LDB(B1, 1, 1); WAIT_V(0); BAR; WAIT_L(0); MMA(0, 1, At, B1); BAR;
;       LDA(At, 1, 1); BAR; WAIT_L(0); MMA(1, 0, At, B0); MMA(1, 1, At, B1); BAR; }
;     if (wr == 0) BAR;
	s_nop 1
	ds_read_b128 v[0:3], v155
	ds_read_b128 v[8:11], v156
	ds_read_b128 v[152:155], v157
	ds_read_b128 v[220:223], v158
	ds_read_b128 v[16:19], v144 offset:32768
	ds_read_b128 v[24:27], v144 offset:33792
	ds_read_b128 v[32:35], v144 offset:34816
	ds_read_b128 v[40:43], v144 offset:35840
	ds_read_b128 v[48:51], v144 offset:36864
	ds_read_b128 v[56:59], v144 offset:37888
	ds_read_b128 v[224:227], v144 offset:38912
	ds_read_b128 v[228:231], v144 offset:39936
	s_waitcnt vmcnt(2)
	s_barrier
	s_waitcnt lgkmcnt(0)
	s_waitcnt lgkmcnt(0)
	v_mfma_f32_16x16x32_bf16 v[64:67], v[0:3], v[16:19], v[126:129]
	v_mfma_f32_16x16x32_bf16 v[122:125], v[8:11], v[24:27], v[64:67]
	v_mfma_f32_16x16x32_bf16 v[64:67], v[152:155], v[16:19], v[236:239]
	v_mfma_f32_16x16x32_bf16 v[114:117], v[220:223], v[24:27], v[64:67]
	v_mfma_f32_16x16x32_bf16 v[64:67], v[0:3], v[32:35], v[118:121]
	v_mfma_f32_16x16x32_bf16 v[106:109], v[8:11], v[40:43], v[64:67]
	v_mfma_f32_16x16x32_bf16 v[64:67], v[152:155], v[32:35], v[240:243]
	v_mfma_f32_16x16x32_bf16 v[98:101], v[220:223], v[40:43], v[64:67]
	v_mfma_f32_16x16x32_bf16 v[64:67], v[0:3], v[48:51], v[110:113]
	v_mfma_f32_16x16x32_bf16 v[88:91], v[8:11], v[56:59], v[64:67]
	v_mfma_f32_16x16x32_bf16 v[64:67], v[152:155], v[48:51], v[244:247]
	v_mfma_f32_16x16x32_bf16 v[80:83], v[220:223], v[56:59], v[64:67]
	v_mfma_f32_16x16x32_bf16 v[64:67], v[0:3], v[224:227], v[102:105]
	v_mfma_f32_16x16x32_bf16 v[72:75], v[8:11], v[228:231], v[64:67]
	v_mfma_f32_16x16x32_bf16 v[64:67], v[152:155], v[224:227], v[248:251]
	v_mfma_f32_16x16x32_bf16 v[64:67], v[220:223], v[228:231], v[64:67]
	s_barrier
	ds_read_b128 v[156:159], v159
	ds_read_b128 v[236:239], v160
	ds_read_b128 v[240:243], v161
	ds_read_b128 v[160:163], v162
	s_waitcnt vmcnt(0)
	s_barrier
	s_waitcnt lgkmcnt(0)
	s_waitcnt lgkmcnt(0)
	v_mfma_f32_16x16x32_bf16 v[92:95], v[156:159], v[16:19], v[92:95]
	v_mfma_f32_16x16x32_bf16 v[16:19], v[240:243], v[16:19], v[148:151]
	v_mfma_f32_16x16x32_bf16 v[118:121], v[160:163], v[24:27], v[16:19]
	v_mfma_f32_16x16x32_bf16 v[16:19], v[156:159], v[32:35], v[84:87]
	v_mfma_f32_16x16x32_bf16 v[110:113], v[236:239], v[40:43], v[16:19]
	v_mfma_f32_16x16x32_bf16 v[16:19], v[240:243], v[32:35], v[180:183]
	v_mfma_f32_16x16x32_bf16 v[102:105], v[160:163], v[40:43], v[16:19]
	v_mfma_f32_16x16x32_bf16 v[16:19], v[156:159], v[48:51], v[76:79]
	v_mfma_f32_16x16x32_bf16 v[126:129], v[236:239], v[24:27], v[92:95]
	v_mfma_f32_16x16x32_bf16 v[92:95], v[236:239], v[56:59], v[16:19]
	v_mfma_f32_16x16x32_bf16 v[16:19], v[240:243], v[48:51], v[208:211]
	v_mfma_f32_16x16x32_bf16 v[84:87], v[160:163], v[56:59], v[16:19]
	v_mfma_f32_16x16x32_bf16 v[16:19], v[156:159], v[224:227], v[68:71]
	v_mfma_f32_16x16x32_bf16 v[76:79], v[236:239], v[228:231], v[16:19]
	v_mfma_f32_16x16x32_bf16 v[16:19], v[240:243], v[224:227], v[212:215]
	v_mfma_f32_16x16x32_bf16 v[68:71], v[160:163], v[228:231], v[16:19]
	s_barrier
	ds_read_b128 v[148:151], v144 offset:49152
	ds_read_b128 v[180:183], v144 offset:50176
	ds_read_b128 v[208:211], v144 offset:51200
	ds_read_b128 v[212:215], v144 offset:52224
	ds_read_b128 v[224:227], v144 offset:53248
	ds_read_b128 v[228:231], v144 offset:54272
	ds_read_b128 v[244:247], v144 offset:55296
	ds_read_b128 v[248:251], v144 offset:56320
	s_barrier
	s_waitcnt lgkmcnt(0)
	s_waitcnt lgkmcnt(0)
	v_mfma_f32_16x16x32_bf16 v[16:19], v[0:3], v[148:151], v[60:63]
	v_mfma_f32_16x16x32_bf16 v[56:59], v[8:11], v[180:183], v[16:19]
	v_mfma_f32_16x16x32_bf16 v[16:19], v[152:155], v[148:151], v[232:235]
	v_mfma_f32_16x16x32_bf16 v[48:51], v[220:223], v[180:183], v[16:19]
	v_mfma_f32_16x16x32_bf16 v[16:19], v[0:3], v[208:211], v[52:55]
	v_mfma_f32_16x16x32_bf16 v[40:43], v[8:11], v[212:215], v[16:19]
	v_mfma_f32_16x16x32_bf16 v[16:19], v[152:155], v[208:211], v[196:199]
	v_mfma_f32_16x16x32_bf16 v[32:35], v[220:223], v[212:215], v[16:19]
	v_mfma_f32_16x16x32_bf16 v[16:19], v[0:3], v[224:227], v[44:47]
	v_mfma_f32_16x16x32_bf16 v[0:3], v[0:3], v[244:247], v[36:39]
	v_mfma_f32_16x16x32_bf16 v[24:27], v[8:11], v[228:231], v[16:19]
	v_mfma_f32_16x16x32_bf16 v[16:19], v[152:155], v[224:227], v[200:203]
	v_mfma_f32_16x16x32_bf16 v[8:11], v[8:11], v[248:251], v[0:3]
	v_mfma_f32_16x16x32_bf16 v[0:3], v[152:155], v[244:247], v[164:167]
	v_mfma_f32_16x16x32_bf16 v[16:19], v[220:223], v[228:231], v[16:19]
	v_mfma_f32_16x16x32_bf16 v[0:3], v[220:223], v[248:251], v[0:3]
	v_mfma_f32_16x16x32_bf16 v[28:31], v[156:159], v[148:151], v[28:31]
	v_mfma_f32_16x16x32_bf16 v[60:63], v[236:239], v[180:183], v[28:31]
	v_mfma_f32_16x16x32_bf16 v[28:31], v[240:243], v[148:151], v[168:171]
	v_mfma_f32_16x16x32_bf16 v[20:23], v[156:159], v[208:211], v[20:23]
	v_mfma_f32_16x16x32_bf16 v[12:15], v[156:159], v[224:227], v[12:15]
	v_mfma_f32_16x16x32_bf16 v[52:55], v[160:163], v[180:183], v[28:31]
	v_mfma_f32_16x16x32_bf16 v[44:47], v[236:239], v[212:215], v[20:23]
	v_mfma_f32_16x16x32_bf16 v[20:23], v[240:243], v[208:211], v[172:175]
	v_mfma_f32_16x16x32_bf16 v[28:31], v[236:239], v[228:231], v[12:15]
	v_mfma_f32_16x16x32_bf16 v[12:15], v[240:243], v[224:227], v[176:179]
	v_mfma_f32_16x16x32_bf16 v[4:7], v[156:159], v[244:247], v[4:7]
	v_mfma_f32_16x16x32_bf16 v[36:39], v[160:163], v[212:215], v[20:23]
	v_mfma_f32_16x16x32_bf16 v[20:23], v[160:163], v[228:231], v[12:15]
	v_mfma_f32_16x16x32_bf16 v[12:15], v[236:239], v[248:251], v[4:7]
	v_mfma_f32_16x16x32_bf16 v[4:7], v[240:243], v[244:247], v[216:219]
	v_mfma_f32_16x16x32_bf16 v[4:7], v[160:163], v[248:251], v[4:7]
	s_andn2_b64 vcc, exec, s[12:13]
	s_barrier
	s_cbranch_vccnz .LBB0_556
	s_barrier
